# speedup vs baseline: 1.0727x; 1.0300x over previous
; template <int RG, int NSW>
; __device__ __forceinline__ void scan_waves(const Params& p, float* lds, const int T, const int dir, const int wave, const int lane,
;                                            const size_t tok0, const int head, const int row_base) {
;     ...
;   const int rowl = lane >> 3, part = lane & 7, k0 = part * 8;
;   int rowi[RG]; f32x2_t S[RG][4];
; #pragma unroll
;   for (int g = 0; g < RG; ++g) {
;     rowi[g] = row_base + g * (NSW * 8) + wave * 8 + rowl;
; #pragma unroll
;     for (int k = 0; k < 4; ++k) S[g][k] = (f32x2_t){0.f, 0.f};
;   }
;   const int orow = row_base + (part & (RG - 1)) * (NSW * 8) + wave * 8 + rowl;
;   char* const obase = dir == 0 ? (char*)(p.ws + OFF_YB) : (char*)(p.ws + OFF_OB);
;   const unsigned ostride = dir == 0 ? (unsigned)DM * 2u : 2048u;
;   const unsigned ooff0 = dir == 0 ? ((unsigned)tok0 * (unsigned)DM + 1024u + (unsigned)(64 * head + orow)) * 2u
;                                   : ((unsigned)tok0 * 1024u + (unsigned)(64 * head + orow)) * 2u;
;   const int nb = T / 16; int i3 = 0;
;   for (int i = -2; i < nb; ++i) {
.LBB0_1219:
	v_and_b32_e32 v3, 7, v144
	v_or_b32_e32 v19, v2, v0
	v_mov_b32_e32 v1, 0
	v_mov_b32_e32 v0, 0
	v_lshlrev_b32_e32 v20, 3, v3
	v_lshl_add_u32 v21, v3, 5, 0
	v_cmp_eq_u32_e32 vcc, 1, v3
	v_cmp_gt_u32_e64 s[4:5], 2, v3
	s_mov_b32 s53, -2
	s_mov_b32 s54, 0
	s_movk_i32 s55, 0xffe0
	s_movk_i32 s56, 0x81f
	v_mov_b64_e32 v[2:3], v[0:1]
	s_waitcnt vmcnt(1)
	v_mov_b64_e32 v[4:5], v[0:1]
	s_waitcnt vmcnt(0)
	v_mov_b64_e32 v[6:7], v[0:1]
	v_mov_b64_e32 v[8:9], v[0:1]
	v_mov_b64_e32 v[10:11], v[0:1]
	v_mov_b64_e32 v[12:13], v[0:1]
	v_mov_b64_e32 v[14:15], v[0:1]
	v_mov_b64_e32 v[16:17], v[0:1]
	v_mov_b32_e32 v0, 0
	v_mov_b32_e32 v1, 0
	v_lshrrev_b32_e32 v22, 3, v20
	v_and_b32_e32 v23, 1, v22
	v_lshrrev_b32_e32 v24, 1, v22
	v_and_b32_e32 v22, 2, v22
	v_lshlrev_b32_e32 v24, 2, v24
	v_mul_lo_u32 v24, v24, s52
	s_branch .LBB0_1222

; template <int RG, int NSW>
; __device__ __forceinline__ void scan_waves(const Params& p, float* lds, const int T, const int dir, const int wave, const int lane,
;                                            const size_t tok0, const int head, const int row_base) {
;     ...
;       i3 = (i3 == 2) ? 0 : i3 + 1;
;     }
;     lds_barrier();
.Lmy_ss_next:
	s_add_i32 s8, s54, 1
	s_cmp_lg_u32 s54, 2
	s_cselect_b32 s54, s8, 0

; __device__ __forceinline__ float red8_sum(float x) { x += dpp_f<0xB1>(x); x += dpp_f<0x4E>(x); x += dpp_f<0x141>(x); return x; }
; template <int RG, int NSW>
; __device__ __forceinline__ void scan_waves(const Params& p, float* lds, const int T, const int dir, const int wave, const int lane,
;                                            const size_t tok0, const int head, const int row_base) {
;     ...
;   for (int i = -2; i < nb; ++i) {
;     if (i >= 0) {
;       const float* wdb = Wd + i3 * 1024 + k0; const float* fbb = F + (i & 1) * 5120;
;       float osv[16];
;       f32x2_t w[2][4], kk[2][4], qa[2][4], kd[2][4], r[2][4]; float vv[2][RG];
;     ...
;       LOADSTEP(0, 0);
; #pragma unroll
;       for (int st = 0; st < 16; ++st) {
;         const int B = st & 1;
;         if (st + 1 < 16) LOADSTEP(1 - B, st + 1);
;         asm volatile("" ::: "memory");
;         float sa[RG], o[RG];
; #pragma unroll
;         for (int g = 0; g < RG; ++g) {
;           f32x2_t a0 = S[g][0] * kk[B][0], a1 = S[g][1] * kk[B][1];
;           a0 = __builtin_elementwise_fma(S[g][2], kk[B][2], a0); a1 = __builtin_elementwise_fma(S[g][3], kk[B][3], a1);
;           a0 = a0 + a1; sa[g] = a0.x + a0.y;
;         }
; #pragma unroll
;         for (int g = 0; g < RG; ++g) sa[g] = -red8_sum(sa[g]);
; #pragma unroll
;         for (int g = 0; g < RG; ++g) {
;           const f32x2_t sav = {sa[g], sa[g]}, vvv = {vv[B][g], vv[B][g]};
; #pragma unroll
;           for (int k = 0; k < 4; ++k)
;             S[g][k] = __builtin_elementwise_fma(vvv, kd[B][k], __builtin_elementwise_fma(sav, qa[B][k], S[g][k] * w[B][k]));
.LBB0_1222:
	s_cmp_lt_i32 s53, 0
	s_cbranch_scc1 .LBB0_1221
	s_bitcmp1_b32 s53, 0
	s_cselect_b32 s8, 0x5000, 0
	v_lshl_add_u32 v26, s54, 12, v21
	v_lshl_add_u32 v25, v20, 2, s8
	v_lshl_add_u32 v27, v19, 2, s8
	ds_read_b128 v[40:43], v25 offset:20480
	ds_read_b128 v[44:47], v25 offset:20496
	ds_read_b128 v[32:35], v26
	ds_read_b128 v[36:39], v26 offset:16
	ds_read_b128 v[56:59], v25 offset:20992
	ds_read_b128 v[60:63], v25 offset:21008
	ds_read_b32 v64, v27 offset:21504
	ds_read_b32 v65, v27 offset:21632
	ds_read_b128 v[48:51], v25 offset:20736
	ds_read_b128 v[52:55], v25 offset:20752
	ds_read_b128 v[100:103], v25 offset:21248
	ds_read_b128 v[104:107], v25 offset:21264
	s_waitcnt lgkmcnt(0)
	ds_read_b128 v[74:77], v25 offset:21760
	ds_read_b128 v[78:81], v25 offset:21776
	ds_read_b128 v[66:69], v26 offset:256
	ds_read_b128 v[70:73], v26 offset:272
	ds_read_b128 v[90:93], v25 offset:22272
	ds_read_b128 v[94:97], v25 offset:22288
	ds_read_b32 v98, v27 offset:22784
	ds_read_b32 v99, v27 offset:22912
	ds_read_b128 v[82:85], v25 offset:22016
	ds_read_b128 v[86:89], v25 offset:22032
	ds_read_b128 v[108:111], v25 offset:22528
	ds_read_b128 v[112:115], v25 offset:22544
	v_pk_mul_f32 v[124:125], v[0:1], v[40:41]
	v_pk_fma_f32 v[124:125], v[2:3], v[42:43], v[124:125]
	v_pk_fma_f32 v[124:125], v[4:5], v[44:45], v[124:125]
	v_pk_fma_f32 v[124:125], v[6:7], v[46:47], v[124:125]
	v_pk_mul_f32 v[126:127], v[8:9], v[40:41]
	v_pk_fma_f32 v[126:127], v[10:11], v[42:43], v[126:127]
	v_pk_fma_f32 v[126:127], v[12:13], v[44:45], v[126:127]
	v_pk_fma_f32 v[126:127], v[14:15], v[46:47], v[126:127]
	v_add_f32_e32 v128, v124, v125
	v_add_f32_e32 v130, v126, v127
	v_pk_mul_f32 v[132:133], v[0:1], v[32:33]
	v_pk_mul_f32 v[134:135], v[2:3], v[34:35]
	v_add_f32_dpp v128, v128, v128 quad_perm:[1,0,3,2] row_mask:0xf bank_mask:0xf bound_ctrl:1
	v_add_f32_dpp v130, v130, v130 quad_perm:[1,0,3,2] row_mask:0xf bank_mask:0xf bound_ctrl:1
	v_pk_mul_f32 v[136:137], v[4:5], v[36:37]
	v_pk_mul_f32 v[138:139], v[6:7], v[38:39]
	v_add_f32_dpp v128, v128, v128 quad_perm:[2,3,0,1] row_mask:0xf bank_mask:0xf bound_ctrl:1
	v_add_f32_dpp v130, v130, v130 quad_perm:[2,3,0,1] row_mask:0xf bank_mask:0xf bound_ctrl:1
	v_pk_mul_f32 v[148:149], v[8:9], v[32:33]
	v_pk_mul_f32 v[150:151], v[10:11], v[34:35]
	v_add_f32_dpp v128, v128, v128 row_half_mirror row_mask:0xf bank_mask:0xf bound_ctrl:1
	v_add_f32_dpp v130, v130, v130 row_half_mirror row_mask:0xf bank_mask:0xf bound_ctrl:1
	v_pk_mul_f32 v[152:153], v[12:13], v[36:37]
	v_pk_mul_f32 v[154:155], v[14:15], v[38:39]
	v_pk_fma_f32 v[132:133], v[64:65], v[56:57], v[132:133] op_sel_hi:[0,1,1]
	v_pk_fma_f32 v[134:135], v[64:65], v[58:59], v[134:135] op_sel_hi:[0,1,1]
	v_pk_fma_f32 v[136:137], v[64:65], v[60:61], v[136:137] op_sel_hi:[0,1,1]
	v_pk_fma_f32 v[138:139], v[64:65], v[62:63], v[138:139] op_sel_hi:[0,1,1]
	v_pk_fma_f32 v[148:149], v[64:65], v[56:57], v[148:149] op_sel:[1,0,0] op_sel_hi:[1,1,1]
	v_pk_fma_f32 v[150:151], v[64:65], v[58:59], v[150:151] op_sel:[1,0,0] op_sel_hi:[1,1,1]
	v_pk_fma_f32 v[152:153], v[64:65], v[60:61], v[152:153] op_sel:[1,0,0] op_sel_hi:[1,1,1]
	v_pk_fma_f32 v[154:155], v[64:65], v[62:63], v[154:155] op_sel:[1,0,0] op_sel_hi:[1,1,1]
	v_pk_fma_f32 v[0:1], v[128:129], v[48:49], v[132:133] op_sel_hi:[0,1,1] neg_lo:[1,0,0] neg_hi:[1,0,0]
	v_pk_fma_f32 v[2:3], v[128:129], v[50:51], v[134:135] op_sel_hi:[0,1,1] neg_lo:[1,0,0] neg_hi:[1,0,0]
	v_pk_fma_f32 v[4:5], v[128:129], v[52:53], v[136:137] op_sel_hi:[0,1,1] neg_lo:[1,0,0] neg_hi:[1,0,0]
	v_pk_fma_f32 v[6:7], v[128:129], v[54:55], v[138:139] op_sel_hi:[0,1,1] neg_lo:[1,0,0] neg_hi:[1,0,0]
	v_pk_fma_f32 v[8:9], v[130:131], v[48:49], v[148:149] op_sel_hi:[0,1,1] neg_lo:[1,0,0] neg_hi:[1,0,0]
	v_pk_fma_f32 v[10:11], v[130:131], v[50:51], v[150:151] op_sel_hi:[0,1,1] neg_lo:[1,0,0] neg_hi:[1,0,0]
	v_pk_fma_f32 v[12:13], v[130:131], v[52:53], v[152:153] op_sel_hi:[0,1,1] neg_lo:[1,0,0] neg_hi:[1,0,0]
	v_pk_fma_f32 v[14:15], v[130:131], v[54:55], v[154:155] op_sel_hi:[0,1,1] neg_lo:[1,0,0] neg_hi:[1,0,0]
	s_waitcnt lgkmcnt(0)
	ds_read_b128 v[40:43], v25 offset:23040
	ds_read_b128 v[44:47], v25 offset:23056
	ds_read_b128 v[32:35], v26 offset:512
	ds_read_b128 v[36:39], v26 offset:528
	ds_read_b128 v[56:59], v25 offset:23552
	ds_read_b128 v[60:63], v25 offset:23568
	ds_read_b32 v64, v27 offset:24064
	ds_read_b32 v65, v27 offset:24192
	ds_read_b128 v[48:51], v25 offset:23296
	ds_read_b128 v[52:55], v25 offset:23312
	ds_read_b128 v[116:119], v25 offset:23808
	ds_read_b128 v[120:123], v25 offset:23824
	v_pk_mul_f32 v[124:125], v[0:1], v[74:75]
	v_pk_fma_f32 v[124:125], v[2:3], v[76:77], v[124:125]
	v_pk_fma_f32 v[124:125], v[4:5], v[78:79], v[124:125]
	v_pk_fma_f32 v[124:125], v[6:7], v[80:81], v[124:125]
	v_pk_mul_f32 v[126:127], v[8:9], v[74:75]
	v_pk_fma_f32 v[126:127], v[10:11], v[76:77], v[126:127]
	v_pk_fma_f32 v[126:127], v[12:13], v[78:79], v[126:127]
	v_pk_fma_f32 v[126:127], v[14:15], v[80:81], v[126:127]
	v_add_f32_e32 v128, v124, v125
	v_add_f32_e32 v130, v126, v127
	v_pk_mul_f32 v[132:133], v[0:1], v[66:67]
	v_pk_mul_f32 v[134:135], v[2:3], v[68:69]
	v_add_f32_dpp v128, v128, v128 quad_perm:[1,0,3,2] row_mask:0xf bank_mask:0xf bound_ctrl:1
	v_add_f32_dpp v130, v130, v130 quad_perm:[1,0,3,2] row_mask:0xf bank_mask:0xf bound_ctrl:1
	v_pk_mul_f32 v[136:137], v[4:5], v[70:71]
	v_pk_mul_f32 v[138:139], v[6:7], v[72:73]
	v_add_f32_dpp v128, v128, v128 quad_perm:[2,3,0,1] row_mask:0xf bank_mask:0xf bound_ctrl:1
	v_add_f32_dpp v130, v130, v130 quad_perm:[2,3,0,1] row_mask:0xf bank_mask:0xf bound_ctrl:1
	v_pk_mul_f32 v[148:149], v[8:9], v[66:67]
; __device__ __forceinline__ float red8_sum(float x) { x += dpp_f<0xB1>(x); x += dpp_f<0x4E>(x); x += dpp_f<0x141>(x); return x; }
; template <int RG, int NSW>
; __device__ __forceinline__ void scan_waves(const Params& p, float* lds, const int T, const int dir, const int wave, const int lane,
;                                            const size_t tok0, const int head, const int row_base) {
;     ...
;       LOADSTEP(0, 0);
; #pragma unroll
;       for (int st = 0; st < 16; ++st) {
;         const int B = st & 1;
;         if (st + 1 < 16) LOADSTEP(1 - B, st + 1);
;         asm volatile("" ::: "memory");
;         float sa[RG], o[RG];
; #pragma unroll
;         for (int g = 0; g < RG; ++g) {
;           f32x2_t a0 = S[g][0] * kk[B][0], a1 = S[g][1] * kk[B][1];
;           a0 = __builtin_elementwise_fma(S[g][2], kk[B][2], a0); a1 = __builtin_elementwise_fma(S[g][3], kk[B][3], a1);
;           a0 = a0 + a1; sa[g] = a0.x + a0.y;
;         }
; #pragma unroll
;         for (int g = 0; g < RG; ++g) sa[g] = -red8_sum(sa[g]);
; #pragma unroll
;         for (int g = 0; g < RG; ++g) {
;           const f32x2_t sav = {sa[g], sa[g]}, vvv = {vv[B][g], vv[B][g]};
; #pragma unroll
;           for (int k = 0; k < 4; ++k)
;             S[g][k] = __builtin_elementwise_fma(vvv, kd[B][k], __builtin_elementwise_fma(sav, qa[B][k], S[g][k] * w[B][k]));
;         }
; #pragma unroll
;         for (int g = 0; g < RG; ++g) {
;           f32x2_t a0 = S[g][0] * r[B][0], a1 = S[g][1] * r[B][1];
;           a0 = __builtin_elementwise_fma(S[g][2], r[B][2], a0); a1 = __builtin_elementwise_fma(S[g][3], r[B][3], a1);
;           a0 = a0 + a1; o[g] = a0.x + a0.y;
;         }
; #pragma unroll
;         for (int g = 0; g < RG; ++g) o[g] = red8_sum(o[g]);
;         float os = o[0];
; #pragma unroll
;         for (int g = 1; g < RG; ++g) os = (part == g) ? o[g] : os;
;         osv[st] = os;
;       }
	v_pk_mul_f32 v[150:151], v[10:11], v[68:69]
	v_add_f32_dpp v128, v128, v128 row_half_mirror row_mask:0xf bank_mask:0xf bound_ctrl:1
	v_add_f32_dpp v130, v130, v130 row_half_mirror row_mask:0xf bank_mask:0xf bound_ctrl:1
	v_pk_mul_f32 v[152:153], v[12:13], v[70:71]
	v_pk_mul_f32 v[154:155], v[14:15], v[72:73]
	v_pk_fma_f32 v[132:133], v[98:99], v[90:91], v[132:133] op_sel_hi:[0,1,1]
	v_pk_fma_f32 v[134:135], v[98:99], v[92:93], v[134:135] op_sel_hi:[0,1,1]
	v_pk_fma_f32 v[136:137], v[98:99], v[94:95], v[136:137] op_sel_hi:[0,1,1]
	v_pk_fma_f32 v[138:139], v[98:99], v[96:97], v[138:139] op_sel_hi:[0,1,1]
	v_pk_fma_f32 v[148:149], v[98:99], v[90:91], v[148:149] op_sel:[1,0,0] op_sel_hi:[1,1,1]
	v_pk_fma_f32 v[150:151], v[98:99], v[92:93], v[150:151] op_sel:[1,0,0] op_sel_hi:[1,1,1]
	v_pk_fma_f32 v[152:153], v[98:99], v[94:95], v[152:153] op_sel:[1,0,0] op_sel_hi:[1,1,1]
	v_pk_fma_f32 v[154:155], v[98:99], v[96:97], v[154:155] op_sel:[1,0,0] op_sel_hi:[1,1,1]
	v_pk_mul_f32 v[192:193], v[0:1], v[100:101]
	v_pk_fma_f32 v[192:193], v[2:3], v[102:103], v[192:193]
	v_pk_fma_f32 v[192:193], v[4:5], v[104:105], v[192:193]
	v_pk_fma_f32 v[192:193], v[6:7], v[106:107], v[192:193]
	v_add_f32_e32 v160, v192, v193
	v_pk_mul_f32 v[194:195], v[8:9], v[100:101]
	v_pk_fma_f32 v[194:195], v[10:11], v[102:103], v[194:195]
	v_pk_fma_f32 v[194:195], v[12:13], v[104:105], v[194:195]
	v_pk_fma_f32 v[194:195], v[14:15], v[106:107], v[194:195]
	v_add_f32_e32 v161, v194, v195
	v_pk_fma_f32 v[0:1], v[128:129], v[82:83], v[132:133] op_sel_hi:[0,1,1] neg_lo:[1,0,0] neg_hi:[1,0,0]
	v_pk_fma_f32 v[2:3], v[128:129], v[84:85], v[134:135] op_sel_hi:[0,1,1] neg_lo:[1,0,0] neg_hi:[1,0,0]
	v_pk_fma_f32 v[4:5], v[128:129], v[86:87], v[136:137] op_sel_hi:[0,1,1] neg_lo:[1,0,0] neg_hi:[1,0,0]
	v_pk_fma_f32 v[6:7], v[128:129], v[88:89], v[138:139] op_sel_hi:[0,1,1] neg_lo:[1,0,0] neg_hi:[1,0,0]
	v_pk_fma_f32 v[8:9], v[130:131], v[82:83], v[148:149] op_sel_hi:[0,1,1] neg_lo:[1,0,0] neg_hi:[1,0,0]
	v_pk_fma_f32 v[10:11], v[130:131], v[84:85], v[150:151] op_sel_hi:[0,1,1] neg_lo:[1,0,0] neg_hi:[1,0,0]
	v_pk_fma_f32 v[12:13], v[130:131], v[86:87], v[152:153] op_sel_hi:[0,1,1] neg_lo:[1,0,0] neg_hi:[1,0,0]
	v_pk_fma_f32 v[14:15], v[130:131], v[88:89], v[154:155] op_sel_hi:[0,1,1] neg_lo:[1,0,0] neg_hi:[1,0,0]
	s_waitcnt lgkmcnt(0)
	ds_read_b128 v[74:77], v25 offset:24320
	ds_read_b128 v[78:81], v25 offset:24336
	ds_read_b128 v[66:69], v26 offset:768
	ds_read_b128 v[70:73], v26 offset:784
	ds_read_b128 v[90:93], v25 offset:24832
	ds_read_b128 v[94:97], v25 offset:24848
	ds_read_b32 v98, v27 offset:25344
	ds_read_b32 v99, v27 offset:25472
	ds_read_b128 v[82:85], v25 offset:24576
	ds_read_b128 v[86:89], v25 offset:24592
	ds_read_b128 v[100:103], v25 offset:25088
	ds_read_b128 v[104:107], v25 offset:25104
	v_pk_mul_f32 v[124:125], v[0:1], v[40:41]
	v_pk_fma_f32 v[124:125], v[2:3], v[42:43], v[124:125]
	v_pk_fma_f32 v[124:125], v[4:5], v[44:45], v[124:125]
	v_pk_fma_f32 v[124:125], v[6:7], v[46:47], v[124:125]
	v_pk_mul_f32 v[126:127], v[8:9], v[40:41]
	v_pk_fma_f32 v[126:127], v[10:11], v[42:43], v[126:127]
	v_pk_fma_f32 v[126:127], v[12:13], v[44:45], v[126:127]
	v_pk_fma_f32 v[126:127], v[14:15], v[46:47], v[126:127]
	v_add_f32_e32 v128, v124, v125
	v_add_f32_e32 v130, v126, v127
	v_pk_mul_f32 v[132:133], v[0:1], v[32:33]
	v_pk_mul_f32 v[134:135], v[2:3], v[34:35]
	v_add_f32_dpp v128, v128, v128 quad_perm:[1,0,3,2] row_mask:0xf bank_mask:0xf bound_ctrl:1
	v_add_f32_dpp v130, v130, v130 quad_perm:[1,0,3,2] row_mask:0xf bank_mask:0xf bound_ctrl:1
	v_pk_mul_f32 v[136:137], v[4:5], v[36:37]
	v_pk_mul_f32 v[138:139], v[6:7], v[38:39]
	v_add_f32_dpp v128, v128, v128 quad_perm:[2,3,0,1] row_mask:0xf bank_mask:0xf bound_ctrl:1
	v_add_f32_dpp v130, v130, v130 quad_perm:[2,3,0,1] row_mask:0xf bank_mask:0xf bound_ctrl:1
	v_pk_mul_f32 v[148:149], v[8:9], v[32:33]
	v_pk_mul_f32 v[150:151], v[10:11], v[34:35]
	v_add_f32_dpp v128, v128, v128 row_half_mirror row_mask:0xf bank_mask:0xf bound_ctrl:1
	v_add_f32_dpp v130, v130, v130 row_half_mirror row_mask:0xf bank_mask:0xf bound_ctrl:1
	v_pk_mul_f32 v[152:153], v[12:13], v[36:37]
	v_pk_mul_f32 v[154:155], v[14:15], v[38:39]
	v_pk_fma_f32 v[132:133], v[64:65], v[56:57], v[132:133] op_sel_hi:[0,1,1]
	v_pk_fma_f32 v[134:135], v[64:65], v[58:59], v[134:135] op_sel_hi:[0,1,1]
	v_pk_fma_f32 v[136:137], v[64:65], v[60:61], v[136:137] op_sel_hi:[0,1,1]
	v_pk_fma_f32 v[138:139], v[64:65], v[62:63], v[138:139] op_sel_hi:[0,1,1]
	v_pk_fma_f32 v[148:149], v[64:65], v[56:57], v[148:149] op_sel:[1,0,0] op_sel_hi:[1,1,1]
	v_pk_fma_f32 v[150:151], v[64:65], v[58:59], v[150:151] op_sel:[1,0,0] op_sel_hi:[1,1,1]
	v_pk_fma_f32 v[152:153], v[64:65], v[60:61], v[152:153] op_sel:[1,0,0] op_sel_hi:[1,1,1]
	v_pk_fma_f32 v[154:155], v[64:65], v[62:63], v[154:155] op_sel:[1,0,0] op_sel_hi:[1,1,1]
	v_pk_mul_f32 v[192:193], v[0:1], v[108:109]
	v_pk_fma_f32 v[192:193], v[2:3], v[110:111], v[192:193]
	v_pk_fma_f32 v[192:193], v[4:5], v[112:113], v[192:193]
	v_pk_fma_f32 v[192:193], v[6:7], v[114:115], v[192:193]
	v_add_f32_e32 v162, v192, v193
	v_pk_mul_f32 v[194:195], v[8:9], v[108:109]
	v_pk_fma_f32 v[194:195], v[10:11], v[110:111], v[194:195]
	v_pk_fma_f32 v[194:195], v[12:13], v[112:113], v[194:195]
	v_pk_fma_f32 v[194:195], v[14:15], v[114:115], v[194:195]
	v_add_f32_e32 v163, v194, v195
	v_pk_fma_f32 v[0:1], v[128:129], v[48:49], v[132:133] op_sel_hi:[0,1,1] neg_lo:[1,0,0] neg_hi:[1,0,0]
	v_pk_fma_f32 v[2:3], v[128:129], v[50:51], v[134:135] op_sel_hi:[0,1,1] neg_lo:[1,0,0] neg_hi:[1,0,0]
	v_pk_fma_f32 v[4:5], v[128:129], v[52:53], v[136:137] op_sel_hi:[0,1,1] neg_lo:[1,0,0] neg_hi:[1,0,0]
	v_pk_fma_f32 v[6:7], v[128:129], v[54:55], v[138:139] op_sel_hi:[0,1,1] neg_lo:[1,0,0] neg_hi:[1,0,0]
	v_pk_fma_f32 v[8:9], v[130:131], v[48:49], v[148:149] op_sel_hi:[0,1,1] neg_lo:[1,0,0] neg_hi:[1,0,0]
	v_pk_fma_f32 v[10:11], v[130:131], v[50:51], v[150:151] op_sel_hi:[0,1,1] neg_lo:[1,0,0] neg_hi:[1,0,0]
	v_pk_fma_f32 v[12:13], v[130:131], v[52:53], v[152:153] op_sel_hi:[0,1,1] neg_lo:[1,0,0] neg_hi:[1,0,0]
	v_pk_fma_f32 v[14:15], v[130:131], v[54:55], v[154:155] op_sel_hi:[0,1,1] neg_lo:[1,0,0] neg_hi:[1,0,0]
	s_waitcnt lgkmcnt(0)
; __device__ __forceinline__ float red8_sum(float x) { x += dpp_f<0xB1>(x); x += dpp_f<0x4E>(x); x += dpp_f<0x141>(x); return x; }
; template <int RG, int NSW>
; __device__ __forceinline__ void scan_waves(const Params& p, float* lds, const int T, const int dir, const int wave, const int lane,
;                                            const size_t tok0, const int head, const int row_base) {
;     ...
;       LOADSTEP(0, 0);
; #pragma unroll
;       for (int st = 0; st < 16; ++st) {
;         const int B = st & 1;
;         if (st + 1 < 16) LOADSTEP(1 - B, st + 1);
;         asm volatile("" ::: "memory");
;         float sa[RG], o[RG];
; #pragma unroll
;         for (int g = 0; g < RG; ++g) {
;           f32x2_t a0 = S[g][0] * kk[B][0], a1 = S[g][1] * kk[B][1];
;           a0 = __builtin_elementwise_fma(S[g][2], kk[B][2], a0); a1 = __builtin_elementwise_fma(S[g][3], kk[B][3], a1);
;           a0 = a0 + a1; sa[g] = a0.x + a0.y;
;         }
; #pragma unroll
;         for (int g = 0; g < RG; ++g) sa[g] = -red8_sum(sa[g]);
; #pragma unroll
;         for (int g = 0; g < RG; ++g) {
;           const f32x2_t sav = {sa[g], sa[g]}, vvv = {vv[B][g], vv[B][g]};
; #pragma unroll
;           for (int k = 0; k < 4; ++k)
;             S[g][k] = __builtin_elementwise_fma(vvv, kd[B][k], __builtin_elementwise_fma(sav, qa[B][k], S[g][k] * w[B][k]));
;         }
; #pragma unroll
;         for (int g = 0; g < RG; ++g) {
;           f32x2_t a0 = S[g][0] * r[B][0], a1 = S[g][1] * r[B][1];
;           a0 = __builtin_elementwise_fma(S[g][2], r[B][2], a0); a1 = __builtin_elementwise_fma(S[g][3], r[B][3], a1);
;           a0 = a0 + a1; o[g] = a0.x + a0.y;
;         }
; #pragma unroll
;         for (int g = 0; g < RG; ++g) o[g] = red8_sum(o[g]);
;         float os = o[0];
; #pragma unroll
;         for (int g = 1; g < RG; ++g) os = (part == g) ? o[g] : os;
;         osv[st] = os;
;       }
	ds_read_b128 v[40:43], v25 offset:25600
	ds_read_b128 v[44:47], v25 offset:25616
	ds_read_b128 v[32:35], v26 offset:1024
	ds_read_b128 v[36:39], v26 offset:1040
	ds_read_b128 v[56:59], v25 offset:26112
	ds_read_b128 v[60:63], v25 offset:26128
	ds_read_b32 v64, v27 offset:26624
	ds_read_b32 v65, v27 offset:26752
	ds_read_b128 v[48:51], v25 offset:25856
	ds_read_b128 v[52:55], v25 offset:25872
	ds_read_b128 v[108:111], v25 offset:26368
	ds_read_b128 v[112:115], v25 offset:26384
	v_pk_mul_f32 v[124:125], v[0:1], v[74:75]
	v_pk_fma_f32 v[124:125], v[2:3], v[76:77], v[124:125]
	v_pk_fma_f32 v[124:125], v[4:5], v[78:79], v[124:125]
	v_pk_fma_f32 v[124:125], v[6:7], v[80:81], v[124:125]
	v_pk_mul_f32 v[126:127], v[8:9], v[74:75]
	v_pk_fma_f32 v[126:127], v[10:11], v[76:77], v[126:127]
	v_pk_fma_f32 v[126:127], v[12:13], v[78:79], v[126:127]
	v_pk_fma_f32 v[126:127], v[14:15], v[80:81], v[126:127]
	v_add_f32_e32 v128, v124, v125
	v_add_f32_e32 v130, v126, v127
	v_pk_mul_f32 v[132:133], v[0:1], v[66:67]
	v_pk_mul_f32 v[134:135], v[2:3], v[68:69]
	v_add_f32_dpp v128, v128, v128 quad_perm:[1,0,3,2] row_mask:0xf bank_mask:0xf bound_ctrl:1
	v_add_f32_dpp v130, v130, v130 quad_perm:[1,0,3,2] row_mask:0xf bank_mask:0xf bound_ctrl:1
	v_pk_mul_f32 v[136:137], v[4:5], v[70:71]
	v_pk_mul_f32 v[138:139], v[6:7], v[72:73]
	v_add_f32_dpp v128, v128, v128 quad_perm:[2,3,0,1] row_mask:0xf bank_mask:0xf bound_ctrl:1
	v_add_f32_dpp v130, v130, v130 quad_perm:[2,3,0,1] row_mask:0xf bank_mask:0xf bound_ctrl:1
	v_pk_mul_f32 v[148:149], v[8:9], v[66:67]
	v_pk_mul_f32 v[150:151], v[10:11], v[68:69]
	v_add_f32_dpp v128, v128, v128 row_half_mirror row_mask:0xf bank_mask:0xf bound_ctrl:1
	v_add_f32_dpp v130, v130, v130 row_half_mirror row_mask:0xf bank_mask:0xf bound_ctrl:1
	v_pk_mul_f32 v[152:153], v[12:13], v[70:71]
	v_pk_mul_f32 v[154:155], v[14:15], v[72:73]
	v_pk_fma_f32 v[132:133], v[98:99], v[90:91], v[132:133] op_sel_hi:[0,1,1]
	v_pk_fma_f32 v[134:135], v[98:99], v[92:93], v[134:135] op_sel_hi:[0,1,1]
	v_pk_fma_f32 v[136:137], v[98:99], v[94:95], v[136:137] op_sel_hi:[0,1,1]
	v_pk_fma_f32 v[138:139], v[98:99], v[96:97], v[138:139] op_sel_hi:[0,1,1]
	v_pk_fma_f32 v[148:149], v[98:99], v[90:91], v[148:149] op_sel:[1,0,0] op_sel_hi:[1,1,1]
	v_pk_fma_f32 v[150:151], v[98:99], v[92:93], v[150:151] op_sel:[1,0,0] op_sel_hi:[1,1,1]
	v_pk_fma_f32 v[152:153], v[98:99], v[94:95], v[152:153] op_sel:[1,0,0] op_sel_hi:[1,1,1]
	v_pk_fma_f32 v[154:155], v[98:99], v[96:97], v[154:155] op_sel:[1,0,0] op_sel_hi:[1,1,1]
	v_pk_mul_f32 v[192:193], v[0:1], v[116:117]
	v_pk_fma_f32 v[192:193], v[2:3], v[118:119], v[192:193]
	v_pk_fma_f32 v[192:193], v[4:5], v[120:121], v[192:193]
	v_pk_fma_f32 v[192:193], v[6:7], v[122:123], v[192:193]
	v_add_f32_e32 v164, v192, v193
	v_pk_mul_f32 v[194:195], v[8:9], v[116:117]
	v_pk_fma_f32 v[194:195], v[10:11], v[118:119], v[194:195]
	v_pk_fma_f32 v[194:195], v[12:13], v[120:121], v[194:195]
	v_pk_fma_f32 v[194:195], v[14:15], v[122:123], v[194:195]
	v_add_f32_e32 v165, v194, v195
	v_pk_fma_f32 v[0:1], v[128:129], v[82:83], v[132:133] op_sel_hi:[0,1,1] neg_lo:[1,0,0] neg_hi:[1,0,0]
	v_pk_fma_f32 v[2:3], v[128:129], v[84:85], v[134:135] op_sel_hi:[0,1,1] neg_lo:[1,0,0] neg_hi:[1,0,0]
	v_pk_fma_f32 v[4:5], v[128:129], v[86:87], v[136:137] op_sel_hi:[0,1,1] neg_lo:[1,0,0] neg_hi:[1,0,0]
	v_pk_fma_f32 v[6:7], v[128:129], v[88:89], v[138:139] op_sel_hi:[0,1,1] neg_lo:[1,0,0] neg_hi:[1,0,0]
	v_pk_fma_f32 v[8:9], v[130:131], v[82:83], v[148:149] op_sel_hi:[0,1,1] neg_lo:[1,0,0] neg_hi:[1,0,0]
	v_pk_fma_f32 v[10:11], v[130:131], v[84:85], v[150:151] op_sel_hi:[0,1,1] neg_lo:[1,0,0] neg_hi:[1,0,0]
	v_pk_fma_f32 v[12:13], v[130:131], v[86:87], v[152:153] op_sel_hi:[0,1,1] neg_lo:[1,0,0] neg_hi:[1,0,0]
	v_pk_fma_f32 v[14:15], v[130:131], v[88:89], v[154:155] op_sel_hi:[0,1,1] neg_lo:[1,0,0] neg_hi:[1,0,0]
	s_waitcnt lgkmcnt(0)
	ds_read_b128 v[74:77], v25 offset:26880
	ds_read_b128 v[78:81], v25 offset:26896
	ds_read_b128 v[66:69], v26 offset:1280
	ds_read_b128 v[70:73], v26 offset:1296
	ds_read_b128 v[90:93], v25 offset:27392
	ds_read_b128 v[94:97], v25 offset:27408
	ds_read_b32 v98, v27 offset:27904
	ds_read_b32 v99, v27 offset:28032
	ds_read_b128 v[82:85], v25 offset:27136
	ds_read_b128 v[86:89], v25 offset:27152
	ds_read_b128 v[116:119], v25 offset:27648
	ds_read_b128 v[120:123], v25 offset:27664
	v_pk_mul_f32 v[124:125], v[0:1], v[40:41]
	v_pk_fma_f32 v[124:125], v[2:3], v[42:43], v[124:125]
	v_pk_fma_f32 v[124:125], v[4:5], v[44:45], v[124:125]
	v_pk_fma_f32 v[124:125], v[6:7], v[46:47], v[124:125]
	v_pk_mul_f32 v[126:127], v[8:9], v[40:41]
	v_pk_fma_f32 v[126:127], v[10:11], v[42:43], v[126:127]
	v_pk_fma_f32 v[126:127], v[12:13], v[44:45], v[126:127]
	v_pk_fma_f32 v[126:127], v[14:15], v[46:47], v[126:127]
	v_add_f32_e32 v128, v124, v125
	v_add_f32_e32 v130, v126, v127
	v_pk_mul_f32 v[132:133], v[0:1], v[32:33]
	v_pk_mul_f32 v[134:135], v[2:3], v[34:35]
	v_add_f32_dpp v128, v128, v128 quad_perm:[1,0,3,2] row_mask:0xf bank_mask:0xf bound_ctrl:1
	v_add_f32_dpp v130, v130, v130 quad_perm:[1,0,3,2] row_mask:0xf bank_mask:0xf bound_ctrl:1
	v_pk_mul_f32 v[136:137], v[4:5], v[36:37]
	v_pk_mul_f32 v[138:139], v[6:7], v[38:39]
	v_add_f32_dpp v128, v128, v128 quad_perm:[2,3,0,1] row_mask:0xf bank_mask:0xf bound_ctrl:1
	v_add_f32_dpp v130, v130, v130 quad_perm:[2,3,0,1] row_mask:0xf bank_mask:0xf bound_ctrl:1
	v_pk_mul_f32 v[148:149], v[8:9], v[32:33]
	v_pk_mul_f32 v[150:151], v[10:11], v[34:35]
	v_add_f32_dpp v128, v128, v128 row_half_mirror row_mask:0xf bank_mask:0xf bound_ctrl:1
	v_add_f32_dpp v130, v130, v130 row_half_mirror row_mask:0xf bank_mask:0xf bound_ctrl:1
; __device__ __forceinline__ float red8_sum(float x) { x += dpp_f<0xB1>(x); x += dpp_f<0x4E>(x); x += dpp_f<0x141>(x); return x; }
; template <int RG, int NSW>
; __device__ __forceinline__ void scan_waves(const Params& p, float* lds, const int T, const int dir, const int wave, const int lane,
;                                            const size_t tok0, const int head, const int row_base) {
;     ...
;       LOADSTEP(0, 0);
; #pragma unroll
;       for (int st = 0; st < 16; ++st) {
;         const int B = st & 1;
;         if (st + 1 < 16) LOADSTEP(1 - B, st + 1);
;         asm volatile("" ::: "memory");
;         float sa[RG], o[RG];
; #pragma unroll
;         for (int g = 0; g < RG; ++g) {
;           f32x2_t a0 = S[g][0] * kk[B][0], a1 = S[g][1] * kk[B][1];
;           a0 = __builtin_elementwise_fma(S[g][2], kk[B][2], a0); a1 = __builtin_elementwise_fma(S[g][3], kk[B][3], a1);
;           a0 = a0 + a1; sa[g] = a0.x + a0.y;
;         }
; #pragma unroll
;         for (int g = 0; g < RG; ++g) sa[g] = -red8_sum(sa[g]);
; #pragma unroll
;         for (int g = 0; g < RG; ++g) {
;           const f32x2_t sav = {sa[g], sa[g]}, vvv = {vv[B][g], vv[B][g]};
; #pragma unroll
;           for (int k = 0; k < 4; ++k)
;             S[g][k] = __builtin_elementwise_fma(vvv, kd[B][k], __builtin_elementwise_fma(sav, qa[B][k], S[g][k] * w[B][k]));
;         }
; #pragma unroll
;         for (int g = 0; g < RG; ++g) {
;           f32x2_t a0 = S[g][0] * r[B][0], a1 = S[g][1] * r[B][1];
;           a0 = __builtin_elementwise_fma(S[g][2], r[B][2], a0); a1 = __builtin_elementwise_fma(S[g][3], r[B][3], a1);
;           a0 = a0 + a1; o[g] = a0.x + a0.y;
;         }
; #pragma unroll
;         for (int g = 0; g < RG; ++g) o[g] = red8_sum(o[g]);
;         float os = o[0];
; #pragma unroll
;         for (int g = 1; g < RG; ++g) os = (part == g) ? o[g] : os;
;         osv[st] = os;
;       }
	v_pk_mul_f32 v[152:153], v[12:13], v[36:37]
	v_pk_mul_f32 v[154:155], v[14:15], v[38:39]
	v_pk_fma_f32 v[132:133], v[64:65], v[56:57], v[132:133] op_sel_hi:[0,1,1]
	v_pk_fma_f32 v[134:135], v[64:65], v[58:59], v[134:135] op_sel_hi:[0,1,1]
	v_pk_fma_f32 v[136:137], v[64:65], v[60:61], v[136:137] op_sel_hi:[0,1,1]
	v_pk_fma_f32 v[138:139], v[64:65], v[62:63], v[138:139] op_sel_hi:[0,1,1]
	v_pk_fma_f32 v[148:149], v[64:65], v[56:57], v[148:149] op_sel:[1,0,0] op_sel_hi:[1,1,1]
	v_pk_fma_f32 v[150:151], v[64:65], v[58:59], v[150:151] op_sel:[1,0,0] op_sel_hi:[1,1,1]
	v_pk_fma_f32 v[152:153], v[64:65], v[60:61], v[152:153] op_sel:[1,0,0] op_sel_hi:[1,1,1]
	v_pk_fma_f32 v[154:155], v[64:65], v[62:63], v[154:155] op_sel:[1,0,0] op_sel_hi:[1,1,1]
	v_pk_mul_f32 v[192:193], v[0:1], v[100:101]
	v_pk_fma_f32 v[192:193], v[2:3], v[102:103], v[192:193]
	v_pk_fma_f32 v[192:193], v[4:5], v[104:105], v[192:193]
	v_pk_fma_f32 v[192:193], v[6:7], v[106:107], v[192:193]
	v_add_f32_e32 v166, v192, v193
	v_pk_mul_f32 v[194:195], v[8:9], v[100:101]
	v_pk_fma_f32 v[194:195], v[10:11], v[102:103], v[194:195]
	v_pk_fma_f32 v[194:195], v[12:13], v[104:105], v[194:195]
	v_pk_fma_f32 v[194:195], v[14:15], v[106:107], v[194:195]
	v_add_f32_e32 v167, v194, v195
	v_pk_fma_f32 v[0:1], v[128:129], v[48:49], v[132:133] op_sel_hi:[0,1,1] neg_lo:[1,0,0] neg_hi:[1,0,0]
	v_pk_fma_f32 v[2:3], v[128:129], v[50:51], v[134:135] op_sel_hi:[0,1,1] neg_lo:[1,0,0] neg_hi:[1,0,0]
	v_pk_fma_f32 v[4:5], v[128:129], v[52:53], v[136:137] op_sel_hi:[0,1,1] neg_lo:[1,0,0] neg_hi:[1,0,0]
	v_pk_fma_f32 v[6:7], v[128:129], v[54:55], v[138:139] op_sel_hi:[0,1,1] neg_lo:[1,0,0] neg_hi:[1,0,0]
	v_pk_fma_f32 v[8:9], v[130:131], v[48:49], v[148:149] op_sel_hi:[0,1,1] neg_lo:[1,0,0] neg_hi:[1,0,0]
	v_pk_fma_f32 v[10:11], v[130:131], v[50:51], v[150:151] op_sel_hi:[0,1,1] neg_lo:[1,0,0] neg_hi:[1,0,0]
	v_pk_fma_f32 v[12:13], v[130:131], v[52:53], v[152:153] op_sel_hi:[0,1,1] neg_lo:[1,0,0] neg_hi:[1,0,0]
	v_pk_fma_f32 v[14:15], v[130:131], v[54:55], v[154:155] op_sel_hi:[0,1,1] neg_lo:[1,0,0] neg_hi:[1,0,0]
	s_waitcnt lgkmcnt(0)
	ds_read_b128 v[40:43], v25 offset:28160
	ds_read_b128 v[44:47], v25 offset:28176
	ds_read_b128 v[32:35], v26 offset:1536
	ds_read_b128 v[36:39], v26 offset:1552
	ds_read_b128 v[56:59], v25 offset:28672
	ds_read_b128 v[60:63], v25 offset:28688
	ds_read_b32 v64, v27 offset:29184
	ds_read_b32 v65, v27 offset:29312
	ds_read_b128 v[48:51], v25 offset:28416
	ds_read_b128 v[52:55], v25 offset:28432
	ds_read_b128 v[100:103], v25 offset:28928
	ds_read_b128 v[104:107], v25 offset:28944
	v_pk_mul_f32 v[124:125], v[0:1], v[74:75]
	v_pk_fma_f32 v[124:125], v[2:3], v[76:77], v[124:125]
	v_pk_fma_f32 v[124:125], v[4:5], v[78:79], v[124:125]
	v_pk_fma_f32 v[124:125], v[6:7], v[80:81], v[124:125]
	v_pk_mul_f32 v[126:127], v[8:9], v[74:75]
	v_pk_fma_f32 v[126:127], v[10:11], v[76:77], v[126:127]
	v_pk_fma_f32 v[126:127], v[12:13], v[78:79], v[126:127]
	v_pk_fma_f32 v[126:127], v[14:15], v[80:81], v[126:127]
	v_add_f32_e32 v128, v124, v125
	v_add_f32_e32 v130, v126, v127
	v_pk_mul_f32 v[132:133], v[0:1], v[66:67]
	v_pk_mul_f32 v[134:135], v[2:3], v[68:69]
	v_add_f32_dpp v128, v128, v128 quad_perm:[1,0,3,2] row_mask:0xf bank_mask:0xf bound_ctrl:1
	v_add_f32_dpp v130, v130, v130 quad_perm:[1,0,3,2] row_mask:0xf bank_mask:0xf bound_ctrl:1
	v_pk_mul_f32 v[136:137], v[4:5], v[70:71]
	v_pk_mul_f32 v[138:139], v[6:7], v[72:73]
	v_add_f32_dpp v128, v128, v128 quad_perm:[2,3,0,1] row_mask:0xf bank_mask:0xf bound_ctrl:1
	v_add_f32_dpp v130, v130, v130 quad_perm:[2,3,0,1] row_mask:0xf bank_mask:0xf bound_ctrl:1
	v_pk_mul_f32 v[148:149], v[8:9], v[66:67]
	v_pk_mul_f32 v[150:151], v[10:11], v[68:69]
	v_add_f32_dpp v128, v128, v128 row_half_mirror row_mask:0xf bank_mask:0xf bound_ctrl:1
	v_add_f32_dpp v130, v130, v130 row_half_mirror row_mask:0xf bank_mask:0xf bound_ctrl:1
	v_pk_mul_f32 v[152:153], v[12:13], v[70:71]
	v_pk_mul_f32 v[154:155], v[14:15], v[72:73]
	v_pk_fma_f32 v[132:133], v[98:99], v[90:91], v[132:133] op_sel_hi:[0,1,1]
	v_pk_fma_f32 v[134:135], v[98:99], v[92:93], v[134:135] op_sel_hi:[0,1,1]
	v_pk_fma_f32 v[136:137], v[98:99], v[94:95], v[136:137] op_sel_hi:[0,1,1]
	v_pk_fma_f32 v[138:139], v[98:99], v[96:97], v[138:139] op_sel_hi:[0,1,1]
	v_pk_fma_f32 v[148:149], v[98:99], v[90:91], v[148:149] op_sel:[1,0,0] op_sel_hi:[1,1,1]
	v_pk_fma_f32 v[150:151], v[98:99], v[92:93], v[150:151] op_sel:[1,0,0] op_sel_hi:[1,1,1]
	v_pk_fma_f32 v[152:153], v[98:99], v[94:95], v[152:153] op_sel:[1,0,0] op_sel_hi:[1,1,1]
	v_pk_fma_f32 v[154:155], v[98:99], v[96:97], v[154:155] op_sel:[1,0,0] op_sel_hi:[1,1,1]
	v_pk_mul_f32 v[192:193], v[0:1], v[108:109]
	v_pk_fma_f32 v[192:193], v[2:3], v[110:111], v[192:193]
	v_pk_fma_f32 v[192:193], v[4:5], v[112:113], v[192:193]
	v_pk_fma_f32 v[192:193], v[6:7], v[114:115], v[192:193]
	v_add_f32_e32 v168, v192, v193
	v_pk_mul_f32 v[194:195], v[8:9], v[108:109]
	v_pk_fma_f32 v[194:195], v[10:11], v[110:111], v[194:195]
	v_pk_fma_f32 v[194:195], v[12:13], v[112:113], v[194:195]
	v_pk_fma_f32 v[194:195], v[14:15], v[114:115], v[194:195]
	v_add_f32_e32 v169, v194, v195
	v_pk_fma_f32 v[0:1], v[128:129], v[82:83], v[132:133] op_sel_hi:[0,1,1] neg_lo:[1,0,0] neg_hi:[1,0,0]
	v_pk_fma_f32 v[2:3], v[128:129], v[84:85], v[134:135] op_sel_hi:[0,1,1] neg_lo:[1,0,0] neg_hi:[1,0,0]
	v_pk_fma_f32 v[4:5], v[128:129], v[86:87], v[136:137] op_sel_hi:[0,1,1] neg_lo:[1,0,0] neg_hi:[1,0,0]
	v_pk_fma_f32 v[6:7], v[128:129], v[88:89], v[138:139] op_sel_hi:[0,1,1] neg_lo:[1,0,0] neg_hi:[1,0,0]
	v_pk_fma_f32 v[8:9], v[130:131], v[82:83], v[148:149] op_sel_hi:[0,1,1] neg_lo:[1,0,0] neg_hi:[1,0,0]
	v_pk_fma_f32 v[10:11], v[130:131], v[84:85], v[150:151] op_sel_hi:[0,1,1] neg_lo:[1,0,0] neg_hi:[1,0,0]
	v_pk_fma_f32 v[12:13], v[130:131], v[86:87], v[152:153] op_sel_hi:[0,1,1] neg_lo:[1,0,0] neg_hi:[1,0,0]
	v_pk_fma_f32 v[14:15], v[130:131], v[88:89], v[154:155] op_sel_hi:[0,1,1] neg_lo:[1,0,0] neg_hi:[1,0,0]
	s_waitcnt lgkmcnt(0)
; __device__ __forceinline__ float red8_sum(float x) { x += dpp_f<0xB1>(x); x += dpp_f<0x4E>(x); x += dpp_f<0x141>(x); return x; }
; template <int RG, int NSW>
; __device__ __forceinline__ void scan_waves(const Params& p, float* lds, const int T, const int dir, const int wave, const int lane,
;                                            const size_t tok0, const int head, const int row_base) {
;     ...
;       LOADSTEP(0, 0);
; #pragma unroll
;       for (int st = 0; st < 16; ++st) {
;         const int B = st & 1;
;         if (st + 1 < 16) LOADSTEP(1 - B, st + 1);
;         asm volatile("" ::: "memory");
;         float sa[RG], o[RG];
; #pragma unroll
;         for (int g = 0; g < RG; ++g) {
;           f32x2_t a0 = S[g][0] * kk[B][0], a1 = S[g][1] * kk[B][1];
;           a0 = __builtin_elementwise_fma(S[g][2], kk[B][2], a0); a1 = __builtin_elementwise_fma(S[g][3], kk[B][3], a1);
;           a0 = a0 + a1; sa[g] = a0.x + a0.y;
;         }
; #pragma unroll
;         for (int g = 0; g < RG; ++g) sa[g] = -red8_sum(sa[g]);
; #pragma unroll
;         for (int g = 0; g < RG; ++g) {
;           const f32x2_t sav = {sa[g], sa[g]}, vvv = {vv[B][g], vv[B][g]};
; #pragma unroll
;           for (int k = 0; k < 4; ++k)
;             S[g][k] = __builtin_elementwise_fma(vvv, kd[B][k], __builtin_elementwise_fma(sav, qa[B][k], S[g][k] * w[B][k]));
;         }
; #pragma unroll
;         for (int g = 0; g < RG; ++g) {
;           f32x2_t a0 = S[g][0] * r[B][0], a1 = S[g][1] * r[B][1];
;           a0 = __builtin_elementwise_fma(S[g][2], r[B][2], a0); a1 = __builtin_elementwise_fma(S[g][3], r[B][3], a1);
;           a0 = a0 + a1; o[g] = a0.x + a0.y;
;         }
; #pragma unroll
;         for (int g = 0; g < RG; ++g) o[g] = red8_sum(o[g]);
;         float os = o[0];
; #pragma unroll
;         for (int g = 1; g < RG; ++g) os = (part == g) ? o[g] : os;
;         osv[st] = os;
;       }
	ds_read_b128 v[74:77], v25 offset:29440
	ds_read_b128 v[78:81], v25 offset:29456
	ds_read_b128 v[66:69], v26 offset:1792
	ds_read_b128 v[70:73], v26 offset:1808
	ds_read_b128 v[90:93], v25 offset:29952
	ds_read_b128 v[94:97], v25 offset:29968
	ds_read_b32 v98, v27 offset:30464
	ds_read_b32 v99, v27 offset:30592
	ds_read_b128 v[82:85], v25 offset:29696
	ds_read_b128 v[86:89], v25 offset:29712
	ds_read_b128 v[108:111], v25 offset:30208
	ds_read_b128 v[112:115], v25 offset:30224
	v_pk_mul_f32 v[124:125], v[0:1], v[40:41]
	v_pk_fma_f32 v[124:125], v[2:3], v[42:43], v[124:125]
	v_pk_fma_f32 v[124:125], v[4:5], v[44:45], v[124:125]
	v_pk_fma_f32 v[124:125], v[6:7], v[46:47], v[124:125]
	v_pk_mul_f32 v[126:127], v[8:9], v[40:41]
	v_pk_fma_f32 v[126:127], v[10:11], v[42:43], v[126:127]
	v_pk_fma_f32 v[126:127], v[12:13], v[44:45], v[126:127]
	v_pk_fma_f32 v[126:127], v[14:15], v[46:47], v[126:127]
	v_add_f32_e32 v128, v124, v125
	v_add_f32_e32 v130, v126, v127
	v_pk_mul_f32 v[132:133], v[0:1], v[32:33]
	v_pk_mul_f32 v[134:135], v[2:3], v[34:35]
	v_add_f32_dpp v128, v128, v128 quad_perm:[1,0,3,2] row_mask:0xf bank_mask:0xf bound_ctrl:1
	v_add_f32_dpp v130, v130, v130 quad_perm:[1,0,3,2] row_mask:0xf bank_mask:0xf bound_ctrl:1
	v_pk_mul_f32 v[136:137], v[4:5], v[36:37]
	v_pk_mul_f32 v[138:139], v[6:7], v[38:39]
	v_add_f32_dpp v128, v128, v128 quad_perm:[2,3,0,1] row_mask:0xf bank_mask:0xf bound_ctrl:1
	v_add_f32_dpp v130, v130, v130 quad_perm:[2,3,0,1] row_mask:0xf bank_mask:0xf bound_ctrl:1
	v_pk_mul_f32 v[148:149], v[8:9], v[32:33]
	v_pk_mul_f32 v[150:151], v[10:11], v[34:35]
	v_add_f32_dpp v128, v128, v128 row_half_mirror row_mask:0xf bank_mask:0xf bound_ctrl:1
	v_add_f32_dpp v130, v130, v130 row_half_mirror row_mask:0xf bank_mask:0xf bound_ctrl:1
	v_pk_mul_f32 v[152:153], v[12:13], v[36:37]
	v_pk_mul_f32 v[154:155], v[14:15], v[38:39]
	v_pk_fma_f32 v[132:133], v[64:65], v[56:57], v[132:133] op_sel_hi:[0,1,1]
	v_pk_fma_f32 v[134:135], v[64:65], v[58:59], v[134:135] op_sel_hi:[0,1,1]
	v_pk_fma_f32 v[136:137], v[64:65], v[60:61], v[136:137] op_sel_hi:[0,1,1]
	v_pk_fma_f32 v[138:139], v[64:65], v[62:63], v[138:139] op_sel_hi:[0,1,1]
	v_pk_fma_f32 v[148:149], v[64:65], v[56:57], v[148:149] op_sel:[1,0,0] op_sel_hi:[1,1,1]
	v_pk_fma_f32 v[150:151], v[64:65], v[58:59], v[150:151] op_sel:[1,0,0] op_sel_hi:[1,1,1]
	v_pk_fma_f32 v[152:153], v[64:65], v[60:61], v[152:153] op_sel:[1,0,0] op_sel_hi:[1,1,1]
	v_pk_fma_f32 v[154:155], v[64:65], v[62:63], v[154:155] op_sel:[1,0,0] op_sel_hi:[1,1,1]
	v_pk_mul_f32 v[192:193], v[0:1], v[116:117]
	v_pk_fma_f32 v[192:193], v[2:3], v[118:119], v[192:193]
	v_pk_fma_f32 v[192:193], v[4:5], v[120:121], v[192:193]
	v_pk_fma_f32 v[192:193], v[6:7], v[122:123], v[192:193]
	v_add_f32_e32 v170, v192, v193
	v_pk_mul_f32 v[194:195], v[8:9], v[116:117]
	v_pk_fma_f32 v[194:195], v[10:11], v[118:119], v[194:195]
	v_pk_fma_f32 v[194:195], v[12:13], v[120:121], v[194:195]
	v_pk_fma_f32 v[194:195], v[14:15], v[122:123], v[194:195]
	v_add_f32_e32 v171, v194, v195
	v_pk_fma_f32 v[0:1], v[128:129], v[48:49], v[132:133] op_sel_hi:[0,1,1] neg_lo:[1,0,0] neg_hi:[1,0,0]
	v_pk_fma_f32 v[2:3], v[128:129], v[50:51], v[134:135] op_sel_hi:[0,1,1] neg_lo:[1,0,0] neg_hi:[1,0,0]
	v_pk_fma_f32 v[4:5], v[128:129], v[52:53], v[136:137] op_sel_hi:[0,1,1] neg_lo:[1,0,0] neg_hi:[1,0,0]
	v_pk_fma_f32 v[6:7], v[128:129], v[54:55], v[138:139] op_sel_hi:[0,1,1] neg_lo:[1,0,0] neg_hi:[1,0,0]
	v_pk_fma_f32 v[8:9], v[130:131], v[48:49], v[148:149] op_sel_hi:[0,1,1] neg_lo:[1,0,0] neg_hi:[1,0,0]
	v_pk_fma_f32 v[10:11], v[130:131], v[50:51], v[150:151] op_sel_hi:[0,1,1] neg_lo:[1,0,0] neg_hi:[1,0,0]
	v_pk_fma_f32 v[12:13], v[130:131], v[52:53], v[152:153] op_sel_hi:[0,1,1] neg_lo:[1,0,0] neg_hi:[1,0,0]
	v_pk_fma_f32 v[14:15], v[130:131], v[54:55], v[154:155] op_sel_hi:[0,1,1] neg_lo:[1,0,0] neg_hi:[1,0,0]
	s_waitcnt lgkmcnt(0)
	ds_read_b128 v[40:43], v25 offset:30720
	ds_read_b128 v[44:47], v25 offset:30736
	ds_read_b128 v[32:35], v26 offset:2048
	ds_read_b128 v[36:39], v26 offset:2064
	ds_read_b128 v[56:59], v25 offset:31232
	ds_read_b128 v[60:63], v25 offset:31248
	ds_read_b32 v64, v27 offset:31744
	ds_read_b32 v65, v27 offset:31872
	ds_read_b128 v[48:51], v25 offset:30976
	ds_read_b128 v[52:55], v25 offset:30992
	ds_read_b128 v[116:119], v25 offset:31488
	ds_read_b128 v[120:123], v25 offset:31504
	v_pk_mul_f32 v[124:125], v[0:1], v[74:75]
	v_pk_fma_f32 v[124:125], v[2:3], v[76:77], v[124:125]
	v_pk_fma_f32 v[124:125], v[4:5], v[78:79], v[124:125]
	v_pk_fma_f32 v[124:125], v[6:7], v[80:81], v[124:125]
	v_pk_mul_f32 v[126:127], v[8:9], v[74:75]
	v_pk_fma_f32 v[126:127], v[10:11], v[76:77], v[126:127]
	v_pk_fma_f32 v[126:127], v[12:13], v[78:79], v[126:127]
	v_pk_fma_f32 v[126:127], v[14:15], v[80:81], v[126:127]
	v_add_f32_e32 v128, v124, v125
	v_add_f32_e32 v130, v126, v127
	v_pk_mul_f32 v[132:133], v[0:1], v[66:67]
	v_pk_mul_f32 v[134:135], v[2:3], v[68:69]
	v_add_f32_dpp v128, v128, v128 quad_perm:[1,0,3,2] row_mask:0xf bank_mask:0xf bound_ctrl:1
	v_add_f32_dpp v130, v130, v130 quad_perm:[1,0,3,2] row_mask:0xf bank_mask:0xf bound_ctrl:1
	v_pk_mul_f32 v[136:137], v[4:5], v[70:71]
	v_pk_mul_f32 v[138:139], v[6:7], v[72:73]
	v_add_f32_dpp v128, v128, v128 quad_perm:[2,3,0,1] row_mask:0xf bank_mask:0xf bound_ctrl:1
	v_add_f32_dpp v130, v130, v130 quad_perm:[2,3,0,1] row_mask:0xf bank_mask:0xf bound_ctrl:1
	v_pk_mul_f32 v[148:149], v[8:9], v[66:67]
	v_pk_mul_f32 v[150:151], v[10:11], v[68:69]
	v_add_f32_dpp v128, v128, v128 row_half_mirror row_mask:0xf bank_mask:0xf bound_ctrl:1
	v_add_f32_dpp v130, v130, v130 row_half_mirror row_mask:0xf bank_mask:0xf bound_ctrl:1
; __device__ __forceinline__ float red8_sum(float x) { x += dpp_f<0xB1>(x); x += dpp_f<0x4E>(x); x += dpp_f<0x141>(x); return x; }
; template <int RG, int NSW>
; __device__ __forceinline__ void scan_waves(const Params& p, float* lds, const int T, const int dir, const int wave, const int lane,
;                                            const size_t tok0, const int head, const int row_base) {
;     ...
;       LOADSTEP(0, 0);
; #pragma unroll
;       for (int st = 0; st < 16; ++st) {
;         const int B = st & 1;
;         if (st + 1 < 16) LOADSTEP(1 - B, st + 1);
;         asm volatile("" ::: "memory");
;         float sa[RG], o[RG];
; #pragma unroll
;         for (int g = 0; g < RG; ++g) {
;           f32x2_t a0 = S[g][0] * kk[B][0], a1 = S[g][1] * kk[B][1];
;           a0 = __builtin_elementwise_fma(S[g][2], kk[B][2], a0); a1 = __builtin_elementwise_fma(S[g][3], kk[B][3], a1);
;           a0 = a0 + a1; sa[g] = a0.x + a0.y;
;         }
; #pragma unroll
;         for (int g = 0; g < RG; ++g) sa[g] = -red8_sum(sa[g]);
; #pragma unroll
;         for (int g = 0; g < RG; ++g) {
;           const f32x2_t sav = {sa[g], sa[g]}, vvv = {vv[B][g], vv[B][g]};
; #pragma unroll
;           for (int k = 0; k < 4; ++k)
;             S[g][k] = __builtin_elementwise_fma(vvv, kd[B][k], __builtin_elementwise_fma(sav, qa[B][k], S[g][k] * w[B][k]));
;         }
; #pragma unroll
;         for (int g = 0; g < RG; ++g) {
;           f32x2_t a0 = S[g][0] * r[B][0], a1 = S[g][1] * r[B][1];
;           a0 = __builtin_elementwise_fma(S[g][2], r[B][2], a0); a1 = __builtin_elementwise_fma(S[g][3], r[B][3], a1);
;           a0 = a0 + a1; o[g] = a0.x + a0.y;
;         }
; #pragma unroll
;         for (int g = 0; g < RG; ++g) o[g] = red8_sum(o[g]);
;         float os = o[0];
; #pragma unroll
;         for (int g = 1; g < RG; ++g) os = (part == g) ? o[g] : os;
;         osv[st] = os;
;       }
	v_pk_mul_f32 v[152:153], v[12:13], v[70:71]
	v_pk_mul_f32 v[154:155], v[14:15], v[72:73]
	v_pk_fma_f32 v[132:133], v[98:99], v[90:91], v[132:133] op_sel_hi:[0,1,1]
	v_pk_fma_f32 v[134:135], v[98:99], v[92:93], v[134:135] op_sel_hi:[0,1,1]
	v_pk_fma_f32 v[136:137], v[98:99], v[94:95], v[136:137] op_sel_hi:[0,1,1]
	v_pk_fma_f32 v[138:139], v[98:99], v[96:97], v[138:139] op_sel_hi:[0,1,1]
	v_pk_fma_f32 v[148:149], v[98:99], v[90:91], v[148:149] op_sel:[1,0,0] op_sel_hi:[1,1,1]
	v_pk_fma_f32 v[150:151], v[98:99], v[92:93], v[150:151] op_sel:[1,0,0] op_sel_hi:[1,1,1]
	v_pk_fma_f32 v[152:153], v[98:99], v[94:95], v[152:153] op_sel:[1,0,0] op_sel_hi:[1,1,1]
	v_pk_fma_f32 v[154:155], v[98:99], v[96:97], v[154:155] op_sel:[1,0,0] op_sel_hi:[1,1,1]
	v_pk_mul_f32 v[192:193], v[0:1], v[100:101]
	v_pk_fma_f32 v[192:193], v[2:3], v[102:103], v[192:193]
	v_pk_fma_f32 v[192:193], v[4:5], v[104:105], v[192:193]
	v_pk_fma_f32 v[192:193], v[6:7], v[106:107], v[192:193]
	v_add_f32_e32 v172, v192, v193
	v_pk_mul_f32 v[194:195], v[8:9], v[100:101]
	v_pk_fma_f32 v[194:195], v[10:11], v[102:103], v[194:195]
	v_pk_fma_f32 v[194:195], v[12:13], v[104:105], v[194:195]
	v_pk_fma_f32 v[194:195], v[14:15], v[106:107], v[194:195]
	v_add_f32_e32 v173, v194, v195
	v_pk_fma_f32 v[0:1], v[128:129], v[82:83], v[132:133] op_sel_hi:[0,1,1] neg_lo:[1,0,0] neg_hi:[1,0,0]
	v_pk_fma_f32 v[2:3], v[128:129], v[84:85], v[134:135] op_sel_hi:[0,1,1] neg_lo:[1,0,0] neg_hi:[1,0,0]
	v_pk_fma_f32 v[4:5], v[128:129], v[86:87], v[136:137] op_sel_hi:[0,1,1] neg_lo:[1,0,0] neg_hi:[1,0,0]
	v_pk_fma_f32 v[6:7], v[128:129], v[88:89], v[138:139] op_sel_hi:[0,1,1] neg_lo:[1,0,0] neg_hi:[1,0,0]
	v_pk_fma_f32 v[8:9], v[130:131], v[82:83], v[148:149] op_sel_hi:[0,1,1] neg_lo:[1,0,0] neg_hi:[1,0,0]
	v_pk_fma_f32 v[10:11], v[130:131], v[84:85], v[150:151] op_sel_hi:[0,1,1] neg_lo:[1,0,0] neg_hi:[1,0,0]
	v_pk_fma_f32 v[12:13], v[130:131], v[86:87], v[152:153] op_sel_hi:[0,1,1] neg_lo:[1,0,0] neg_hi:[1,0,0]
	v_pk_fma_f32 v[14:15], v[130:131], v[88:89], v[154:155] op_sel_hi:[0,1,1] neg_lo:[1,0,0] neg_hi:[1,0,0]
	s_waitcnt lgkmcnt(0)
	ds_read_b128 v[74:77], v25 offset:32000
	ds_read_b128 v[78:81], v25 offset:32016
	ds_read_b128 v[66:69], v26 offset:2304
	ds_read_b128 v[70:73], v26 offset:2320
	ds_read_b128 v[90:93], v25 offset:32512
	ds_read_b128 v[94:97], v25 offset:32528
	ds_read_b32 v98, v27 offset:33024
	ds_read_b32 v99, v27 offset:33152
	ds_read_b128 v[82:85], v25 offset:32256
	ds_read_b128 v[86:89], v25 offset:32272
	ds_read_b128 v[100:103], v25 offset:32768
	ds_read_b128 v[104:107], v25 offset:32784
	v_pk_mul_f32 v[124:125], v[0:1], v[40:41]
	v_pk_fma_f32 v[124:125], v[2:3], v[42:43], v[124:125]
	v_pk_fma_f32 v[124:125], v[4:5], v[44:45], v[124:125]
	v_pk_fma_f32 v[124:125], v[6:7], v[46:47], v[124:125]
	v_pk_mul_f32 v[126:127], v[8:9], v[40:41]
	v_pk_fma_f32 v[126:127], v[10:11], v[42:43], v[126:127]
	v_pk_fma_f32 v[126:127], v[12:13], v[44:45], v[126:127]
	v_pk_fma_f32 v[126:127], v[14:15], v[46:47], v[126:127]
	v_add_f32_e32 v128, v124, v125
	v_add_f32_e32 v130, v126, v127
	v_pk_mul_f32 v[132:133], v[0:1], v[32:33]
	v_pk_mul_f32 v[134:135], v[2:3], v[34:35]
	v_add_f32_dpp v128, v128, v128 quad_perm:[1,0,3,2] row_mask:0xf bank_mask:0xf bound_ctrl:1
	v_add_f32_dpp v130, v130, v130 quad_perm:[1,0,3,2] row_mask:0xf bank_mask:0xf bound_ctrl:1
	v_pk_mul_f32 v[136:137], v[4:5], v[36:37]
	v_pk_mul_f32 v[138:139], v[6:7], v[38:39]
	v_add_f32_dpp v128, v128, v128 quad_perm:[2,3,0,1] row_mask:0xf bank_mask:0xf bound_ctrl:1
	v_add_f32_dpp v130, v130, v130 quad_perm:[2,3,0,1] row_mask:0xf bank_mask:0xf bound_ctrl:1
	v_pk_mul_f32 v[148:149], v[8:9], v[32:33]
	v_pk_mul_f32 v[150:151], v[10:11], v[34:35]
	v_add_f32_dpp v128, v128, v128 row_half_mirror row_mask:0xf bank_mask:0xf bound_ctrl:1
	v_add_f32_dpp v130, v130, v130 row_half_mirror row_mask:0xf bank_mask:0xf bound_ctrl:1
	v_pk_mul_f32 v[152:153], v[12:13], v[36:37]
	v_pk_mul_f32 v[154:155], v[14:15], v[38:39]
	v_pk_fma_f32 v[132:133], v[64:65], v[56:57], v[132:133] op_sel_hi:[0,1,1]
	v_pk_fma_f32 v[134:135], v[64:65], v[58:59], v[134:135] op_sel_hi:[0,1,1]
	v_pk_fma_f32 v[136:137], v[64:65], v[60:61], v[136:137] op_sel_hi:[0,1,1]
	v_pk_fma_f32 v[138:139], v[64:65], v[62:63], v[138:139] op_sel_hi:[0,1,1]
	v_pk_fma_f32 v[148:149], v[64:65], v[56:57], v[148:149] op_sel:[1,0,0] op_sel_hi:[1,1,1]
	v_pk_fma_f32 v[150:151], v[64:65], v[58:59], v[150:151] op_sel:[1,0,0] op_sel_hi:[1,1,1]
	v_pk_fma_f32 v[152:153], v[64:65], v[60:61], v[152:153] op_sel:[1,0,0] op_sel_hi:[1,1,1]
	v_pk_fma_f32 v[154:155], v[64:65], v[62:63], v[154:155] op_sel:[1,0,0] op_sel_hi:[1,1,1]
	v_pk_mul_f32 v[192:193], v[0:1], v[108:109]
	v_pk_fma_f32 v[192:193], v[2:3], v[110:111], v[192:193]
	v_pk_fma_f32 v[192:193], v[4:5], v[112:113], v[192:193]
	v_pk_fma_f32 v[192:193], v[6:7], v[114:115], v[192:193]
	v_add_f32_e32 v174, v192, v193
	v_pk_mul_f32 v[194:195], v[8:9], v[108:109]
	v_pk_fma_f32 v[194:195], v[10:11], v[110:111], v[194:195]
	v_pk_fma_f32 v[194:195], v[12:13], v[112:113], v[194:195]
	v_pk_fma_f32 v[194:195], v[14:15], v[114:115], v[194:195]
	v_add_f32_e32 v175, v194, v195
	v_pk_fma_f32 v[0:1], v[128:129], v[48:49], v[132:133] op_sel_hi:[0,1,1] neg_lo:[1,0,0] neg_hi:[1,0,0]
	v_pk_fma_f32 v[2:3], v[128:129], v[50:51], v[134:135] op_sel_hi:[0,1,1] neg_lo:[1,0,0] neg_hi:[1,0,0]
	v_pk_fma_f32 v[4:5], v[128:129], v[52:53], v[136:137] op_sel_hi:[0,1,1] neg_lo:[1,0,0] neg_hi:[1,0,0]
	v_pk_fma_f32 v[6:7], v[128:129], v[54:55], v[138:139] op_sel_hi:[0,1,1] neg_lo:[1,0,0] neg_hi:[1,0,0]
	v_pk_fma_f32 v[8:9], v[130:131], v[48:49], v[148:149] op_sel_hi:[0,1,1] neg_lo:[1,0,0] neg_hi:[1,0,0]
	v_pk_fma_f32 v[10:11], v[130:131], v[50:51], v[150:151] op_sel_hi:[0,1,1] neg_lo:[1,0,0] neg_hi:[1,0,0]
	v_pk_fma_f32 v[12:13], v[130:131], v[52:53], v[152:153] op_sel_hi:[0,1,1] neg_lo:[1,0,0] neg_hi:[1,0,0]
	v_pk_fma_f32 v[14:15], v[130:131], v[54:55], v[154:155] op_sel_hi:[0,1,1] neg_lo:[1,0,0] neg_hi:[1,0,0]
	s_waitcnt lgkmcnt(0)
; __device__ __forceinline__ float red8_sum(float x) { x += dpp_f<0xB1>(x); x += dpp_f<0x4E>(x); x += dpp_f<0x141>(x); return x; }
; template <int RG, int NSW>
; __device__ __forceinline__ void scan_waves(const Params& p, float* lds, const int T, const int dir, const int wave, const int lane,
;                                            const size_t tok0, const int head, const int row_base) {
;     ...
;       LOADSTEP(0, 0);
; #pragma unroll
;       for (int st = 0; st < 16; ++st) {
;         const int B = st & 1;
;         if (st + 1 < 16) LOADSTEP(1 - B, st + 1);
;         asm volatile("" ::: "memory");
;         float sa[RG], o[RG];
; #pragma unroll
;         for (int g = 0; g < RG; ++g) {
;           f32x2_t a0 = S[g][0] * kk[B][0], a1 = S[g][1] * kk[B][1];
;           a0 = __builtin_elementwise_fma(S[g][2], kk[B][2], a0); a1 = __builtin_elementwise_fma(S[g][3], kk[B][3], a1);
;           a0 = a0 + a1; sa[g] = a0.x + a0.y;
;         }
; #pragma unroll
;         for (int g = 0; g < RG; ++g) sa[g] = -red8_sum(sa[g]);
; #pragma unroll
;         for (int g = 0; g < RG; ++g) {
;           const f32x2_t sav = {sa[g], sa[g]}, vvv = {vv[B][g], vv[B][g]};
; #pragma unroll
;           for (int k = 0; k < 4; ++k)
;             S[g][k] = __builtin_elementwise_fma(vvv, kd[B][k], __builtin_elementwise_fma(sav, qa[B][k], S[g][k] * w[B][k]));
;         }
; #pragma unroll
;         for (int g = 0; g < RG; ++g) {
;           f32x2_t a0 = S[g][0] * r[B][0], a1 = S[g][1] * r[B][1];
;           a0 = __builtin_elementwise_fma(S[g][2], r[B][2], a0); a1 = __builtin_elementwise_fma(S[g][3], r[B][3], a1);
;           a0 = a0 + a1; o[g] = a0.x + a0.y;
;         }
; #pragma unroll
;         for (int g = 0; g < RG; ++g) o[g] = red8_sum(o[g]);
;         float os = o[0];
; #pragma unroll
;         for (int g = 1; g < RG; ++g) os = (part == g) ? o[g] : os;
;         osv[st] = os;
;       }
	ds_read_b128 v[40:43], v25 offset:33280
	ds_read_b128 v[44:47], v25 offset:33296
	ds_read_b128 v[32:35], v26 offset:2560
	ds_read_b128 v[36:39], v26 offset:2576
	ds_read_b128 v[56:59], v25 offset:33792
	ds_read_b128 v[60:63], v25 offset:33808
	ds_read_b32 v64, v27 offset:34304
	ds_read_b32 v65, v27 offset:34432
	ds_read_b128 v[48:51], v25 offset:33536
	ds_read_b128 v[52:55], v25 offset:33552
	ds_read_b128 v[108:111], v25 offset:34048
	ds_read_b128 v[112:115], v25 offset:34064
	v_pk_mul_f32 v[124:125], v[0:1], v[74:75]
	v_pk_fma_f32 v[124:125], v[2:3], v[76:77], v[124:125]
	v_pk_fma_f32 v[124:125], v[4:5], v[78:79], v[124:125]
	v_pk_fma_f32 v[124:125], v[6:7], v[80:81], v[124:125]
	v_pk_mul_f32 v[126:127], v[8:9], v[74:75]
	v_pk_fma_f32 v[126:127], v[10:11], v[76:77], v[126:127]
	v_pk_fma_f32 v[126:127], v[12:13], v[78:79], v[126:127]
	v_pk_fma_f32 v[126:127], v[14:15], v[80:81], v[126:127]
	v_add_f32_e32 v128, v124, v125
	v_add_f32_e32 v130, v126, v127
	v_pk_mul_f32 v[132:133], v[0:1], v[66:67]
	v_pk_mul_f32 v[134:135], v[2:3], v[68:69]
	v_add_f32_dpp v128, v128, v128 quad_perm:[1,0,3,2] row_mask:0xf bank_mask:0xf bound_ctrl:1
	v_add_f32_dpp v130, v130, v130 quad_perm:[1,0,3,2] row_mask:0xf bank_mask:0xf bound_ctrl:1
	v_pk_mul_f32 v[136:137], v[4:5], v[70:71]
	v_pk_mul_f32 v[138:139], v[6:7], v[72:73]
	v_add_f32_dpp v128, v128, v128 quad_perm:[2,3,0,1] row_mask:0xf bank_mask:0xf bound_ctrl:1
	v_add_f32_dpp v130, v130, v130 quad_perm:[2,3,0,1] row_mask:0xf bank_mask:0xf bound_ctrl:1
	v_pk_mul_f32 v[148:149], v[8:9], v[66:67]
	v_pk_mul_f32 v[150:151], v[10:11], v[68:69]
	v_add_f32_dpp v128, v128, v128 row_half_mirror row_mask:0xf bank_mask:0xf bound_ctrl:1
	v_add_f32_dpp v130, v130, v130 row_half_mirror row_mask:0xf bank_mask:0xf bound_ctrl:1
	v_pk_mul_f32 v[152:153], v[12:13], v[70:71]
	v_pk_mul_f32 v[154:155], v[14:15], v[72:73]
	v_pk_fma_f32 v[132:133], v[98:99], v[90:91], v[132:133] op_sel_hi:[0,1,1]
	v_pk_fma_f32 v[134:135], v[98:99], v[92:93], v[134:135] op_sel_hi:[0,1,1]
	v_pk_fma_f32 v[136:137], v[98:99], v[94:95], v[136:137] op_sel_hi:[0,1,1]
	v_pk_fma_f32 v[138:139], v[98:99], v[96:97], v[138:139] op_sel_hi:[0,1,1]
	v_pk_fma_f32 v[148:149], v[98:99], v[90:91], v[148:149] op_sel:[1,0,0] op_sel_hi:[1,1,1]
	v_pk_fma_f32 v[150:151], v[98:99], v[92:93], v[150:151] op_sel:[1,0,0] op_sel_hi:[1,1,1]
	v_pk_fma_f32 v[152:153], v[98:99], v[94:95], v[152:153] op_sel:[1,0,0] op_sel_hi:[1,1,1]
	v_pk_fma_f32 v[154:155], v[98:99], v[96:97], v[154:155] op_sel:[1,0,0] op_sel_hi:[1,1,1]
	v_pk_mul_f32 v[192:193], v[0:1], v[116:117]
	v_pk_fma_f32 v[192:193], v[2:3], v[118:119], v[192:193]
	v_pk_fma_f32 v[192:193], v[4:5], v[120:121], v[192:193]
	v_pk_fma_f32 v[192:193], v[6:7], v[122:123], v[192:193]
	v_add_f32_e32 v176, v192, v193
	v_pk_mul_f32 v[194:195], v[8:9], v[116:117]
	v_pk_fma_f32 v[194:195], v[10:11], v[118:119], v[194:195]
	v_pk_fma_f32 v[194:195], v[12:13], v[120:121], v[194:195]
	v_pk_fma_f32 v[194:195], v[14:15], v[122:123], v[194:195]
	v_add_f32_e32 v177, v194, v195
	v_pk_fma_f32 v[0:1], v[128:129], v[82:83], v[132:133] op_sel_hi:[0,1,1] neg_lo:[1,0,0] neg_hi:[1,0,0]
	v_pk_fma_f32 v[2:3], v[128:129], v[84:85], v[134:135] op_sel_hi:[0,1,1] neg_lo:[1,0,0] neg_hi:[1,0,0]
	v_pk_fma_f32 v[4:5], v[128:129], v[86:87], v[136:137] op_sel_hi:[0,1,1] neg_lo:[1,0,0] neg_hi:[1,0,0]
	v_pk_fma_f32 v[6:7], v[128:129], v[88:89], v[138:139] op_sel_hi:[0,1,1] neg_lo:[1,0,0] neg_hi:[1,0,0]
	v_pk_fma_f32 v[8:9], v[130:131], v[82:83], v[148:149] op_sel_hi:[0,1,1] neg_lo:[1,0,0] neg_hi:[1,0,0]
	v_pk_fma_f32 v[10:11], v[130:131], v[84:85], v[150:151] op_sel_hi:[0,1,1] neg_lo:[1,0,0] neg_hi:[1,0,0]
	v_pk_fma_f32 v[12:13], v[130:131], v[86:87], v[152:153] op_sel_hi:[0,1,1] neg_lo:[1,0,0] neg_hi:[1,0,0]
	v_pk_fma_f32 v[14:15], v[130:131], v[88:89], v[154:155] op_sel_hi:[0,1,1] neg_lo:[1,0,0] neg_hi:[1,0,0]
	s_waitcnt lgkmcnt(0)
	ds_read_b128 v[74:77], v25 offset:34560
	ds_read_b128 v[78:81], v25 offset:34576
	ds_read_b128 v[66:69], v26 offset:2816
	ds_read_b128 v[70:73], v26 offset:2832
	ds_read_b128 v[90:93], v25 offset:35072
	ds_read_b128 v[94:97], v25 offset:35088
	ds_read_b32 v98, v27 offset:35584
	ds_read_b32 v99, v27 offset:35712
	ds_read_b128 v[82:85], v25 offset:34816
	ds_read_b128 v[86:89], v25 offset:34832
	ds_read_b128 v[116:119], v25 offset:35328
	ds_read_b128 v[120:123], v25 offset:35344
	v_pk_mul_f32 v[124:125], v[0:1], v[40:41]
	v_pk_fma_f32 v[124:125], v[2:3], v[42:43], v[124:125]
	v_pk_fma_f32 v[124:125], v[4:5], v[44:45], v[124:125]
	v_pk_fma_f32 v[124:125], v[6:7], v[46:47], v[124:125]
	v_pk_mul_f32 v[126:127], v[8:9], v[40:41]
	v_pk_fma_f32 v[126:127], v[10:11], v[42:43], v[126:127]
	v_pk_fma_f32 v[126:127], v[12:13], v[44:45], v[126:127]
	v_pk_fma_f32 v[126:127], v[14:15], v[46:47], v[126:127]
	v_add_f32_e32 v128, v124, v125
	v_add_f32_e32 v130, v126, v127
	v_pk_mul_f32 v[132:133], v[0:1], v[32:33]
	v_pk_mul_f32 v[134:135], v[2:3], v[34:35]
	v_add_f32_dpp v128, v128, v128 quad_perm:[1,0,3,2] row_mask:0xf bank_mask:0xf bound_ctrl:1
	v_add_f32_dpp v130, v130, v130 quad_perm:[1,0,3,2] row_mask:0xf bank_mask:0xf bound_ctrl:1
	v_pk_mul_f32 v[136:137], v[4:5], v[36:37]
	v_pk_mul_f32 v[138:139], v[6:7], v[38:39]
	v_add_f32_dpp v128, v128, v128 quad_perm:[2,3,0,1] row_mask:0xf bank_mask:0xf bound_ctrl:1
	v_add_f32_dpp v130, v130, v130 quad_perm:[2,3,0,1] row_mask:0xf bank_mask:0xf bound_ctrl:1
	v_pk_mul_f32 v[148:149], v[8:9], v[32:33]
	v_pk_mul_f32 v[150:151], v[10:11], v[34:35]
	v_add_f32_dpp v128, v128, v128 row_half_mirror row_mask:0xf bank_mask:0xf bound_ctrl:1
	v_add_f32_dpp v130, v130, v130 row_half_mirror row_mask:0xf bank_mask:0xf bound_ctrl:1
; __device__ __forceinline__ float red8_sum(float x) { x += dpp_f<0xB1>(x); x += dpp_f<0x4E>(x); x += dpp_f<0x141>(x); return x; }
; template <int RG, int NSW>
; __device__ __forceinline__ void scan_waves(const Params& p, float* lds, const int T, const int dir, const int wave, const int lane,
;                                            const size_t tok0, const int head, const int row_base) {
;     ...
;       LOADSTEP(0, 0);
; #pragma unroll
;       for (int st = 0; st < 16; ++st) {
;         const int B = st & 1;
;         if (st + 1 < 16) LOADSTEP(1 - B, st + 1);
;         asm volatile("" ::: "memory");
;         float sa[RG], o[RG];
; #pragma unroll
;         for (int g = 0; g < RG; ++g) {
;           f32x2_t a0 = S[g][0] * kk[B][0], a1 = S[g][1] * kk[B][1];
;           a0 = __builtin_elementwise_fma(S[g][2], kk[B][2], a0); a1 = __builtin_elementwise_fma(S[g][3], kk[B][3], a1);
;           a0 = a0 + a1; sa[g] = a0.x + a0.y;
;         }
; #pragma unroll
;         for (int g = 0; g < RG; ++g) sa[g] = -red8_sum(sa[g]);
; #pragma unroll
;         for (int g = 0; g < RG; ++g) {
;           const f32x2_t sav = {sa[g], sa[g]}, vvv = {vv[B][g], vv[B][g]};
; #pragma unroll
;           for (int k = 0; k < 4; ++k)
;             S[g][k] = __builtin_elementwise_fma(vvv, kd[B][k], __builtin_elementwise_fma(sav, qa[B][k], S[g][k] * w[B][k]));
;         }
; #pragma unroll
;         for (int g = 0; g < RG; ++g) {
;           f32x2_t a0 = S[g][0] * r[B][0], a1 = S[g][1] * r[B][1];
;           a0 = __builtin_elementwise_fma(S[g][2], r[B][2], a0); a1 = __builtin_elementwise_fma(S[g][3], r[B][3], a1);
;           a0 = a0 + a1; o[g] = a0.x + a0.y;
;         }
; #pragma unroll
;         for (int g = 0; g < RG; ++g) o[g] = red8_sum(o[g]);
;         float os = o[0];
; #pragma unroll
;         for (int g = 1; g < RG; ++g) os = (part == g) ? o[g] : os;
;         osv[st] = os;
;       }
	v_pk_mul_f32 v[152:153], v[12:13], v[36:37]
	v_pk_mul_f32 v[154:155], v[14:15], v[38:39]
	v_pk_fma_f32 v[132:133], v[64:65], v[56:57], v[132:133] op_sel_hi:[0,1,1]
	v_pk_fma_f32 v[134:135], v[64:65], v[58:59], v[134:135] op_sel_hi:[0,1,1]
	v_pk_fma_f32 v[136:137], v[64:65], v[60:61], v[136:137] op_sel_hi:[0,1,1]
	v_pk_fma_f32 v[138:139], v[64:65], v[62:63], v[138:139] op_sel_hi:[0,1,1]
	v_pk_fma_f32 v[148:149], v[64:65], v[56:57], v[148:149] op_sel:[1,0,0] op_sel_hi:[1,1,1]
	v_pk_fma_f32 v[150:151], v[64:65], v[58:59], v[150:151] op_sel:[1,0,0] op_sel_hi:[1,1,1]
	v_pk_fma_f32 v[152:153], v[64:65], v[60:61], v[152:153] op_sel:[1,0,0] op_sel_hi:[1,1,1]
	v_pk_fma_f32 v[154:155], v[64:65], v[62:63], v[154:155] op_sel:[1,0,0] op_sel_hi:[1,1,1]
	v_pk_mul_f32 v[192:193], v[0:1], v[100:101]
	v_pk_fma_f32 v[192:193], v[2:3], v[102:103], v[192:193]
	v_pk_fma_f32 v[192:193], v[4:5], v[104:105], v[192:193]
	v_pk_fma_f32 v[192:193], v[6:7], v[106:107], v[192:193]
	v_add_f32_e32 v178, v192, v193
	v_pk_mul_f32 v[194:195], v[8:9], v[100:101]
	v_pk_fma_f32 v[194:195], v[10:11], v[102:103], v[194:195]
	v_pk_fma_f32 v[194:195], v[12:13], v[104:105], v[194:195]
	v_pk_fma_f32 v[194:195], v[14:15], v[106:107], v[194:195]
	v_add_f32_e32 v179, v194, v195
	v_pk_fma_f32 v[0:1], v[128:129], v[48:49], v[132:133] op_sel_hi:[0,1,1] neg_lo:[1,0,0] neg_hi:[1,0,0]
	v_pk_fma_f32 v[2:3], v[128:129], v[50:51], v[134:135] op_sel_hi:[0,1,1] neg_lo:[1,0,0] neg_hi:[1,0,0]
	v_pk_fma_f32 v[4:5], v[128:129], v[52:53], v[136:137] op_sel_hi:[0,1,1] neg_lo:[1,0,0] neg_hi:[1,0,0]
	v_pk_fma_f32 v[6:7], v[128:129], v[54:55], v[138:139] op_sel_hi:[0,1,1] neg_lo:[1,0,0] neg_hi:[1,0,0]
	v_pk_fma_f32 v[8:9], v[130:131], v[48:49], v[148:149] op_sel_hi:[0,1,1] neg_lo:[1,0,0] neg_hi:[1,0,0]
	v_pk_fma_f32 v[10:11], v[130:131], v[50:51], v[150:151] op_sel_hi:[0,1,1] neg_lo:[1,0,0] neg_hi:[1,0,0]
	v_pk_fma_f32 v[12:13], v[130:131], v[52:53], v[152:153] op_sel_hi:[0,1,1] neg_lo:[1,0,0] neg_hi:[1,0,0]
	v_pk_fma_f32 v[14:15], v[130:131], v[54:55], v[154:155] op_sel_hi:[0,1,1] neg_lo:[1,0,0] neg_hi:[1,0,0]
	s_waitcnt lgkmcnt(0)
	ds_read_b128 v[40:43], v25 offset:35840
	ds_read_b128 v[44:47], v25 offset:35856
	ds_read_b128 v[32:35], v26 offset:3072
	ds_read_b128 v[36:39], v26 offset:3088
	ds_read_b128 v[56:59], v25 offset:36352
	ds_read_b128 v[60:63], v25 offset:36368
	ds_read_b32 v64, v27 offset:36864
	ds_read_b32 v65, v27 offset:36992
	ds_read_b128 v[48:51], v25 offset:36096
	ds_read_b128 v[52:55], v25 offset:36112
	ds_read_b128 v[100:103], v25 offset:36608
	ds_read_b128 v[104:107], v25 offset:36624
	v_pk_mul_f32 v[124:125], v[0:1], v[74:75]
	v_pk_fma_f32 v[124:125], v[2:3], v[76:77], v[124:125]
	v_pk_fma_f32 v[124:125], v[4:5], v[78:79], v[124:125]
	v_pk_fma_f32 v[124:125], v[6:7], v[80:81], v[124:125]
	v_pk_mul_f32 v[126:127], v[8:9], v[74:75]
	v_pk_fma_f32 v[126:127], v[10:11], v[76:77], v[126:127]
	v_pk_fma_f32 v[126:127], v[12:13], v[78:79], v[126:127]
	v_pk_fma_f32 v[126:127], v[14:15], v[80:81], v[126:127]
	v_add_f32_e32 v128, v124, v125
	v_add_f32_e32 v130, v126, v127
	v_pk_mul_f32 v[132:133], v[0:1], v[66:67]
	v_pk_mul_f32 v[134:135], v[2:3], v[68:69]
	v_add_f32_dpp v128, v128, v128 quad_perm:[1,0,3,2] row_mask:0xf bank_mask:0xf bound_ctrl:1
	v_add_f32_dpp v130, v130, v130 quad_perm:[1,0,3,2] row_mask:0xf bank_mask:0xf bound_ctrl:1
	v_pk_mul_f32 v[136:137], v[4:5], v[70:71]
	v_pk_mul_f32 v[138:139], v[6:7], v[72:73]
	v_add_f32_dpp v128, v128, v128 quad_perm:[2,3,0,1] row_mask:0xf bank_mask:0xf bound_ctrl:1
	v_add_f32_dpp v130, v130, v130 quad_perm:[2,3,0,1] row_mask:0xf bank_mask:0xf bound_ctrl:1
	v_pk_mul_f32 v[148:149], v[8:9], v[66:67]
	v_pk_mul_f32 v[150:151], v[10:11], v[68:69]
	v_add_f32_dpp v128, v128, v128 row_half_mirror row_mask:0xf bank_mask:0xf bound_ctrl:1
	v_add_f32_dpp v130, v130, v130 row_half_mirror row_mask:0xf bank_mask:0xf bound_ctrl:1
	v_pk_mul_f32 v[152:153], v[12:13], v[70:71]
	v_pk_mul_f32 v[154:155], v[14:15], v[72:73]
	v_pk_fma_f32 v[132:133], v[98:99], v[90:91], v[132:133] op_sel_hi:[0,1,1]
	v_pk_fma_f32 v[134:135], v[98:99], v[92:93], v[134:135] op_sel_hi:[0,1,1]
	v_pk_fma_f32 v[136:137], v[98:99], v[94:95], v[136:137] op_sel_hi:[0,1,1]
	v_pk_fma_f32 v[138:139], v[98:99], v[96:97], v[138:139] op_sel_hi:[0,1,1]
	v_pk_fma_f32 v[148:149], v[98:99], v[90:91], v[148:149] op_sel:[1,0,0] op_sel_hi:[1,1,1]
	v_pk_fma_f32 v[150:151], v[98:99], v[92:93], v[150:151] op_sel:[1,0,0] op_sel_hi:[1,1,1]
	v_pk_fma_f32 v[152:153], v[98:99], v[94:95], v[152:153] op_sel:[1,0,0] op_sel_hi:[1,1,1]
	v_pk_fma_f32 v[154:155], v[98:99], v[96:97], v[154:155] op_sel:[1,0,0] op_sel_hi:[1,1,1]
	v_pk_mul_f32 v[192:193], v[0:1], v[108:109]
	v_pk_fma_f32 v[192:193], v[2:3], v[110:111], v[192:193]
	v_pk_fma_f32 v[192:193], v[4:5], v[112:113], v[192:193]
	v_pk_fma_f32 v[192:193], v[6:7], v[114:115], v[192:193]
	v_add_f32_e32 v180, v192, v193
	v_pk_mul_f32 v[194:195], v[8:9], v[108:109]
	v_pk_fma_f32 v[194:195], v[10:11], v[110:111], v[194:195]
	v_pk_fma_f32 v[194:195], v[12:13], v[112:113], v[194:195]
	v_pk_fma_f32 v[194:195], v[14:15], v[114:115], v[194:195]
	v_add_f32_e32 v181, v194, v195
	v_pk_fma_f32 v[0:1], v[128:129], v[82:83], v[132:133] op_sel_hi:[0,1,1] neg_lo:[1,0,0] neg_hi:[1,0,0]
	v_pk_fma_f32 v[2:3], v[128:129], v[84:85], v[134:135] op_sel_hi:[0,1,1] neg_lo:[1,0,0] neg_hi:[1,0,0]
	v_pk_fma_f32 v[4:5], v[128:129], v[86:87], v[136:137] op_sel_hi:[0,1,1] neg_lo:[1,0,0] neg_hi:[1,0,0]
	v_pk_fma_f32 v[6:7], v[128:129], v[88:89], v[138:139] op_sel_hi:[0,1,1] neg_lo:[1,0,0] neg_hi:[1,0,0]
	v_pk_fma_f32 v[8:9], v[130:131], v[82:83], v[148:149] op_sel_hi:[0,1,1] neg_lo:[1,0,0] neg_hi:[1,0,0]
	v_pk_fma_f32 v[10:11], v[130:131], v[84:85], v[150:151] op_sel_hi:[0,1,1] neg_lo:[1,0,0] neg_hi:[1,0,0]
	v_pk_fma_f32 v[12:13], v[130:131], v[86:87], v[152:153] op_sel_hi:[0,1,1] neg_lo:[1,0,0] neg_hi:[1,0,0]
	v_pk_fma_f32 v[14:15], v[130:131], v[88:89], v[154:155] op_sel_hi:[0,1,1] neg_lo:[1,0,0] neg_hi:[1,0,0]
	s_waitcnt lgkmcnt(0)
; __device__ __forceinline__ float red8_sum(float x) { x += dpp_f<0xB1>(x); x += dpp_f<0x4E>(x); x += dpp_f<0x141>(x); return x; }
; template <int RG, int NSW>
; __device__ __forceinline__ void scan_waves(const Params& p, float* lds, const int T, const int dir, const int wave, const int lane,
;                                            const size_t tok0, const int head, const int row_base) {
;     ...
;       LOADSTEP(0, 0);
; #pragma unroll
;       for (int st = 0; st < 16; ++st) {
;         const int B = st & 1;
;         if (st + 1 < 16) LOADSTEP(1 - B, st + 1);
;         asm volatile("" ::: "memory");
;         float sa[RG], o[RG];
; #pragma unroll
;         for (int g = 0; g < RG; ++g) {
;           f32x2_t a0 = S[g][0] * kk[B][0], a1 = S[g][1] * kk[B][1];
;           a0 = __builtin_elementwise_fma(S[g][2], kk[B][2], a0); a1 = __builtin_elementwise_fma(S[g][3], kk[B][3], a1);
;           a0 = a0 + a1; sa[g] = a0.x + a0.y;
;         }
; #pragma unroll
;         for (int g = 0; g < RG; ++g) sa[g] = -red8_sum(sa[g]);
; #pragma unroll
;         for (int g = 0; g < RG; ++g) {
;           const f32x2_t sav = {sa[g], sa[g]}, vvv = {vv[B][g], vv[B][g]};
; #pragma unroll
;           for (int k = 0; k < 4; ++k)
;             S[g][k] = __builtin_elementwise_fma(vvv, kd[B][k], __builtin_elementwise_fma(sav, qa[B][k], S[g][k] * w[B][k]));
;         }
; #pragma unroll
;         for (int g = 0; g < RG; ++g) {
;           f32x2_t a0 = S[g][0] * r[B][0], a1 = S[g][1] * r[B][1];
;           a0 = __builtin_elementwise_fma(S[g][2], r[B][2], a0); a1 = __builtin_elementwise_fma(S[g][3], r[B][3], a1);
;           a0 = a0 + a1; o[g] = a0.x + a0.y;
;         }
; #pragma unroll
;         for (int g = 0; g < RG; ++g) o[g] = red8_sum(o[g]);
;         float os = o[0];
; #pragma unroll
;         for (int g = 1; g < RG; ++g) os = (part == g) ? o[g] : os;
;         osv[st] = os;
;       }
	ds_read_b128 v[74:77], v25 offset:37120
	ds_read_b128 v[78:81], v25 offset:37136
	ds_read_b128 v[66:69], v26 offset:3328
	ds_read_b128 v[70:73], v26 offset:3344
	ds_read_b128 v[90:93], v25 offset:37632
	ds_read_b128 v[94:97], v25 offset:37648
	ds_read_b32 v98, v27 offset:38144
	ds_read_b32 v99, v27 offset:38272
	ds_read_b128 v[82:85], v25 offset:37376
	ds_read_b128 v[86:89], v25 offset:37392
	ds_read_b128 v[108:111], v25 offset:37888
	ds_read_b128 v[112:115], v25 offset:37904
	v_pk_mul_f32 v[124:125], v[0:1], v[40:41]
	v_pk_fma_f32 v[124:125], v[2:3], v[42:43], v[124:125]
	v_pk_fma_f32 v[124:125], v[4:5], v[44:45], v[124:125]
	v_pk_fma_f32 v[124:125], v[6:7], v[46:47], v[124:125]
	v_pk_mul_f32 v[126:127], v[8:9], v[40:41]
	v_pk_fma_f32 v[126:127], v[10:11], v[42:43], v[126:127]
	v_pk_fma_f32 v[126:127], v[12:13], v[44:45], v[126:127]
	v_pk_fma_f32 v[126:127], v[14:15], v[46:47], v[126:127]
	v_add_f32_e32 v128, v124, v125
	v_add_f32_e32 v130, v126, v127
	v_pk_mul_f32 v[132:133], v[0:1], v[32:33]
	v_pk_mul_f32 v[134:135], v[2:3], v[34:35]
	v_add_f32_dpp v128, v128, v128 quad_perm:[1,0,3,2] row_mask:0xf bank_mask:0xf bound_ctrl:1
	v_add_f32_dpp v130, v130, v130 quad_perm:[1,0,3,2] row_mask:0xf bank_mask:0xf bound_ctrl:1
	v_pk_mul_f32 v[136:137], v[4:5], v[36:37]
	v_pk_mul_f32 v[138:139], v[6:7], v[38:39]
	v_add_f32_dpp v128, v128, v128 quad_perm:[2,3,0,1] row_mask:0xf bank_mask:0xf bound_ctrl:1
	v_add_f32_dpp v130, v130, v130 quad_perm:[2,3,0,1] row_mask:0xf bank_mask:0xf bound_ctrl:1
	v_pk_mul_f32 v[148:149], v[8:9], v[32:33]
	v_pk_mul_f32 v[150:151], v[10:11], v[34:35]
	v_add_f32_dpp v128, v128, v128 row_half_mirror row_mask:0xf bank_mask:0xf bound_ctrl:1
	v_add_f32_dpp v130, v130, v130 row_half_mirror row_mask:0xf bank_mask:0xf bound_ctrl:1
	v_pk_mul_f32 v[152:153], v[12:13], v[36:37]
	v_pk_mul_f32 v[154:155], v[14:15], v[38:39]
	v_pk_fma_f32 v[132:133], v[64:65], v[56:57], v[132:133] op_sel_hi:[0,1,1]
	v_pk_fma_f32 v[134:135], v[64:65], v[58:59], v[134:135] op_sel_hi:[0,1,1]
	v_pk_fma_f32 v[136:137], v[64:65], v[60:61], v[136:137] op_sel_hi:[0,1,1]
	v_pk_fma_f32 v[138:139], v[64:65], v[62:63], v[138:139] op_sel_hi:[0,1,1]
	v_pk_fma_f32 v[148:149], v[64:65], v[56:57], v[148:149] op_sel:[1,0,0] op_sel_hi:[1,1,1]
	v_pk_fma_f32 v[150:151], v[64:65], v[58:59], v[150:151] op_sel:[1,0,0] op_sel_hi:[1,1,1]
	v_pk_fma_f32 v[152:153], v[64:65], v[60:61], v[152:153] op_sel:[1,0,0] op_sel_hi:[1,1,1]
	v_pk_fma_f32 v[154:155], v[64:65], v[62:63], v[154:155] op_sel:[1,0,0] op_sel_hi:[1,1,1]
	v_pk_mul_f32 v[192:193], v[0:1], v[116:117]
	v_pk_fma_f32 v[192:193], v[2:3], v[118:119], v[192:193]
	v_pk_fma_f32 v[192:193], v[4:5], v[120:121], v[192:193]
	v_pk_fma_f32 v[192:193], v[6:7], v[122:123], v[192:193]
	v_add_f32_e32 v182, v192, v193
	v_pk_mul_f32 v[194:195], v[8:9], v[116:117]
	v_pk_fma_f32 v[194:195], v[10:11], v[118:119], v[194:195]
	v_pk_fma_f32 v[194:195], v[12:13], v[120:121], v[194:195]
	v_pk_fma_f32 v[194:195], v[14:15], v[122:123], v[194:195]
	v_add_f32_e32 v183, v194, v195
	v_pk_fma_f32 v[0:1], v[128:129], v[48:49], v[132:133] op_sel_hi:[0,1,1] neg_lo:[1,0,0] neg_hi:[1,0,0]
	v_pk_fma_f32 v[2:3], v[128:129], v[50:51], v[134:135] op_sel_hi:[0,1,1] neg_lo:[1,0,0] neg_hi:[1,0,0]
	v_pk_fma_f32 v[4:5], v[128:129], v[52:53], v[136:137] op_sel_hi:[0,1,1] neg_lo:[1,0,0] neg_hi:[1,0,0]
	v_pk_fma_f32 v[6:7], v[128:129], v[54:55], v[138:139] op_sel_hi:[0,1,1] neg_lo:[1,0,0] neg_hi:[1,0,0]
	v_pk_fma_f32 v[8:9], v[130:131], v[48:49], v[148:149] op_sel_hi:[0,1,1] neg_lo:[1,0,0] neg_hi:[1,0,0]
	v_pk_fma_f32 v[10:11], v[130:131], v[50:51], v[150:151] op_sel_hi:[0,1,1] neg_lo:[1,0,0] neg_hi:[1,0,0]
	v_pk_fma_f32 v[12:13], v[130:131], v[52:53], v[152:153] op_sel_hi:[0,1,1] neg_lo:[1,0,0] neg_hi:[1,0,0]
	v_pk_fma_f32 v[14:15], v[130:131], v[54:55], v[154:155] op_sel_hi:[0,1,1] neg_lo:[1,0,0] neg_hi:[1,0,0]
	s_waitcnt lgkmcnt(0)
	ds_read_b128 v[40:43], v25 offset:38400
	ds_read_b128 v[44:47], v25 offset:38416
	ds_read_b128 v[32:35], v26 offset:3584
	ds_read_b128 v[36:39], v26 offset:3600
	ds_read_b128 v[56:59], v25 offset:38912
	ds_read_b128 v[60:63], v25 offset:38928
	ds_read_b32 v64, v27 offset:39424
	ds_read_b32 v65, v27 offset:39552
	ds_read_b128 v[48:51], v25 offset:38656
	ds_read_b128 v[52:55], v25 offset:38672
	ds_read_b128 v[116:119], v25 offset:39168
	ds_read_b128 v[120:123], v25 offset:39184
	v_pk_mul_f32 v[124:125], v[0:1], v[74:75]
	v_pk_fma_f32 v[124:125], v[2:3], v[76:77], v[124:125]
	v_pk_fma_f32 v[124:125], v[4:5], v[78:79], v[124:125]
	v_pk_fma_f32 v[124:125], v[6:7], v[80:81], v[124:125]
	v_pk_mul_f32 v[126:127], v[8:9], v[74:75]
	v_pk_fma_f32 v[126:127], v[10:11], v[76:77], v[126:127]
	v_pk_fma_f32 v[126:127], v[12:13], v[78:79], v[126:127]
	v_pk_fma_f32 v[126:127], v[14:15], v[80:81], v[126:127]
	v_add_f32_e32 v128, v124, v125
	v_add_f32_e32 v130, v126, v127
	v_pk_mul_f32 v[132:133], v[0:1], v[66:67]
	v_pk_mul_f32 v[134:135], v[2:3], v[68:69]
	v_add_f32_dpp v128, v128, v128 quad_perm:[1,0,3,2] row_mask:0xf bank_mask:0xf bound_ctrl:1
	v_add_f32_dpp v130, v130, v130 quad_perm:[1,0,3,2] row_mask:0xf bank_mask:0xf bound_ctrl:1
	v_pk_mul_f32 v[136:137], v[4:5], v[70:71]
	v_pk_mul_f32 v[138:139], v[6:7], v[72:73]
	v_add_f32_dpp v128, v128, v128 quad_perm:[2,3,0,1] row_mask:0xf bank_mask:0xf bound_ctrl:1
	v_add_f32_dpp v130, v130, v130 quad_perm:[2,3,0,1] row_mask:0xf bank_mask:0xf bound_ctrl:1
	v_pk_mul_f32 v[148:149], v[8:9], v[66:67]
	v_pk_mul_f32 v[150:151], v[10:11], v[68:69]
	v_add_f32_dpp v128, v128, v128 row_half_mirror row_mask:0xf bank_mask:0xf bound_ctrl:1
	v_add_f32_dpp v130, v130, v130 row_half_mirror row_mask:0xf bank_mask:0xf bound_ctrl:1
; __device__ __forceinline__ float red8_sum(float x) { x += dpp_f<0xB1>(x); x += dpp_f<0x4E>(x); x += dpp_f<0x141>(x); return x; }
; template <int RG, int NSW>
; __device__ __forceinline__ void scan_waves(const Params& p, float* lds, const int T, const int dir, const int wave, const int lane,
;                                            const size_t tok0, const int head, const int row_base) {
;     ...
;       for (int st = 0; st < 16; ++st) {
;         const int B = st & 1;
;         if (st + 1 < 16) LOADSTEP(1 - B, st + 1);
;         asm volatile("" ::: "memory");
;         float sa[RG], o[RG];
; #pragma unroll
;         for (int g = 0; g < RG; ++g) {
;           f32x2_t a0 = S[g][0] * kk[B][0], a1 = S[g][1] * kk[B][1];
;           a0 = __builtin_elementwise_fma(S[g][2], kk[B][2], a0); a1 = __builtin_elementwise_fma(S[g][3], kk[B][3], a1);
;           a0 = a0 + a1; sa[g] = a0.x + a0.y;
;         }
; #pragma unroll
;         for (int g = 0; g < RG; ++g) sa[g] = -red8_sum(sa[g]);
; #pragma unroll
;         for (int g = 0; g < RG; ++g) {
;           const f32x2_t sav = {sa[g], sa[g]}, vvv = {vv[B][g], vv[B][g]};
; #pragma unroll
;           for (int k = 0; k < 4; ++k)
;             S[g][k] = __builtin_elementwise_fma(vvv, kd[B][k], __builtin_elementwise_fma(sav, qa[B][k], S[g][k] * w[B][k]));
;         }
; #pragma unroll
;         for (int g = 0; g < RG; ++g) {
;           f32x2_t a0 = S[g][0] * r[B][0], a1 = S[g][1] * r[B][1];
;           a0 = __builtin_elementwise_fma(S[g][2], r[B][2], a0); a1 = __builtin_elementwise_fma(S[g][3], r[B][3], a1);
;           a0 = a0 + a1; o[g] = a0.x + a0.y;
;         }
; #pragma unroll
;         for (int g = 0; g < RG; ++g) o[g] = red8_sum(o[g]);
;         float os = o[0];
; #pragma unroll
;         for (int g = 1; g < RG; ++g) os = (part == g) ? o[g] : os;
;         osv[st] = os;
;       }
	v_pk_mul_f32 v[152:153], v[12:13], v[70:71]
	v_pk_mul_f32 v[154:155], v[14:15], v[72:73]
	v_pk_fma_f32 v[132:133], v[98:99], v[90:91], v[132:133] op_sel_hi:[0,1,1]
	v_pk_fma_f32 v[134:135], v[98:99], v[92:93], v[134:135] op_sel_hi:[0,1,1]
	v_pk_fma_f32 v[136:137], v[98:99], v[94:95], v[136:137] op_sel_hi:[0,1,1]
	v_pk_fma_f32 v[138:139], v[98:99], v[96:97], v[138:139] op_sel_hi:[0,1,1]
	v_pk_fma_f32 v[148:149], v[98:99], v[90:91], v[148:149] op_sel:[1,0,0] op_sel_hi:[1,1,1]
	v_pk_fma_f32 v[150:151], v[98:99], v[92:93], v[150:151] op_sel:[1,0,0] op_sel_hi:[1,1,1]
	v_pk_fma_f32 v[152:153], v[98:99], v[94:95], v[152:153] op_sel:[1,0,0] op_sel_hi:[1,1,1]
	v_pk_fma_f32 v[154:155], v[98:99], v[96:97], v[154:155] op_sel:[1,0,0] op_sel_hi:[1,1,1]
	v_pk_mul_f32 v[192:193], v[0:1], v[100:101]
	v_pk_fma_f32 v[192:193], v[2:3], v[102:103], v[192:193]
	v_pk_fma_f32 v[192:193], v[4:5], v[104:105], v[192:193]
	v_pk_fma_f32 v[192:193], v[6:7], v[106:107], v[192:193]
	v_add_f32_e32 v184, v192, v193
	v_pk_mul_f32 v[194:195], v[8:9], v[100:101]
	v_pk_fma_f32 v[194:195], v[10:11], v[102:103], v[194:195]
	v_pk_fma_f32 v[194:195], v[12:13], v[104:105], v[194:195]
	v_pk_fma_f32 v[194:195], v[14:15], v[106:107], v[194:195]
	v_add_f32_e32 v185, v194, v195
	v_pk_fma_f32 v[0:1], v[128:129], v[82:83], v[132:133] op_sel_hi:[0,1,1] neg_lo:[1,0,0] neg_hi:[1,0,0]
	v_pk_fma_f32 v[2:3], v[128:129], v[84:85], v[134:135] op_sel_hi:[0,1,1] neg_lo:[1,0,0] neg_hi:[1,0,0]
	v_pk_fma_f32 v[4:5], v[128:129], v[86:87], v[136:137] op_sel_hi:[0,1,1] neg_lo:[1,0,0] neg_hi:[1,0,0]
	v_pk_fma_f32 v[6:7], v[128:129], v[88:89], v[138:139] op_sel_hi:[0,1,1] neg_lo:[1,0,0] neg_hi:[1,0,0]
	v_pk_fma_f32 v[8:9], v[130:131], v[82:83], v[148:149] op_sel_hi:[0,1,1] neg_lo:[1,0,0] neg_hi:[1,0,0]
	v_pk_fma_f32 v[10:11], v[130:131], v[84:85], v[150:151] op_sel_hi:[0,1,1] neg_lo:[1,0,0] neg_hi:[1,0,0]
	v_pk_fma_f32 v[12:13], v[130:131], v[86:87], v[152:153] op_sel_hi:[0,1,1] neg_lo:[1,0,0] neg_hi:[1,0,0]
	v_pk_fma_f32 v[14:15], v[130:131], v[88:89], v[154:155] op_sel_hi:[0,1,1] neg_lo:[1,0,0] neg_hi:[1,0,0]
	s_waitcnt lgkmcnt(0)
	ds_read_b128 v[74:77], v25 offset:39680
	ds_read_b128 v[78:81], v25 offset:39696
	ds_read_b128 v[66:69], v26 offset:3840
	ds_read_b128 v[70:73], v26 offset:3856
	ds_read_b128 v[90:93], v25 offset:40192
	ds_read_b128 v[94:97], v25 offset:40208
	ds_read_b32 v98, v27 offset:40704
	ds_read_b32 v99, v27 offset:40832
	ds_read_b128 v[82:85], v25 offset:39936
	ds_read_b128 v[86:89], v25 offset:39952
	ds_read_b128 v[100:103], v25 offset:40448
	ds_read_b128 v[104:107], v25 offset:40464
	v_pk_mul_f32 v[124:125], v[0:1], v[40:41]
	v_pk_fma_f32 v[124:125], v[2:3], v[42:43], v[124:125]
	v_pk_fma_f32 v[124:125], v[4:5], v[44:45], v[124:125]
	v_pk_fma_f32 v[124:125], v[6:7], v[46:47], v[124:125]
	v_pk_mul_f32 v[126:127], v[8:9], v[40:41]
	v_pk_fma_f32 v[126:127], v[10:11], v[42:43], v[126:127]
	v_pk_fma_f32 v[126:127], v[12:13], v[44:45], v[126:127]
	v_pk_fma_f32 v[126:127], v[14:15], v[46:47], v[126:127]
	v_add_f32_e32 v128, v124, v125
	v_add_f32_e32 v130, v126, v127
	v_pk_mul_f32 v[132:133], v[0:1], v[32:33]
	v_pk_mul_f32 v[134:135], v[2:3], v[34:35]
	v_add_f32_dpp v128, v128, v128 quad_perm:[1,0,3,2] row_mask:0xf bank_mask:0xf bound_ctrl:1
	v_add_f32_dpp v130, v130, v130 quad_perm:[1,0,3,2] row_mask:0xf bank_mask:0xf bound_ctrl:1
	v_pk_mul_f32 v[136:137], v[4:5], v[36:37]
	v_pk_mul_f32 v[138:139], v[6:7], v[38:39]
	v_add_f32_dpp v128, v128, v128 quad_perm:[2,3,0,1] row_mask:0xf bank_mask:0xf bound_ctrl:1
	v_add_f32_dpp v130, v130, v130 quad_perm:[2,3,0,1] row_mask:0xf bank_mask:0xf bound_ctrl:1
	v_pk_mul_f32 v[148:149], v[8:9], v[32:33]
	v_pk_mul_f32 v[150:151], v[10:11], v[34:35]
	v_add_f32_dpp v128, v128, v128 row_half_mirror row_mask:0xf bank_mask:0xf bound_ctrl:1
	v_add_f32_dpp v130, v130, v130 row_half_mirror row_mask:0xf bank_mask:0xf bound_ctrl:1
	v_pk_mul_f32 v[152:153], v[12:13], v[36:37]
	v_pk_mul_f32 v[154:155], v[14:15], v[38:39]
	v_pk_fma_f32 v[132:133], v[64:65], v[56:57], v[132:133] op_sel_hi:[0,1,1]
	v_pk_fma_f32 v[134:135], v[64:65], v[58:59], v[134:135] op_sel_hi:[0,1,1]
	v_pk_fma_f32 v[136:137], v[64:65], v[60:61], v[136:137] op_sel_hi:[0,1,1]
	v_pk_fma_f32 v[138:139], v[64:65], v[62:63], v[138:139] op_sel_hi:[0,1,1]
	v_pk_fma_f32 v[148:149], v[64:65], v[56:57], v[148:149] op_sel:[1,0,0] op_sel_hi:[1,1,1]
	v_pk_fma_f32 v[150:151], v[64:65], v[58:59], v[150:151] op_sel:[1,0,0] op_sel_hi:[1,1,1]
	v_pk_fma_f32 v[152:153], v[64:65], v[60:61], v[152:153] op_sel:[1,0,0] op_sel_hi:[1,1,1]
	v_pk_fma_f32 v[154:155], v[64:65], v[62:63], v[154:155] op_sel:[1,0,0] op_sel_hi:[1,1,1]
	v_pk_mul_f32 v[192:193], v[0:1], v[108:109]
	v_pk_fma_f32 v[192:193], v[2:3], v[110:111], v[192:193]
	v_pk_fma_f32 v[192:193], v[4:5], v[112:113], v[192:193]
	v_pk_fma_f32 v[192:193], v[6:7], v[114:115], v[192:193]
	v_add_f32_e32 v186, v192, v193
	v_pk_mul_f32 v[194:195], v[8:9], v[108:109]
	v_pk_fma_f32 v[194:195], v[10:11], v[110:111], v[194:195]
	v_pk_fma_f32 v[194:195], v[12:13], v[112:113], v[194:195]
	v_pk_fma_f32 v[194:195], v[14:15], v[114:115], v[194:195]
	v_add_f32_e32 v187, v194, v195
	v_pk_fma_f32 v[0:1], v[128:129], v[48:49], v[132:133] op_sel_hi:[0,1,1] neg_lo:[1,0,0] neg_hi:[1,0,0]
	v_pk_fma_f32 v[2:3], v[128:129], v[50:51], v[134:135] op_sel_hi:[0,1,1] neg_lo:[1,0,0] neg_hi:[1,0,0]
	v_pk_fma_f32 v[4:5], v[128:129], v[52:53], v[136:137] op_sel_hi:[0,1,1] neg_lo:[1,0,0] neg_hi:[1,0,0]
	v_pk_fma_f32 v[6:7], v[128:129], v[54:55], v[138:139] op_sel_hi:[0,1,1] neg_lo:[1,0,0] neg_hi:[1,0,0]
	v_pk_fma_f32 v[8:9], v[130:131], v[48:49], v[148:149] op_sel_hi:[0,1,1] neg_lo:[1,0,0] neg_hi:[1,0,0]
	v_pk_fma_f32 v[10:11], v[130:131], v[50:51], v[150:151] op_sel_hi:[0,1,1] neg_lo:[1,0,0] neg_hi:[1,0,0]
	v_pk_fma_f32 v[12:13], v[130:131], v[52:53], v[152:153] op_sel_hi:[0,1,1] neg_lo:[1,0,0] neg_hi:[1,0,0]
	v_pk_fma_f32 v[14:15], v[130:131], v[54:55], v[154:155] op_sel_hi:[0,1,1] neg_lo:[1,0,0] neg_hi:[1,0,0]
	s_waitcnt lgkmcnt(0)
; __device__ __forceinline__ float red8_sum(float x) { x += dpp_f<0xB1>(x); x += dpp_f<0x4E>(x); x += dpp_f<0x141>(x); return x; }
; template <int RG, int NSW>
; __device__ __forceinline__ void scan_waves(const Params& p, float* lds, const int T, const int dir, const int wave, const int lane,
;                                            const size_t tok0, const int head, const int row_base) {
;     ...
; #pragma unroll
;         for (int g = 0; g < RG; ++g) {
;           f32x2_t a0 = S[g][0] * r[B][0], a1 = S[g][1] * r[B][1];
;           a0 = __builtin_elementwise_fma(S[g][2], r[B][2], a0); a1 = __builtin_elementwise_fma(S[g][3], r[B][3], a1);
;           a0 = a0 + a1; o[g] = a0.x + a0.y;
;         }
; #pragma unroll
;         for (int g = 0; g < RG; ++g) o[g] = red8_sum(o[g]);
;         float os = o[0];
; #pragma unroll
;         for (int g = 1; g < RG; ++g) os = (part == g) ? o[g] : os;
;         osv[st] = os;
;       }
	v_pk_mul_f32 v[124:125], v[0:1], v[74:75]
	v_pk_fma_f32 v[124:125], v[2:3], v[76:77], v[124:125]
	v_pk_fma_f32 v[124:125], v[4:5], v[78:79], v[124:125]
	v_pk_fma_f32 v[124:125], v[6:7], v[80:81], v[124:125]
	v_pk_mul_f32 v[126:127], v[8:9], v[74:75]
	v_pk_fma_f32 v[126:127], v[10:11], v[76:77], v[126:127]
	v_pk_fma_f32 v[126:127], v[12:13], v[78:79], v[126:127]
	v_pk_fma_f32 v[126:127], v[14:15], v[80:81], v[126:127]
	v_add_f32_e32 v128, v124, v125
	v_add_f32_e32 v130, v126, v127
	v_pk_mul_f32 v[132:133], v[0:1], v[66:67]
	v_pk_mul_f32 v[134:135], v[2:3], v[68:69]
	v_add_f32_dpp v128, v128, v128 quad_perm:[1,0,3,2] row_mask:0xf bank_mask:0xf bound_ctrl:1
	v_add_f32_dpp v130, v130, v130 quad_perm:[1,0,3,2] row_mask:0xf bank_mask:0xf bound_ctrl:1
	v_pk_mul_f32 v[136:137], v[4:5], v[70:71]
	v_pk_mul_f32 v[138:139], v[6:7], v[72:73]
	v_add_f32_dpp v128, v128, v128 quad_perm:[2,3,0,1] row_mask:0xf bank_mask:0xf bound_ctrl:1
	v_add_f32_dpp v130, v130, v130 quad_perm:[2,3,0,1] row_mask:0xf bank_mask:0xf bound_ctrl:1
	v_pk_mul_f32 v[148:149], v[8:9], v[66:67]
	v_pk_mul_f32 v[150:151], v[10:11], v[68:69]
	v_add_f32_dpp v128, v128, v128 row_half_mirror row_mask:0xf bank_mask:0xf bound_ctrl:1
	v_add_f32_dpp v130, v130, v130 row_half_mirror row_mask:0xf bank_mask:0xf bound_ctrl:1
	v_pk_mul_f32 v[152:153], v[12:13], v[70:71]
	v_pk_mul_f32 v[154:155], v[14:15], v[72:73]
	v_pk_fma_f32 v[132:133], v[98:99], v[90:91], v[132:133] op_sel_hi:[0,1,1]
	v_pk_fma_f32 v[134:135], v[98:99], v[92:93], v[134:135] op_sel_hi:[0,1,1]
	v_pk_fma_f32 v[136:137], v[98:99], v[94:95], v[136:137] op_sel_hi:[0,1,1]
	v_pk_fma_f32 v[138:139], v[98:99], v[96:97], v[138:139] op_sel_hi:[0,1,1]
	v_pk_fma_f32 v[148:149], v[98:99], v[90:91], v[148:149] op_sel:[1,0,0] op_sel_hi:[1,1,1]
	v_pk_fma_f32 v[150:151], v[98:99], v[92:93], v[150:151] op_sel:[1,0,0] op_sel_hi:[1,1,1]
	v_pk_fma_f32 v[152:153], v[98:99], v[94:95], v[152:153] op_sel:[1,0,0] op_sel_hi:[1,1,1]
	v_pk_fma_f32 v[154:155], v[98:99], v[96:97], v[154:155] op_sel:[1,0,0] op_sel_hi:[1,1,1]
	v_pk_mul_f32 v[192:193], v[0:1], v[116:117]
	v_pk_fma_f32 v[192:193], v[2:3], v[118:119], v[192:193]
	v_pk_fma_f32 v[192:193], v[4:5], v[120:121], v[192:193]
	v_pk_fma_f32 v[192:193], v[6:7], v[122:123], v[192:193]
	v_add_f32_e32 v188, v192, v193
	v_pk_mul_f32 v[194:195], v[8:9], v[116:117]
	v_pk_fma_f32 v[194:195], v[10:11], v[118:119], v[194:195]
	v_pk_fma_f32 v[194:195], v[12:13], v[120:121], v[194:195]
	v_pk_fma_f32 v[194:195], v[14:15], v[122:123], v[194:195]
	v_add_f32_e32 v189, v194, v195
	v_pk_fma_f32 v[0:1], v[128:129], v[82:83], v[132:133] op_sel_hi:[0,1,1] neg_lo:[1,0,0] neg_hi:[1,0,0]
	v_pk_fma_f32 v[2:3], v[128:129], v[84:85], v[134:135] op_sel_hi:[0,1,1] neg_lo:[1,0,0] neg_hi:[1,0,0]
	v_pk_fma_f32 v[4:5], v[128:129], v[86:87], v[136:137] op_sel_hi:[0,1,1] neg_lo:[1,0,0] neg_hi:[1,0,0]
	v_pk_fma_f32 v[6:7], v[128:129], v[88:89], v[138:139] op_sel_hi:[0,1,1] neg_lo:[1,0,0] neg_hi:[1,0,0]
	v_pk_fma_f32 v[8:9], v[130:131], v[82:83], v[148:149] op_sel_hi:[0,1,1] neg_lo:[1,0,0] neg_hi:[1,0,0]
	v_pk_fma_f32 v[10:11], v[130:131], v[84:85], v[150:151] op_sel_hi:[0,1,1] neg_lo:[1,0,0] neg_hi:[1,0,0]
	v_pk_fma_f32 v[12:13], v[130:131], v[86:87], v[152:153] op_sel_hi:[0,1,1] neg_lo:[1,0,0] neg_hi:[1,0,0]
	v_pk_fma_f32 v[14:15], v[130:131], v[88:89], v[154:155] op_sel_hi:[0,1,1] neg_lo:[1,0,0] neg_hi:[1,0,0]
	v_pk_mul_f32 v[192:193], v[0:1], v[100:101]
	v_pk_fma_f32 v[192:193], v[2:3], v[102:103], v[192:193]
	v_pk_fma_f32 v[192:193], v[4:5], v[104:105], v[192:193]
	v_pk_fma_f32 v[192:193], v[6:7], v[106:107], v[192:193]
	v_add_f32_e32 v190, v192, v193
	v_pk_mul_f32 v[194:195], v[8:9], v[100:101]
	v_pk_fma_f32 v[194:195], v[10:11], v[102:103], v[194:195]
	v_pk_fma_f32 v[194:195], v[12:13], v[104:105], v[194:195]
	v_pk_fma_f32 v[194:195], v[14:15], v[106:107], v[194:195]
	v_add_f32_e32 v191, v194, v195
	v_cmp_ne_u32_e32 vcc, 0, v22
	v_add_f32_dpp v160, v160, v160 row_half_mirror row_mask:0xf bank_mask:0x5 bound_ctrl:1
	v_add_f32_dpp v160, v176, v176 row_half_mirror row_mask:0xf bank_mask:0xa bound_ctrl:1
	v_add_f32_dpp v161, v161, v161 row_half_mirror row_mask:0xf bank_mask:0x5 bound_ctrl:1
	v_add_f32_dpp v161, v177, v177 row_half_mirror row_mask:0xf bank_mask:0xa bound_ctrl:1
	v_add_f32_dpp v162, v162, v162 row_half_mirror row_mask:0xf bank_mask:0x5 bound_ctrl:1
	v_add_f32_dpp v162, v178, v178 row_half_mirror row_mask:0xf bank_mask:0xa bound_ctrl:1
	v_add_f32_dpp v163, v163, v163 row_half_mirror row_mask:0xf bank_mask:0x5 bound_ctrl:1
	v_add_f32_dpp v163, v179, v179 row_half_mirror row_mask:0xf bank_mask:0xa bound_ctrl:1
	v_add_f32_dpp v164, v164, v164 row_half_mirror row_mask:0xf bank_mask:0x5 bound_ctrl:1
; __device__ __forceinline__ u16 f2bf(float f) { unsigned u = __float_as_uint(f); u += 0x7fffu + ((u >> 16) & 1u); return (u16)(u >> 16); }
; __device__ __forceinline__ float red8_sum(float x) { x += dpp_f<0xB1>(x); x += dpp_f<0x4E>(x); x += dpp_f<0x141>(x); return x; }
; template <int RG, int NSW>
; __device__ __forceinline__ void scan_waves(const Params& p, float* lds, const int T, const int dir, const int wave, const int lane,
;                                            const size_t tok0, const int head, const int row_base) {
;     ...
;         for (int g = 0; g < RG; ++g) o[g] = red8_sum(o[g]);
;         float os = o[0];
; #pragma unroll
;         for (int g = 1; g < RG; ++g) os = (part == g) ? o[g] : os;
;         osv[st] = os;
;       }
;     ...
;       if (part < RG) {
;         const int s0 = i * 16; const unsigned t0 = dir ? (unsigned)(T - 1 - s0) : (unsigned)s0;
;         unsigned off = ooff0 + t0 * ostride; const unsigned dt = dir ? 0u - ostride : ostride;
; #pragma unroll
;         for (int st = 0; st < 16; ++st) { *(u16*)(obase + (size_t)off) = f2bf(osv[st]); off += dt; }
;       }
	v_add_f32_dpp v164, v180, v180 row_half_mirror row_mask:0xf bank_mask:0xa bound_ctrl:1
	v_add_f32_dpp v165, v165, v165 row_half_mirror row_mask:0xf bank_mask:0x5 bound_ctrl:1
	v_add_f32_dpp v165, v181, v181 row_half_mirror row_mask:0xf bank_mask:0xa bound_ctrl:1
	v_add_f32_dpp v166, v166, v166 row_half_mirror row_mask:0xf bank_mask:0x5 bound_ctrl:1
	v_add_f32_dpp v166, v182, v182 row_half_mirror row_mask:0xf bank_mask:0xa bound_ctrl:1
	v_add_f32_dpp v167, v167, v167 row_half_mirror row_mask:0xf bank_mask:0x5 bound_ctrl:1
	v_add_f32_dpp v167, v183, v183 row_half_mirror row_mask:0xf bank_mask:0xa bound_ctrl:1
	v_add_f32_dpp v168, v168, v168 row_half_mirror row_mask:0xf bank_mask:0x5 bound_ctrl:1
	v_add_f32_dpp v168, v184, v184 row_half_mirror row_mask:0xf bank_mask:0xa bound_ctrl:1
	v_add_f32_dpp v169, v169, v169 row_half_mirror row_mask:0xf bank_mask:0x5 bound_ctrl:1
	v_add_f32_dpp v169, v185, v185 row_half_mirror row_mask:0xf bank_mask:0xa bound_ctrl:1
	v_add_f32_dpp v170, v170, v170 row_half_mirror row_mask:0xf bank_mask:0x5 bound_ctrl:1
	v_add_f32_dpp v170, v186, v186 row_half_mirror row_mask:0xf bank_mask:0xa bound_ctrl:1
	v_add_f32_dpp v171, v171, v171 row_half_mirror row_mask:0xf bank_mask:0x5 bound_ctrl:1
	v_add_f32_dpp v171, v187, v187 row_half_mirror row_mask:0xf bank_mask:0xa bound_ctrl:1
	v_add_f32_dpp v172, v172, v172 row_half_mirror row_mask:0xf bank_mask:0x5 bound_ctrl:1
	v_add_f32_dpp v172, v188, v188 row_half_mirror row_mask:0xf bank_mask:0xa bound_ctrl:1
	v_add_f32_dpp v173, v173, v173 row_half_mirror row_mask:0xf bank_mask:0x5 bound_ctrl:1
	v_add_f32_dpp v173, v189, v189 row_half_mirror row_mask:0xf bank_mask:0xa bound_ctrl:1
	v_add_f32_dpp v174, v174, v174 row_half_mirror row_mask:0xf bank_mask:0x5 bound_ctrl:1
	v_add_f32_dpp v174, v190, v190 row_half_mirror row_mask:0xf bank_mask:0xa bound_ctrl:1
	v_add_f32_dpp v175, v175, v175 row_half_mirror row_mask:0xf bank_mask:0x5 bound_ctrl:1
	v_add_f32_dpp v175, v191, v191 row_half_mirror row_mask:0xf bank_mask:0xa bound_ctrl:1
	v_cndmask_b32_e32 v204, v168, v160, vcc
	v_cndmask_b32_e32 v205, v169, v161, vcc
	v_cndmask_b32_e32 v206, v170, v162, vcc
	v_cndmask_b32_e32 v207, v171, v163, vcc
	v_cndmask_b32_e32 v208, v172, v164, vcc
	v_cndmask_b32_e32 v209, v173, v165, vcc
	v_cndmask_b32_e32 v210, v174, v166, vcc
	v_cndmask_b32_e32 v211, v175, v167, vcc
	v_cndmask_b32_e32 v212, v160, v168, vcc
	v_cndmask_b32_e32 v213, v161, v169, vcc
	v_cndmask_b32_e32 v214, v162, v170, vcc
	v_cndmask_b32_e32 v215, v163, v171, vcc
	v_cndmask_b32_e32 v216, v164, v172, vcc
	v_cndmask_b32_e32 v217, v165, v173, vcc
	v_cndmask_b32_e32 v218, v166, v174, vcc
	v_cndmask_b32_e32 v219, v167, v175, vcc
	v_cmp_ne_u32_e32 vcc, 0, v23
	v_add_f32_dpp v196, v204, v212 quad_perm:[2,3,0,1] row_mask:0xf bank_mask:0xf bound_ctrl:1
	v_add_f32_dpp v197, v205, v213 quad_perm:[2,3,0,1] row_mask:0xf bank_mask:0xf bound_ctrl:1
	v_add_f32_dpp v198, v206, v214 quad_perm:[2,3,0,1] row_mask:0xf bank_mask:0xf bound_ctrl:1
	v_add_f32_dpp v199, v207, v215 quad_perm:[2,3,0,1] row_mask:0xf bank_mask:0xf bound_ctrl:1
	v_add_f32_dpp v200, v208, v216 quad_perm:[2,3,0,1] row_mask:0xf bank_mask:0xf bound_ctrl:1
	v_add_f32_dpp v201, v209, v217 quad_perm:[2,3,0,1] row_mask:0xf bank_mask:0xf bound_ctrl:1
	v_add_f32_dpp v202, v210, v218 quad_perm:[2,3,0,1] row_mask:0xf bank_mask:0xf bound_ctrl:1
	v_add_f32_dpp v203, v211, v219 quad_perm:[2,3,0,1] row_mask:0xf bank_mask:0xf bound_ctrl:1
	v_cndmask_b32_e32 v204, v197, v196, vcc
	v_cndmask_b32_e32 v205, v199, v198, vcc
	v_cndmask_b32_e32 v206, v201, v200, vcc
	v_cndmask_b32_e32 v207, v203, v202, vcc
	v_cndmask_b32_e32 v212, v196, v197, vcc
	v_cndmask_b32_e32 v213, v198, v199, vcc
	v_cndmask_b32_e32 v214, v200, v201, vcc
	v_cndmask_b32_e32 v215, v202, v203, vcc
	s_and_b64 s[58:59], s[0:1], exec
	s_cselect_b32 s57, s55, s56
	s_lshl_b32 s57, s57, s10
	v_add_f32_dpp v196, v204, v212 quad_perm:[1,0,3,2] row_mask:0xf bank_mask:0xf bound_ctrl:1
	v_add_f32_dpp v197, v205, v213 quad_perm:[1,0,3,2] row_mask:0xf bank_mask:0xf bound_ctrl:1
	v_add_f32_dpp v198, v206, v214 quad_perm:[1,0,3,2] row_mask:0xf bank_mask:0xf bound_ctrl:1
	v_add_f32_dpp v199, v207, v215 quad_perm:[1,0,3,2] row_mask:0xf bank_mask:0xf bound_ctrl:1
	v_add3_u32 v204, v18, v24, s57
	v_cvt_pk_bf16_f32 v196, v196, v197
	v_cvt_pk_bf16_f32 v198, v198, v199
	v_add_u32_e32 v205, s52, v204
	v_add_u32_e32 v206, s52, v205
	v_add_u32_e32 v207, s52, v206
	global_store_short v204, v196, s[14:15]
	global_store_short_d16_hi v205, v196, s[14:15]
	global_store_short v206, v198, s[14:15]
	global_store_short_d16_hi v207, v198, s[14:15]
	s_branch .Lmy_ss_next

; template <int NS, bool LORA, int mat> ...
;     ...
;   const int ch = 64 * head + lane;
;   const float kk_c = p.k_k[ch], ka_c = p.k_a[ch], rk_c = p.r_k[ch];
;   const float mu_r = p.mu_shift[ch], mu_k = p.mu_shift[1024 + ch], mu_v = p.mu_shift[2048 + ch];
;   uint4 la[2][6];
;   u16 rv[2][NS][9];
.LBB0_1226:
	s_andn2_b64 vcc, exec, s[0:1]
	s_cbranch_vccnz .LBB0_1354
	s_ashr_i32 s0, s2, 3
	s_add_i32 s4, s3, s0
	s_and_b32 s3, s0, 3
	s_ashr_i32 s59, s4, 3
	s_bfe_u32 s58, s0, 0x10002
	s_cmp_eq_u32 s58, 0
	s_waitcnt vmcnt(7)
	v_mov_b32 v140, v146
	s_cselect_b64 s[0:1], -1, 0
	s_waitcnt vmcnt(0)
	v_ashrrev_i32_e32 v6, 6, v140
	v_and_b32_e32 v148, 63, v140
	v_cmp_lt_i32_e32 vcc, 3, v6
	s_and_saveexec_b64 s[6:7], vcc
	s_xor_b64 s[46:47], exec, s[6:7]
	s_cbranch_execz .LBB0_1346
	s_lshl_b32 s61, s59, 6
	s_lshl_b32 s63, s58, 6
	s_lshl_b32 s5, s58, 10
	s_ashr_i32 s6, s61, 31
	s_add_u32 s64, s61, s5
	s_addc_u32 s65, s6, 0
	s_add_i32 s62, s61, s5
	s_and_b32 s4, s4, -8
	s_lshl_b32 s5, s58, 2
	s_or_b32 s60, s5, s4
	v_cmp_lt_i32_e32 vcc, 4, v6
	s_and_saveexec_b64 s[4:5], vcc
	s_xor_b64 s[48:49], exec, s[4:5]
	s_cbranch_execz .LBB0_1319
	v_cmp_ne_u32_e32 vcc, 5, v6
	s_and_saveexec_b64 s[4:5], vcc
	s_xor_b64 s[52:53], exec, s[4:5]
	s_cbranch_execz .LBB0_1276
	v_readfirstlane_b32 s4, v6
	v_and_b32_e32 v48, 7, v148
	v_lshrrev_b32_e32 v49, 3, v148
	s_sub_i32 s4, s4, 6
	s_lshl_b32 s4, s4, 3
	v_add_u32_e32 v50, s4, v49
	v_lshl_add_u32 v51, v48, 3, s61
	v_lshlrev_b32_e32 v52, 1, v51
	v_add_u32_e32 v52, 0x800, v52
	v_lshlrev_b32_e32 v51, 2, v51
	v_mov_b32_e32 v53, 0x1c00
	v_add_u32_e32 v205, 0x1000, v51
	v_add_u32_e32 v206, 0x2000, v51
	global_load_dwordx4 v[0:3], v51, s[50:51]
	global_load_dwordx4 v[4:7], v51, s[50:51] offset:16
	global_load_dwordx4 v[8:11], v51, s[16:17]
	global_load_dwordx4 v[12:15], v51, s[16:17] offset:16
	global_load_dwordx4 v[16:19], v51, s[18:19]
	global_load_dwordx4 v[20:23], v51, s[18:19] offset:16
	global_load_dwordx4 v[24:27], v51, s[38:39]
	global_load_dwordx4 v[28:31], v51, s[38:39] offset:16
	global_load_dwordx4 v[32:35], v205, s[38:39]
	global_load_dwordx4 v[36:39], v205, s[38:39] offset:16
	global_load_dwordx4 v[40:43], v206, s[38:39]
	global_load_dwordx4 v[44:47], v206, s[38:39] offset:16
	v_mul_u32_u24_e32 v54, 0x500, v50
	v_lshlrev_b32_e32 v55, 8, v50
	v_lshl_add_u32 v54, v48, 5, v54
	v_lshl_add_u32 v55, v48, 5, v55
	v_add_u32_e32 v54, 0x5000, v54
	v_add_u32_e32 v55, 0x3000, v55
	s_movk_i32 s77, 0x3fff
	s_cmp_eq_u32 s58, 0
	s_cselect_b32 s80, 16, -16
	v_sub_u32_e32 v205, s77, v50
	v_cndmask_b32_e64 v56, v205, v50, s[0:1]
	v_and_b32_e32 v205, 3, v50
	v_cmp_eq_u32_e64 s[8:9], s3, v205
	v_cmp_eq_u32_e32 vcc, 0, v48
	s_and_b64 s[8:9], s[8:9], vcc
	s_waitcnt vmcnt(0)
	v_cmp_lt_i32_e64 s[10:11], 0, v56
	v_cmp_gt_i32_e64 s[12:13], s77, v56
	v_mad_u32_u24 v205, v56, v53, v52
	s_nop 0
	v_cndmask_b32_e64 v206, 0, v53, s[10:11]
	v_cndmask_b32_e64 v207, 0, v53, s[12:13]
	v_sub_u32_e32 v206, v205, v206
	v_add_u32_e32 v207, v205, v207
	global_load_dwordx4 v[64:67], v205, s[72:73] offset:-2048
	global_load_dwordx4 v[68:71], v205, s[72:73]
	global_load_dwordx4 v[72:75], v205, s[72:73] offset:2048
	global_load_dwordx4 v[76:79], v206, s[72:73] offset:-2048
	global_load_dwordx4 v[80:83], v206, s[72:73]
	global_load_dwordx4 v[84:87], v206, s[72:73] offset:2048
	global_load_dwordx4 v[88:91], v207, s[72:73] offset:-2048
	global_load_dwordx4 v[92:95], v207, s[72:73]
	global_load_dwordx4 v[96:99], v207, s[72:73] offset:2048
	s_mov_b32 s66, 1
	s_waitcnt lgkmcnt(0)
	s_barrier
.Lmy_k_loop:
	v_cmp_lt_i32_e64 s[14:15], 0, v56
	v_cmp_gt_i32_e64 s[54:55], s77, v56
	v_add_u32_e32 v57, s80, v56
	v_cmp_lt_i32_e64 s[10:11], 0, v57
	v_cmp_gt_i32_e64 s[12:13], s77, v57
	v_mad_u32_u24 v205, v57, v53, v52
	s_nop 0
	v_cndmask_b32_e64 v206, 0, v53, s[10:11]
	v_cndmask_b32_e64 v207, 0, v53, s[12:13]
	v_sub_u32_e32 v206, v205, v206
	v_add_u32_e32 v207, v205, v207
	global_load_dwordx4 v[100:103], v205, s[72:73] offset:-2048
	global_load_dwordx4 v[104:107], v205, s[72:73]
	global_load_dwordx4 v[108:111], v205, s[72:73] offset:2048
	global_load_dwordx4 v[112:115], v206, s[72:73] offset:-2048
	global_load_dwordx4 v[116:119], v206, s[72:73]
	global_load_dwordx4 v[120:123], v206, s[72:73] offset:2048
	global_load_dwordx4 v[124:127], v207, s[72:73] offset:-2048
	global_load_dwordx4 v[128:131], v207, s[72:73]
	global_load_dwordx4 v[132:135], v207, s[72:73] offset:2048
	ds_read_b128 v[184:187], v55 offset:0
	ds_read_b128 v[188:191], v55 offset:16
	s_waitcnt vmcnt(9)
	v_cndmask_b32_e64 v203, 0, 1.0, s[14:15]
	v_cndmask_b32_e64 v204, 0, 1.0, s[54:55]
	v_lshlrev_b32_e32 v136, 16, v64
	v_lshlrev_b32_e32 v192, 16, v76
	v_lshlrev_b32_e32 v193, 16, v88
	v_mul_f32_e32 v193, v204, v193
	v_fmac_f32_e32 v193, v203, v192
	v_fma_f32 v192, v193, 0.5, -v136
	v_fmac_f32_e32 v136, v24, v192
	v_and_b32_e32 v137, 0xffff0000, v64
	v_and_b32_e32 v192, 0xffff0000, v76
	v_and_b32_e32 v193, 0xffff0000, v88
	v_mul_f32_e32 v193, v204, v193
	v_fmac_f32_e32 v193, v203, v192
	v_fma_f32 v192, v193, 0.5, -v137
	v_fmac_f32_e32 v137, v25, v192
	v_lshlrev_b32_e32 v138, 16, v65
	v_lshlrev_b32_e32 v192, 16, v77
	v_lshlrev_b32_e32 v193, 16, v89
	v_mul_f32_e32 v193, v204, v193
	v_fmac_f32_e32 v193, v203, v192
	v_fma_f32 v192, v193, 0.5, -v138
	v_fmac_f32_e32 v138, v26, v192
	v_and_b32_e32 v139, 0xffff0000, v65
	v_and_b32_e32 v192, 0xffff0000, v77
	v_and_b32_e32 v193, 0xffff0000, v89
	v_mul_f32_e32 v193, v204, v193
	v_fmac_f32_e32 v193, v203, v192
	v_fma_f32 v192, v193, 0.5, -v139
	v_fmac_f32_e32 v139, v27, v192
	v_lshlrev_b32_e32 v140, 16, v66
	v_lshlrev_b32_e32 v192, 16, v78
	v_lshlrev_b32_e32 v193, 16, v90
	v_mul_f32_e32 v193, v204, v193
	v_fmac_f32_e32 v193, v203, v192
	v_fma_f32 v192, v193, 0.5, -v140
	v_fmac_f32_e32 v140, v28, v192
	v_and_b32_e32 v141, 0xffff0000, v66
	v_and_b32_e32 v192, 0xffff0000, v78
	v_and_b32_e32 v193, 0xffff0000, v90
	v_mul_f32_e32 v193, v204, v193
	v_fmac_f32_e32 v193, v203, v192
	v_fma_f32 v192, v193, 0.5, -v141
	v_fmac_f32_e32 v141, v29, v192
	v_lshlrev_b32_e32 v142, 16, v67
	v_lshlrev_b32_e32 v192, 16, v79
	v_lshlrev_b32_e32 v193, 16, v91
	v_mul_f32_e32 v193, v204, v193
	v_fmac_f32_e32 v193, v203, v192
	v_fma_f32 v192, v193, 0.5, -v142
	v_fmac_f32_e32 v142, v30, v192
	v_and_b32_e32 v143, 0xffff0000, v67
	v_and_b32_e32 v192, 0xffff0000, v79
	v_and_b32_e32 v193, 0xffff0000, v91
	v_mul_f32_e32 v193, v204, v193
	v_fmac_f32_e32 v193, v203, v192
	v_fma_f32 v192, v193, 0.5, -v143
	v_fmac_f32_e32 v143, v31, v192
	v_lshlrev_b32_e32 v208, 16, v68
	v_lshlrev_b32_e32 v192, 16, v80
	v_lshlrev_b32_e32 v193, 16, v92
	v_mul_f32_e32 v193, v204, v193
	v_fmac_f32_e32 v193, v203, v192
	v_fma_f32 v192, v193, 0.5, -v208
	v_fmac_f32_e32 v208, v32, v192
	v_and_b32_e32 v209, 0xffff0000, v68
	v_and_b32_e32 v192, 0xffff0000, v80
	v_and_b32_e32 v193, 0xffff0000, v92
	v_mul_f32_e32 v193, v204, v193
	v_fmac_f32_e32 v193, v203, v192
	v_fma_f32 v192, v193, 0.5, -v209
	v_fmac_f32_e32 v209, v33, v192
	v_lshlrev_b32_e32 v210, 16, v69
	v_lshlrev_b32_e32 v192, 16, v81
	v_lshlrev_b32_e32 v193, 16, v93
	v_mul_f32_e32 v193, v204, v193
	v_fmac_f32_e32 v193, v203, v192
	v_fma_f32 v192, v193, 0.5, -v210
	v_fmac_f32_e32 v210, v34, v192
	v_and_b32_e32 v211, 0xffff0000, v69
	v_and_b32_e32 v192, 0xffff0000, v81
	v_and_b32_e32 v193, 0xffff0000, v93
	v_mul_f32_e32 v193, v204, v193
	v_fmac_f32_e32 v193, v203, v192
	v_fma_f32 v192, v193, 0.5, -v211
	v_fmac_f32_e32 v211, v35, v192
	v_lshlrev_b32_e32 v212, 16, v70
	v_lshlrev_b32_e32 v192, 16, v82
	v_lshlrev_b32_e32 v193, 16, v94
	v_mul_f32_e32 v193, v204, v193
	v_fmac_f32_e32 v193, v203, v192
	v_fma_f32 v192, v193, 0.5, -v212
	v_fmac_f32_e32 v212, v36, v192
	v_and_b32_e32 v213, 0xffff0000, v70
	v_and_b32_e32 v192, 0xffff0000, v82
	v_and_b32_e32 v193, 0xffff0000, v94
	v_mul_f32_e32 v193, v204, v193
	v_fmac_f32_e32 v193, v203, v192
	v_fma_f32 v192, v193, 0.5, -v213
	v_fmac_f32_e32 v213, v37, v192
	v_lshlrev_b32_e32 v214, 16, v71
	v_lshlrev_b32_e32 v192, 16, v83
	v_lshlrev_b32_e32 v193, 16, v95
	v_mul_f32_e32 v193, v204, v193
	v_fmac_f32_e32 v193, v203, v192
	v_fma_f32 v192, v193, 0.5, -v214
	v_fmac_f32_e32 v214, v38, v192
	v_and_b32_e32 v215, 0xffff0000, v71
	v_and_b32_e32 v192, 0xffff0000, v83
	v_and_b32_e32 v193, 0xffff0000, v95
	v_mul_f32_e32 v193, v204, v193
	v_fmac_f32_e32 v193, v203, v192
	v_fma_f32 v192, v193, 0.5, -v215
	v_fmac_f32_e32 v215, v39, v192
	v_lshlrev_b32_e32 v152, 16, v72
	v_lshlrev_b32_e32 v192, 16, v84
	v_lshlrev_b32_e32 v193, 16, v96
	v_mul_f32_e32 v193, v204, v193
	v_fmac_f32_e32 v193, v203, v192
	v_fma_f32 v192, v193, 0.5, -v152
	v_fmac_f32_e32 v152, v40, v192
	v_and_b32_e32 v153, 0xffff0000, v72
	v_and_b32_e32 v192, 0xffff0000, v84
	v_and_b32_e32 v193, 0xffff0000, v96
	v_mul_f32_e32 v193, v204, v193
	v_fmac_f32_e32 v193, v203, v192
	v_fma_f32 v192, v193, 0.5, -v153
	v_fmac_f32_e32 v153, v41, v192
	v_lshlrev_b32_e32 v154, 16, v73
	v_lshlrev_b32_e32 v192, 16, v85
	v_lshlrev_b32_e32 v193, 16, v97
	v_mul_f32_e32 v193, v204, v193
	v_fmac_f32_e32 v193, v203, v192
	v_fma_f32 v192, v193, 0.5, -v154
	v_fmac_f32_e32 v154, v42, v192
	v_and_b32_e32 v155, 0xffff0000, v73
	v_and_b32_e32 v192, 0xffff0000, v85
	v_and_b32_e32 v193, 0xffff0000, v97
	v_mul_f32_e32 v193, v204, v193
	v_fmac_f32_e32 v193, v203, v192
	v_fma_f32 v192, v193, 0.5, -v155
	v_fmac_f32_e32 v155, v43, v192
	v_lshlrev_b32_e32 v156, 16, v74
	v_lshlrev_b32_e32 v192, 16, v86
	v_lshlrev_b32_e32 v193, 16, v98
	v_mul_f32_e32 v193, v204, v193
	v_fmac_f32_e32 v193, v203, v192
	v_fma_f32 v192, v193, 0.5, -v156
	v_fmac_f32_e32 v156, v44, v192
	v_and_b32_e32 v157, 0xffff0000, v74
	v_and_b32_e32 v192, 0xffff0000, v86
	v_and_b32_e32 v193, 0xffff0000, v98
	v_mul_f32_e32 v193, v204, v193
	v_fmac_f32_e32 v193, v203, v192
	v_fma_f32 v192, v193, 0.5, -v157
	v_fmac_f32_e32 v157, v45, v192
	v_lshlrev_b32_e32 v158, 16, v75
	v_lshlrev_b32_e32 v192, 16, v87
	v_lshlrev_b32_e32 v193, 16, v99
	v_mul_f32_e32 v193, v204, v193
	v_fmac_f32_e32 v193, v203, v192
	v_fma_f32 v192, v193, 0.5, -v158
	v_fmac_f32_e32 v158, v46, v192
	v_and_b32_e32 v159, 0xffff0000, v75
	v_and_b32_e32 v192, 0xffff0000, v87
	v_and_b32_e32 v193, 0xffff0000, v99
	v_mul_f32_e32 v193, v204, v193
	v_fmac_f32_e32 v193, v203, v192
	v_fma_f32 v192, v193, 0.5, -v159
	v_fmac_f32_e32 v159, v47, v192
	v_mul_f32_e32 v160, v0, v208
	v_mul_f32_e32 v161, v1, v209
	v_mul_f32_e32 v162, v2, v210
	v_mul_f32_e32 v163, v3, v211
	v_mul_f32_e32 v164, v4, v212
	v_mul_f32_e32 v165, v5, v213
	v_mul_f32_e32 v166, v6, v214
	v_mul_f32_e32 v167, v7, v215
	v_mul_f32_e32 v200, v160, v160
	v_fmac_f32_e32 v200, v161, v161
	v_fmac_f32_e32 v200, v162, v162
	v_fmac_f32_e32 v200, v163, v163
	v_fmac_f32_e32 v200, v164, v164
	v_fmac_f32_e32 v200, v165, v165
	v_fmac_f32_e32 v200, v166, v166
	v_fmac_f32_e32 v200, v167, v167
	s_waitcnt lgkmcnt(0)
	v_add_f32_e32 v192, -1.0, v184
	v_fma_f32 v192, v8, v192, 1.0
	v_mul_f32_e32 v176, v208, v192
	v_add_f32_dpp v200, v200, v200 quad_perm:[1,0,3,2] row_mask:0xf bank_mask:0xf bound_ctrl:1
	v_add_f32_e32 v192, -1.0, v185
	v_fma_f32 v192, v9, v192, 1.0
	v_mul_f32_e32 v177, v209, v192
	v_add_f32_dpp v200, v200, v200 quad_perm:[2,3,0,1] row_mask:0xf bank_mask:0xf bound_ctrl:1
	v_add_f32_e32 v192, -1.0, v186
	v_fma_f32 v192, v10, v192, 1.0
	v_mul_f32_e32 v178, v210, v192
	v_add_f32_dpp v200, v200, v200 row_half_mirror row_mask:0xf bank_mask:0xf bound_ctrl:1
	v_add_f32_e32 v192, -1.0, v187
	v_fma_f32 v192, v11, v192, 1.0
	v_mul_f32_e32 v179, v211, v192
	v_add_f32_e32 v192, -1.0, v188
	v_fma_f32 v192, v12, v192, 1.0
	v_mul_f32_e32 v180, v212, v192
	v_add_f32_e32 v192, -1.0, v189
	v_fma_f32 v192, v13, v192, 1.0
	v_mul_f32_e32 v181, v213, v192
	v_add_f32_e32 v192, -1.0, v190
	v_fma_f32 v192, v14, v192, 1.0
	v_mul_f32_e32 v182, v214, v192
	v_add_f32_e32 v192, -1.0, v191
	v_fma_f32 v192, v15, v192, 1.0
	v_mul_f32_e32 v183, v215, v192
	v_max_f32_e32 v200, v200, v200
	v_max_f32_e32 v200, 0x179abe15, v200
	v_rsq_f32_e32 v201, v200
	v_mul_f32_e32 v192, v136, v176
	v_mul_f32_e32 v202, v16, v192
	v_mul_f32_e32 v160, v160, v201
	v_mul_f32_e32 v161, v161, v201
	v_mul_f32_e32 v162, v162, v201
	v_mul_f32_e32 v163, v163, v201
	v_mul_f32_e32 v164, v164, v201
	v_mul_f32_e32 v165, v165, v201
	v_mul_f32_e32 v166, v166, v201
	v_mul_f32_e32 v167, v167, v201
	v_mul_f32_e32 v168, v184, v160
	v_mul_f32_e32 v169, v185, v161
	v_mul_f32_e32 v170, v186, v162
	v_mul_f32_e32 v171, v187, v163
	v_mul_f32_e32 v172, v188, v164
	v_mul_f32_e32 v173, v189, v165
	v_mul_f32_e32 v174, v190, v166
	v_mul_f32_e32 v175, v191, v167
	ds_write_b128 v54, v[160:163] offset:0
	ds_write_b128 v54, v[164:167] offset:16
	ds_write_b128 v54, v[168:171] offset:256
	ds_write_b128 v54, v[172:175] offset:272
	ds_write_b128 v54, v[176:179] offset:512
	ds_write_b128 v54, v[180:183] offset:528
	ds_write_b128 v54, v[136:139] offset:768
	ds_write_b128 v54, v[140:143] offset:784
	ds_write_b128 v54, v[152:155] offset:1024
	ds_write_b128 v54, v[156:159] offset:1040
	v_mul_f32_e32 v192, v137, v177
	v_fmac_f32_e32 v202, v17, v192
	v_mul_f32_e32 v192, v138, v178
	v_fmac_f32_e32 v202, v18, v192
	v_mul_f32_e32 v192, v139, v179
	v_fmac_f32_e32 v202, v19, v192
	v_mul_f32_e32 v192, v140, v180
	v_fmac_f32_e32 v202, v20, v192
	v_mul_f32_e32 v192, v141, v181
	v_fmac_f32_e32 v202, v21, v192
	v_mul_f32_e32 v192, v142, v182
	v_fmac_f32_e32 v202, v22, v192
	v_mul_f32_e32 v192, v143, v183
	v_fmac_f32_e32 v202, v23, v192
	s_nop 1
	v_add_f32_dpp v202, v202, v202 quad_perm:[1,0,3,2] row_mask:0xf bank_mask:0xf bound_ctrl:1
	s_nop 1
	v_add_f32_dpp v202, v202, v202 quad_perm:[2,3,0,1] row_mask:0xf bank_mask:0xf bound_ctrl:1
	s_nop 1
	v_add_f32_dpp v202, v202, v202 row_half_mirror row_mask:0xf bank_mask:0xf bound_ctrl:1
	v_lshl_add_u32 v205, v56, 7, s60
	s_and_saveexec_b64 s[6:7], s[8:9]
	global_store_dword v205, v202, s[24:25]
	s_or_b64 exec, exec, s[6:7]
	v_mov_b32_e32 v56, v57
	s_waitcnt lgkmcnt(0)
	s_barrier
	s_add_i32 s66, s66, 1
	v_cmp_lt_i32_e64 s[14:15], 0, v56
	v_cmp_gt_i32_e64 s[54:55], s77, v56
	v_add_u32_e32 v57, s80, v56
	s_cmp_lt_u32 s66, 1024
	s_cbranch_scc0 .Lmy_kb_nonext
	v_cmp_lt_i32_e64 s[10:11], 0, v57
	v_cmp_gt_i32_e64 s[12:13], s77, v57
	v_mad_u32_u24 v205, v57, v53, v52
	s_nop 0
	v_cndmask_b32_e64 v206, 0, v53, s[10:11]
	v_cndmask_b32_e64 v207, 0, v53, s[12:13]
	v_sub_u32_e32 v206, v205, v206
	v_add_u32_e32 v207, v205, v207
	global_load_dwordx4 v[64:67], v205, s[72:73] offset:-2048
	global_load_dwordx4 v[68:71], v205, s[72:73]
	global_load_dwordx4 v[72:75], v205, s[72:73] offset:2048
	global_load_dwordx4 v[76:79], v206, s[72:73] offset:-2048
	global_load_dwordx4 v[80:83], v206, s[72:73]
	global_load_dwordx4 v[84:87], v206, s[72:73] offset:2048
	global_load_dwordx4 v[88:91], v207, s[72:73] offset:-2048
	global_load_dwordx4 v[92:95], v207, s[72:73]
	global_load_dwordx4 v[96:99], v207, s[72:73] offset:2048
	ds_read_b128 v[184:187], v55 offset:4096
	ds_read_b128 v[188:191], v55 offset:4112
	s_waitcnt vmcnt(9)
	s_branch .Lmy_kb_go
.Lmy_kb_nonext:
	ds_read_b128 v[184:187], v55 offset:4096
	ds_read_b128 v[188:191], v55 offset:4112
	s_waitcnt vmcnt(0)
.Lmy_kb_go:
	v_cndmask_b32_e64 v203, 0, 1.0, s[14:15]
	v_cndmask_b32_e64 v204, 0, 1.0, s[54:55]
	v_lshlrev_b32_e32 v136, 16, v100
	v_lshlrev_b32_e32 v192, 16, v112
	v_lshlrev_b32_e32 v193, 16, v124
	v_mul_f32_e32 v193, v204, v193
	v_fmac_f32_e32 v193, v203, v192
	v_fma_f32 v192, v193, 0.5, -v136
	v_fmac_f32_e32 v136, v24, v192
	v_and_b32_e32 v137, 0xffff0000, v100
	v_and_b32_e32 v192, 0xffff0000, v112
	v_and_b32_e32 v193, 0xffff0000, v124
	v_mul_f32_e32 v193, v204, v193
	v_fmac_f32_e32 v193, v203, v192
	v_fma_f32 v192, v193, 0.5, -v137
	v_fmac_f32_e32 v137, v25, v192
	v_lshlrev_b32_e32 v138, 16, v101
	v_lshlrev_b32_e32 v192, 16, v113
	v_lshlrev_b32_e32 v193, 16, v125
	v_mul_f32_e32 v193, v204, v193
	v_fmac_f32_e32 v193, v203, v192
	v_fma_f32 v192, v193, 0.5, -v138
	v_fmac_f32_e32 v138, v26, v192
	v_and_b32_e32 v139, 0xffff0000, v101
	v_and_b32_e32 v192, 0xffff0000, v113
	v_and_b32_e32 v193, 0xffff0000, v125
	v_mul_f32_e32 v193, v204, v193
	v_fmac_f32_e32 v193, v203, v192
	v_fma_f32 v192, v193, 0.5, -v139
	v_fmac_f32_e32 v139, v27, v192
	v_lshlrev_b32_e32 v140, 16, v102
	v_lshlrev_b32_e32 v192, 16, v114
	v_lshlrev_b32_e32 v193, 16, v126
	v_mul_f32_e32 v193, v204, v193
	v_fmac_f32_e32 v193, v203, v192
	v_fma_f32 v192, v193, 0.5, -v140
	v_fmac_f32_e32 v140, v28, v192
	v_and_b32_e32 v141, 0xffff0000, v102
	v_and_b32_e32 v192, 0xffff0000, v114
	v_and_b32_e32 v193, 0xffff0000, v126
	v_mul_f32_e32 v193, v204, v193
	v_fmac_f32_e32 v193, v203, v192
	v_fma_f32 v192, v193, 0.5, -v141
	v_fmac_f32_e32 v141, v29, v192
	v_lshlrev_b32_e32 v142, 16, v103
	v_lshlrev_b32_e32 v192, 16, v115
	v_lshlrev_b32_e32 v193, 16, v127
	v_mul_f32_e32 v193, v204, v193
	v_fmac_f32_e32 v193, v203, v192
	v_fma_f32 v192, v193, 0.5, -v142
	v_fmac_f32_e32 v142, v30, v192
	v_and_b32_e32 v143, 0xffff0000, v103
	v_and_b32_e32 v192, 0xffff0000, v115
	v_and_b32_e32 v193, 0xffff0000, v127
	v_mul_f32_e32 v193, v204, v193
	v_fmac_f32_e32 v193, v203, v192
	v_fma_f32 v192, v193, 0.5, -v143
	v_fmac_f32_e32 v143, v31, v192
	v_lshlrev_b32_e32 v208, 16, v104
	v_lshlrev_b32_e32 v192, 16, v116
	v_lshlrev_b32_e32 v193, 16, v128
	v_mul_f32_e32 v193, v204, v193
	v_fmac_f32_e32 v193, v203, v192
	v_fma_f32 v192, v193, 0.5, -v208
	v_fmac_f32_e32 v208, v32, v192
	v_and_b32_e32 v209, 0xffff0000, v104
	v_and_b32_e32 v192, 0xffff0000, v116
	v_and_b32_e32 v193, 0xffff0000, v128
	v_mul_f32_e32 v193, v204, v193
	v_fmac_f32_e32 v193, v203, v192
	v_fma_f32 v192, v193, 0.5, -v209
	v_fmac_f32_e32 v209, v33, v192
	v_lshlrev_b32_e32 v210, 16, v105
	v_lshlrev_b32_e32 v192, 16, v117
	v_lshlrev_b32_e32 v193, 16, v129
	v_mul_f32_e32 v193, v204, v193
	v_fmac_f32_e32 v193, v203, v192
	v_fma_f32 v192, v193, 0.5, -v210
	v_fmac_f32_e32 v210, v34, v192
	v_and_b32_e32 v211, 0xffff0000, v105
	v_and_b32_e32 v192, 0xffff0000, v117
	v_and_b32_e32 v193, 0xffff0000, v129
	v_mul_f32_e32 v193, v204, v193
	v_fmac_f32_e32 v193, v203, v192
	v_fma_f32 v192, v193, 0.5, -v211
	v_fmac_f32_e32 v211, v35, v192
	v_lshlrev_b32_e32 v212, 16, v106
	v_lshlrev_b32_e32 v192, 16, v118
	v_lshlrev_b32_e32 v193, 16, v130
	v_mul_f32_e32 v193, v204, v193
	v_fmac_f32_e32 v193, v203, v192
	v_fma_f32 v192, v193, 0.5, -v212
	v_fmac_f32_e32 v212, v36, v192
	v_and_b32_e32 v213, 0xffff0000, v106
	v_and_b32_e32 v192, 0xffff0000, v118
	v_and_b32_e32 v193, 0xffff0000, v130
	v_mul_f32_e32 v193, v204, v193
	v_fmac_f32_e32 v193, v203, v192
	v_fma_f32 v192, v193, 0.5, -v213
	v_fmac_f32_e32 v213, v37, v192
	v_lshlrev_b32_e32 v214, 16, v107
	v_lshlrev_b32_e32 v192, 16, v119
	v_lshlrev_b32_e32 v193, 16, v131
	v_mul_f32_e32 v193, v204, v193
	v_fmac_f32_e32 v193, v203, v192
	v_fma_f32 v192, v193, 0.5, -v214
	v_fmac_f32_e32 v214, v38, v192
	v_and_b32_e32 v215, 0xffff0000, v107
	v_and_b32_e32 v192, 0xffff0000, v119
	v_and_b32_e32 v193, 0xffff0000, v131
	v_mul_f32_e32 v193, v204, v193
	v_fmac_f32_e32 v193, v203, v192
	v_fma_f32 v192, v193, 0.5, -v215
	v_fmac_f32_e32 v215, v39, v192
	v_lshlrev_b32_e32 v152, 16, v108
	v_lshlrev_b32_e32 v192, 16, v120
	v_lshlrev_b32_e32 v193, 16, v132
	v_mul_f32_e32 v193, v204, v193
	v_fmac_f32_e32 v193, v203, v192
	v_fma_f32 v192, v193, 0.5, -v152
	v_fmac_f32_e32 v152, v40, v192
	v_and_b32_e32 v153, 0xffff0000, v108
	v_and_b32_e32 v192, 0xffff0000, v120
	v_and_b32_e32 v193, 0xffff0000, v132
	v_mul_f32_e32 v193, v204, v193
	v_fmac_f32_e32 v193, v203, v192
	v_fma_f32 v192, v193, 0.5, -v153
	v_fmac_f32_e32 v153, v41, v192
	v_lshlrev_b32_e32 v154, 16, v109
	v_lshlrev_b32_e32 v192, 16, v121
	v_lshlrev_b32_e32 v193, 16, v133
	v_mul_f32_e32 v193, v204, v193
	v_fmac_f32_e32 v193, v203, v192
	v_fma_f32 v192, v193, 0.5, -v154
	v_fmac_f32_e32 v154, v42, v192
	v_and_b32_e32 v155, 0xffff0000, v109
	v_and_b32_e32 v192, 0xffff0000, v121
	v_and_b32_e32 v193, 0xffff0000, v133
	v_mul_f32_e32 v193, v204, v193
	v_fmac_f32_e32 v193, v203, v192
	v_fma_f32 v192, v193, 0.5, -v155
	v_fmac_f32_e32 v155, v43, v192
	v_lshlrev_b32_e32 v156, 16, v110
	v_lshlrev_b32_e32 v192, 16, v122
	v_lshlrev_b32_e32 v193, 16, v134
	v_mul_f32_e32 v193, v204, v193
	v_fmac_f32_e32 v193, v203, v192
	v_fma_f32 v192, v193, 0.5, -v156
	v_fmac_f32_e32 v156, v44, v192
	v_and_b32_e32 v157, 0xffff0000, v110
	v_and_b32_e32 v192, 0xffff0000, v122
	v_and_b32_e32 v193, 0xffff0000, v134
	v_mul_f32_e32 v193, v204, v193
	v_fmac_f32_e32 v193, v203, v192
	v_fma_f32 v192, v193, 0.5, -v157
	v_fmac_f32_e32 v157, v45, v192
	v_lshlrev_b32_e32 v158, 16, v111
	v_lshlrev_b32_e32 v192, 16, v123
	v_lshlrev_b32_e32 v193, 16, v135
	v_mul_f32_e32 v193, v204, v193
	v_fmac_f32_e32 v193, v203, v192
	v_fma_f32 v192, v193, 0.5, -v158
	v_fmac_f32_e32 v158, v46, v192
	v_and_b32_e32 v159, 0xffff0000, v111
	v_and_b32_e32 v192, 0xffff0000, v123
	v_and_b32_e32 v193, 0xffff0000, v135
	v_mul_f32_e32 v193, v204, v193
	v_fmac_f32_e32 v193, v203, v192
	v_fma_f32 v192, v193, 0.5, -v159
	v_fmac_f32_e32 v159, v47, v192
	v_mul_f32_e32 v160, v0, v208
	v_mul_f32_e32 v161, v1, v209
	v_mul_f32_e32 v162, v2, v210
	v_mul_f32_e32 v163, v3, v211
	v_mul_f32_e32 v164, v4, v212
	v_mul_f32_e32 v165, v5, v213
	v_mul_f32_e32 v166, v6, v214
	v_mul_f32_e32 v167, v7, v215
	v_mul_f32_e32 v200, v160, v160
	v_fmac_f32_e32 v200, v161, v161
	v_fmac_f32_e32 v200, v162, v162
	v_fmac_f32_e32 v200, v163, v163
	v_fmac_f32_e32 v200, v164, v164
	v_fmac_f32_e32 v200, v165, v165
	v_fmac_f32_e32 v200, v166, v166
	v_fmac_f32_e32 v200, v167, v167
	s_waitcnt lgkmcnt(0)
; template <int NS, bool LORA, int mat> ...
;     ...
;   if (LORA) ISSUE_LORA(0, 0);
;   int l3 = 0;
;   for (int i = -2; i < nb; i += 2) {
;     PREP_ITER(0, 1);
;     ++i;
;     PREP_ITER(1, 0);
;     --i;
;   }
	v_add_f32_e32 v192, -1.0, v184
	v_fma_f32 v192, v8, v192, 1.0
	v_mul_f32_e32 v176, v208, v192
	v_add_f32_dpp v200, v200, v200 quad_perm:[1,0,3,2] row_mask:0xf bank_mask:0xf bound_ctrl:1
	v_add_f32_e32 v192, -1.0, v185
	v_fma_f32 v192, v9, v192, 1.0
	v_mul_f32_e32 v177, v209, v192
	v_add_f32_dpp v200, v200, v200 quad_perm:[2,3,0,1] row_mask:0xf bank_mask:0xf bound_ctrl:1
	v_add_f32_e32 v192, -1.0, v186
	v_fma_f32 v192, v10, v192, 1.0
	v_mul_f32_e32 v178, v210, v192
	v_add_f32_dpp v200, v200, v200 row_half_mirror row_mask:0xf bank_mask:0xf bound_ctrl:1
	v_add_f32_e32 v192, -1.0, v187
	v_fma_f32 v192, v11, v192, 1.0
	v_mul_f32_e32 v179, v211, v192
	v_add_f32_e32 v192, -1.0, v188
	v_fma_f32 v192, v12, v192, 1.0
	v_mul_f32_e32 v180, v212, v192
	v_add_f32_e32 v192, -1.0, v189
	v_fma_f32 v192, v13, v192, 1.0
	v_mul_f32_e32 v181, v213, v192
	v_add_f32_e32 v192, -1.0, v190
	v_fma_f32 v192, v14, v192, 1.0
	v_mul_f32_e32 v182, v214, v192
	v_add_f32_e32 v192, -1.0, v191
	v_fma_f32 v192, v15, v192, 1.0
	v_mul_f32_e32 v183, v215, v192
	v_max_f32_e32 v200, v200, v200
	v_max_f32_e32 v200, 0x179abe15, v200
	v_rsq_f32_e32 v201, v200
	v_mul_f32_e32 v192, v136, v176
	v_mul_f32_e32 v202, v16, v192
	v_mul_f32_e32 v160, v160, v201
	v_mul_f32_e32 v161, v161, v201
	v_mul_f32_e32 v162, v162, v201
	v_mul_f32_e32 v163, v163, v201
	v_mul_f32_e32 v164, v164, v201
	v_mul_f32_e32 v165, v165, v201
	v_mul_f32_e32 v166, v166, v201
	v_mul_f32_e32 v167, v167, v201
	v_mul_f32_e32 v168, v184, v160
	v_mul_f32_e32 v169, v185, v161
	v_mul_f32_e32 v170, v186, v162
	v_mul_f32_e32 v171, v187, v163
	v_mul_f32_e32 v172, v188, v164
	v_mul_f32_e32 v173, v189, v165
	v_mul_f32_e32 v174, v190, v166
	v_mul_f32_e32 v175, v191, v167
	ds_write_b128 v54, v[160:163] offset:20480
	ds_write_b128 v54, v[164:167] offset:20496
	ds_write_b128 v54, v[168:171] offset:20736
	ds_write_b128 v54, v[172:175] offset:20752
	ds_write_b128 v54, v[176:179] offset:20992
	ds_write_b128 v54, v[180:183] offset:21008
	ds_write_b128 v54, v[136:139] offset:21248
	ds_write_b128 v54, v[140:143] offset:21264
	ds_write_b128 v54, v[152:155] offset:21504
	ds_write_b128 v54, v[156:159] offset:21520
	v_mul_f32_e32 v192, v137, v177
	v_fmac_f32_e32 v202, v17, v192
	v_mul_f32_e32 v192, v138, v178
	v_fmac_f32_e32 v202, v18, v192
	v_mul_f32_e32 v192, v139, v179
	v_fmac_f32_e32 v202, v19, v192
	v_mul_f32_e32 v192, v140, v180
	v_fmac_f32_e32 v202, v20, v192
	v_mul_f32_e32 v192, v141, v181
	v_fmac_f32_e32 v202, v21, v192
	v_mul_f32_e32 v192, v142, v182
	v_fmac_f32_e32 v202, v22, v192
	v_mul_f32_e32 v192, v143, v183
	v_fmac_f32_e32 v202, v23, v192
	s_nop 1
	v_add_f32_dpp v202, v202, v202 quad_perm:[1,0,3,2] row_mask:0xf bank_mask:0xf bound_ctrl:1
	s_nop 1
	v_add_f32_dpp v202, v202, v202 quad_perm:[2,3,0,1] row_mask:0xf bank_mask:0xf bound_ctrl:1
	s_nop 1
	v_add_f32_dpp v202, v202, v202 row_half_mirror row_mask:0xf bank_mask:0xf bound_ctrl:1
	v_lshl_add_u32 v205, v56, 7, s60
	s_and_saveexec_b64 s[6:7], s[8:9]
	global_store_dword v205, v202, s[24:25]
	s_or_b64 exec, exec, s[6:7]
	v_mov_b32_e32 v56, v57
	s_waitcnt lgkmcnt(0)
	s_barrier
	s_add_i32 s66, s66, 1
	s_cmp_lt_u32 s66, 1025
	s_cbranch_scc1 .Lmy_k_loop
	s_waitcnt lgkmcnt(0)
	s_barrier

.LBB0_1283:
	s_add_i32 s67, s55, -2
	s_cmpk_lt_u32 s67, 0x400
	s_cselect_b64 s[8:9], -1, 0
	s_cmpk_gt_u32 s67, 0x3ff
	s_branch .LBB0_1285
	s_add_i32 s10, s57, 16
	s_add_i32 s11, s66, -16
	s_and_b64 s[6:7], s[0:1], exec
	s_cselect_b32 s6, s10, s11
	s_mulk_i32 s6, 0xe00
	s_add_i32 s10, s57, 17
	s_sub_i32 s11, s66, 17
	v_add_lshl_u32 v88, s6, v128, 1
	s_and_b64 s[6:7], s[0:1], exec
	s_cselect_b32 s6, s10, s11
	s_mulk_i32 s6, 0xe00
	s_add_i32 s10, s57, 18
	s_sub_i32 s11, s66, 18
	v_add_lshl_u32 v162, s6, v128, 1
	s_and_b64 s[6:7], s[0:1], exec
	s_cselect_b32 s6, s10, s11
	s_mulk_i32 s6, 0xe00
	v_add_u32_e32 v136, 0xffffe400, v88
	v_add_u32_e32 v139, 0x1c00, v88
	v_add_u32_e32 v132, 0xfffff800, v88
	v_add_u32_e32 v134, 0x800, v88
	v_add_u32_e32 v135, 0xffffdc00, v88
	v_add_u32_e32 v137, 0xffffec00, v88
	v_add_u32_e32 v138, 0x1400, v88
	v_add_lshl_u32 v172, s6, v128, 1
	global_load_ushort v132, v132, s[72:73]
	global_load_ushort v133, v88, s[72:73]
	global_load_ushort v134, v134, s[72:73]
	global_load_ushort v135, v135, s[72:73]
	global_load_ushort v136, v136, s[72:73]
	global_load_ushort v137, v137, s[72:73]
	global_load_ushort v138, v138, s[72:73]
	global_load_ushort v139, v139, s[72:73]
	v_add_u32_e32 v88, 0x2400, v88
	v_add_u32_e32 v154, 0xffffe400, v162
	v_add_u32_e32 v156, 0x1c00, v162
	v_add_u32_e32 v148, 0xfffff800, v162
	v_add_u32_e32 v152, 0x800, v162
	v_add_u32_e32 v153, 0xffffdc00, v162
	v_add_u32_e32 v155, 0xffffec00, v162
	v_add_u32_e32 v165, 0x1400, v162
	v_add_u32_e32 v171, 0xffffe400, v172
	v_add_u32_e32 v173, 0x1c00, v172
	v_add_u32_e32 v166, 0xfffff800, v172
	v_add_u32_e32 v169, 0x800, v172
	v_add_u32_e32 v170, 0xffffdc00, v172
	global_load_ushort v145, v88, s[72:73]
	global_load_ushort v148, v148, s[72:73]
	global_load_ushort v150, v162, s[72:73]
	global_load_ushort v152, v152, s[72:73]
	global_load_ushort v153, v153, s[72:73]
	global_load_ushort v154, v154, s[72:73]
	global_load_ushort v155, v155, s[72:73]
	global_load_ushort v156, v156, s[72:73]
	v_add_u32_e32 v88, 0x2400, v162
	global_load_ushort v162, v165, s[72:73]
	global_load_ushort v165, v88, s[72:73]
	global_load_ushort v166, v166, s[72:73]
	global_load_ushort v168, v172, s[72:73]
	global_load_ushort v169, v169, s[72:73]
	global_load_ushort v170, v170, s[72:73]
	global_load_ushort v171, v171, s[72:73]
	global_load_ushort v173, v173, s[72:73]
	v_add_u32_e32 v174, 0xffffec00, v172
	v_add_u32_e32 v175, 0x1400, v172
	v_add_u32_e32 v88, 0x2400, v172
	global_load_ushort v172, v174, s[72:73]
	global_load_ushort v174, v175, s[72:73]
	global_load_ushort v175, v88, s[72:73]

.Lmy_w5_skA:
	s_branch .LBB0_1300
	s_add_i32 s8, s55, -4
	v_cndmask_b32_e64 v88, 0, 1, s[14:15]
	s_cmp_lt_i32 s8, 0
	v_cmp_ne_u32_e64 s[8:9], 1, v88
	s_cbranch_scc1 .LBB0_1300
	s_and_b64 s[10:11], s[0:1], exec
	s_cselect_b32 s77, s57, s66
	s_cmpk_lt_u32 s77, 0x3fff
	s_cselect_b64 s[10:11], -1, 0
	v_cndmask_b32_e64 v190, 0, 1.0, s[10:11]
	v_lshlrev_b32_e32 v191, 16, v143
	v_lshlrev_b32_e32 v192, 16, v149
	v_lshlrev_b32_e32 v88, 16, v140
	v_fmac_f32_e32 v191, v190, v192
	v_fma_f32 v191, v191, 0.5, -v88
	v_lshlrev_b32_e32 v192, 16, v144
	v_lshlrev_b32_e32 v193, 16, v151
	v_fmac_f32_e32 v88, v123, v191
	v_lshlrev_b32_e32 v191, 16, v141
	v_fmac_f32_e32 v192, v190, v193
	v_fma_f32 v192, v192, 0.5, -v191
	v_lshlrev_b32_e32 v193, 16, v147
	v_lshlrev_b32_e32 v194, 16, v157
	v_fmac_f32_e32 v191, v124, v192
	v_lshlrev_b32_e32 v192, 16, v142
	v_fmac_f32_e32 v193, v190, v194
	v_fma_f32 v190, v193, 0.5, -v192
	v_mul_f32_e32 v194, v120, v191
	v_fmac_f32_e32 v192, v125, v190
	v_mul_f32_e32 v190, v194, v194
	v_mov_b32_e32 v195, 0
	ds_read_b32 v193, v129 offset:16640
	v_mov_b32_dpp v190, v190 quad_perm:[1,0,3,2] row_mask:0xf bank_mask:0xf bound_ctrl:1
	v_fmac_f32_e32 v190, v194, v194
	s_and_b64 vcc, exec, s[8:9]
	s_nop 0
	v_add_f32_dpp v190, v190, v190 quad_perm:[2,3,0,1] row_mask:0xf bank_mask:0xf bound_ctrl:1
	s_nop 1
	v_add_f32_dpp v190, v190, v190 row_half_mirror row_mask:0xf bank_mask:0xf bound_ctrl:1
	s_nop 1
	v_add_f32_dpp v190, v190, v190 row_mirror row_mask:0xf bank_mask:0xf bound_ctrl:1
	s_nop 1
	v_mov_b32_dpp v195, v190 row_bcast:15 row_mask:0xa bank_mask:0xf
	v_add_f32_e32 v190, v190, v195
	v_mov_b32_e32 v195, 0
	s_nop 1
	v_mov_b32_dpp v195, v190 row_bcast:31 row_mask:0xc bank_mask:0xf
	v_add_f32_e32 v190, v190, v195
	s_nop 0
	v_readlane_b32 s10, v190, 63
	s_nop 1
	v_max_f32_e64 v190, s10, s10
	v_max_f32_e32 v190, 0x179abe15, v190
	v_rsq_f32_e32 v195, v190
	s_waitcnt lgkmcnt(0)
	v_add_f32_e32 v190, -1.0, v193
	v_fma_f32 v190, v121, v190, 1.0
	v_mul_f32_e32 v190, v191, v190
	v_mul_f32_e32 v191, v194, v195
	v_mul_f32_e32 v193, v193, v191
	ds_write2st64_b32 v129, v191, v193 offset0:165 offset1:166
	ds_write2st64_b32 v129, v190, v88 offset0:167 offset1:168
	ds_write_b32 v129, v192 offset:43264
	s_cbranch_vccnz .LBB0_1292
	v_mul_f32_e32 v88, v88, v190
	v_mul_f32_e32 v190, v122, v88
	s_nop 1
	v_mov_b32_dpp v190, v190 quad_perm:[1,0,3,2] row_mask:0xf bank_mask:0xf bound_ctrl:1
	v_fmac_f32_e32 v190, v122, v88
	s_nop 1
	v_add_f32_dpp v88, v190, v190 quad_perm:[2,3,0,1] row_mask:0xf bank_mask:0xf bound_ctrl:1
	v_mov_b32_e32 v190, 0
	s_nop 0
	v_add_f32_dpp v88, v88, v88 row_half_mirror row_mask:0xf bank_mask:0xf bound_ctrl:1
	s_nop 1
	v_add_f32_dpp v88, v88, v88 row_mirror row_mask:0xf bank_mask:0xf bound_ctrl:1
	s_nop 1
	v_mov_b32_dpp v190, v88 row_bcast:15 row_mask:0xa bank_mask:0xf
	v_add_f32_e32 v88, v88, v190
	v_mov_b32_e32 v190, 0
	s_nop 1
	v_mov_b32_dpp v190, v88 row_bcast:31 row_mask:0xc bank_mask:0xf
	v_add_f32_e32 v88, v88, v190
	s_nop 0
	v_readlane_b32 s80, v88, 63
	s_and_saveexec_b64 s[10:11], s[4:5]
	s_cbranch_execz .LBB0_1291
	s_lshl_b32 s77, s77, 7
	s_add_i32 s77, s77, s60
	v_mov_b32_e32 v88, s77
	v_mov_b32_e32 v190, s80
	global_store_dword v88, v190, s[24:25]

.LBB0_1302:
	v_cndmask_b32_e64 v88, 0, 1, s[52:53]
	v_cmp_ne_u32_e64 s[10:11], 1, v88
	s_andn2_b64 vcc, exec, s[52:53]
	s_branch .LBB0_1304
	s_add_i32 s77, s57, 32
	s_sub_i32 s80, s66, 32
	s_and_b64 s[52:53], s[0:1], exec
	s_cselect_b32 s52, s77, s80
	s_mulk_i32 s52, 0xe00
	s_add_i32 s77, s57, 33
	s_sub_i32 s80, s66, 33
	v_add_lshl_u32 v88, s52, v128, 1
	s_and_b64 s[52:53], s[0:1], exec
	s_cselect_b32 s52, s77, s80
	s_mulk_i32 s52, 0xe00
	s_add_i32 s77, s57, 34
	s_sub_i32 s80, s66, 34
	v_add_lshl_u32 v176, s52, v128, 1
	s_and_b64 s[52:53], s[0:1], exec
	s_cselect_b32 s52, s77, s80
	s_mulk_i32 s52, 0xe00
	v_add_u32_e32 v144, 0xffffe400, v88
	v_add_u32_e32 v151, 0x1c00, v88
	v_add_u32_e32 v140, 0xfffff800, v88
	v_add_u32_e32 v142, 0x800, v88
	v_add_u32_e32 v143, 0xffffdc00, v88
	v_add_u32_e32 v147, 0xffffec00, v88
	v_add_u32_e32 v149, 0x1400, v88
	v_add_lshl_u32 v183, s52, v128, 1
	global_load_ushort v140, v140, s[72:73]
	global_load_ushort v141, v88, s[72:73]
	global_load_ushort v142, v142, s[72:73]
	global_load_ushort v143, v143, s[72:73]
	global_load_ushort v144, v144, s[72:73]
	global_load_ushort v147, v147, s[72:73]
	global_load_ushort v149, v149, s[72:73]
	global_load_ushort v151, v151, s[72:73]
	v_add_u32_e32 v88, 0x2400, v88
	v_add_u32_e32 v163, 0xffffe400, v176
	v_add_u32_e32 v167, 0x1c00, v176
	v_add_u32_e32 v158, 0xfffff800, v176
	v_add_u32_e32 v160, 0x800, v176
	v_add_u32_e32 v161, 0xffffdc00, v176
	v_add_u32_e32 v164, 0xffffec00, v176
	v_add_u32_e32 v177, 0x1400, v176
	v_add_u32_e32 v182, 0xffffe400, v183
	v_add_u32_e32 v184, 0x1c00, v183
	v_add_u32_e32 v178, 0xfffff800, v183
	v_add_u32_e32 v180, 0x800, v183
	v_add_u32_e32 v181, 0xffffdc00, v183
	global_load_ushort v157, v88, s[72:73]
	global_load_ushort v158, v158, s[72:73]
	global_load_ushort v159, v176, s[72:73]
	global_load_ushort v160, v160, s[72:73]
	global_load_ushort v161, v161, s[72:73]
	global_load_ushort v163, v163, s[72:73]
	global_load_ushort v164, v164, s[72:73]
	global_load_ushort v167, v167, s[72:73]
	v_add_u32_e32 v88, 0x2400, v176
	global_load_ushort v176, v177, s[72:73]
	global_load_ushort v177, v88, s[72:73]
	global_load_ushort v178, v178, s[72:73]
	global_load_ushort v179, v183, s[72:73]
	global_load_ushort v180, v180, s[72:73]
	global_load_ushort v181, v181, s[72:73]
	global_load_ushort v182, v182, s[72:73]
	global_load_ushort v184, v184, s[72:73]
	v_add_u32_e32 v185, 0xffffec00, v183
	v_add_u32_e32 v186, 0x1400, v183
	v_add_u32_e32 v88, 0x2400, v183
	global_load_ushort v183, v185, s[72:73]
	global_load_ushort v185, v186, s[72:73]
	global_load_ushort v186, v88, s[72:73]

.LBB0_1306:
	s_waitcnt vmcnt(0)
	s_branch .LBB0_1279
	s_and_b64 vcc, exec, s[6:7]
	s_cbranch_vccnz .LBB0_1279
	v_lshlrev_b32_e32 v98, 16, v135
	v_lshlrev_b32_e32 v99, 16, v138
	v_lshlrev_b32_e32 v88, 16, v132
	v_add_f32_e32 v98, v98, v99
	v_fma_f32 v98, v98, 0.5, -v88
	v_lshlrev_b32_e32 v99, 16, v136
	v_lshlrev_b32_e32 v100, 16, v139
	v_fmac_f32_e32 v88, v123, v98
	v_lshlrev_b32_e32 v98, 16, v133
	v_add_f32_e32 v99, v99, v100
	v_fma_f32 v99, v99, 0.5, -v98
	v_fmac_f32_e32 v98, v124, v99
	v_lshlrev_b32_e32 v100, 16, v137
	v_lshlrev_b32_e32 v101, 16, v145
	v_add_f32_e32 v100, v100, v101
	v_mul_f32_e32 v101, v120, v98
	v_mul_f32_e32 v102, v101, v101
	v_mov_b32_e32 v103, 0
	v_lshlrev_b32_e32 v99, 16, v134
	v_mov_b32_dpp v102, v102 quad_perm:[1,0,3,2] row_mask:0xf bank_mask:0xf bound_ctrl:1
	v_fmac_f32_e32 v102, v101, v101
	v_fma_f32 v100, v100, 0.5, -v99
	v_fmac_f32_e32 v99, v125, v100
	v_add_f32_dpp v102, v102, v102 quad_perm:[2,3,0,1] row_mask:0xf bank_mask:0xf bound_ctrl:1
	ds_read_b32 v100, v129 offset:12544
	s_and_b64 vcc, exec, s[8:9]
	v_add_f32_dpp v102, v102, v102 row_half_mirror row_mask:0xf bank_mask:0xf bound_ctrl:1
	s_nop 1
	v_add_f32_dpp v102, v102, v102 row_mirror row_mask:0xf bank_mask:0xf bound_ctrl:1
	s_nop 1
	v_mov_b32_dpp v103, v102 row_bcast:15 row_mask:0xa bank_mask:0xf
	v_add_f32_e32 v102, v102, v103
	v_mov_b32_e32 v103, 0
	s_nop 1
	v_mov_b32_dpp v103, v102 row_bcast:31 row_mask:0xc bank_mask:0xf
	v_add_f32_e32 v102, v102, v103
	s_waitcnt lgkmcnt(0)
	v_add_f32_e32 v103, -1.0, v100
	v_readlane_b32 s6, v102, 63
	v_fma_f32 v103, v121, v103, 1.0
	v_mul_f32_e32 v98, v98, v103
	v_max_f32_e64 v102, s6, s6
	v_max_f32_e32 v102, 0x179abe15, v102
	v_rsq_f32_e32 v102, v102
	s_nop 0
	v_mul_f32_e32 v101, v101, v102
	v_mul_f32_e32 v100, v100, v101
	ds_write2st64_b32 v129, v101, v100 offset0:85 offset1:86
	ds_write2st64_b32 v129, v98, v88 offset0:87 offset1:88
	ds_write_b32 v129, v99 offset:22784
	s_cbranch_vccnz .LBB0_1311
	v_mul_f32_e32 v88, v88, v98
	v_mul_f32_e32 v98, v122, v88
	s_nop 1
	v_mov_b32_dpp v98, v98 quad_perm:[1,0,3,2] row_mask:0xf bank_mask:0xf bound_ctrl:1
	v_fmac_f32_e32 v98, v122, v88
	s_nop 1
	v_add_f32_dpp v88, v98, v98 quad_perm:[2,3,0,1] row_mask:0xf bank_mask:0xf bound_ctrl:1
	v_mov_b32_e32 v98, 0
	s_nop 0
	v_add_f32_dpp v88, v88, v88 row_half_mirror row_mask:0xf bank_mask:0xf bound_ctrl:1
	s_nop 1
	v_add_f32_dpp v88, v88, v88 row_mirror row_mask:0xf bank_mask:0xf bound_ctrl:1
	s_nop 1
	v_mov_b32_dpp v98, v88 row_bcast:15 row_mask:0xa bank_mask:0xf
	v_add_f32_e32 v88, v88, v98
	v_mov_b32_e32 v98, 0
	s_nop 1
	v_mov_b32_dpp v98, v88 row_bcast:31 row_mask:0xc bank_mask:0xf
	v_add_f32_e32 v88, v88, v98
	s_nop 0
	v_readlane_b32 s8, v88, 63
	s_and_saveexec_b64 s[6:7], s[4:5]
	s_cbranch_execz .LBB0_1310
	s_add_i32 s9, s57, 16
	s_add_i32 s52, s66, -16
	s_and_b64 s[10:11], s[0:1], exec
	s_cselect_b32 s9, s9, s52
	s_lshl_b32 s9, s9, 7
	s_add_i32 s9, s9, s60
	v_mov_b32_e32 v88, s9
	v_mov_b32_e32 v98, s8
	global_store_dword v88, v98, s[24:25]

.LBB0_1326:
	s_add_i32 s44, s36, -2
	s_cmpk_lt_u32 s44, 0x400
	s_cselect_b64 s[8:9], -1, 0
	s_cmpk_gt_u32 s44, 0x3ff
	s_branch .LBB0_1328
	s_add_i32 s10, s40, 16
	s_add_i32 s11, s41, -16
	s_and_b64 s[6:7], s[0:1], exec
	s_cselect_b32 s6, s10, s11
	s_mul_i32 s7, s6, 0xe00
	s_cmp_eq_u32 s6, 0
	v_add_lshl_u32 v0, s7, v142, 1
	s_cselect_b32 s7, 0, 0xffffe400
	s_cmpk_lt_u32 s6, 0x3fff
	s_cselect_b32 s6, 0x1c00, 0
	v_add_u32_e32 v2, s7, v0
	v_add_u32_e32 v3, s6, v0
	v_add_u32_e32 v4, 0xfffff800, v0
	v_add_u32_e32 v5, 0x800, v0
	v_add_u32_e32 v102, 0xfffff800, v2
	v_add_u32_e32 v103, 0x800, v2
	v_add_u32_e32 v104, 0xfffff800, v3
	global_load_ushort v196, v4, s[72:73]
	global_load_ushort v197, v0, s[72:73]
	global_load_ushort v198, v5, s[72:73]
	global_load_ushort v199, v102, s[72:73]
	global_load_ushort v200, v2, s[72:73]
	global_load_ushort v201, v103, s[72:73]
	global_load_ushort v202, v104, s[72:73]
	global_load_ushort v203, v3, s[72:73]
	v_add_u32_e32 v2, 0x800, v3
	global_load_ushort v204, v2, s[72:73]

.Lmy_w4_skA:
.Lmy_w4_skR:
	s_branch .LBB0_1335
	s_add_i32 s8, s36, -4
	v_cndmask_b32_e64 v0, 0, 1, s[14:15]
	s_cmp_lt_i32 s8, 0
	v_cmp_ne_u32_e64 s[8:9], 1, v0
	s_cbranch_scc1 .LBB0_1335
	s_and_b64 s[10:11], s[0:1], exec
	s_cselect_b32 s45, s40, s41
	s_cmpk_lt_u32 s45, 0x3fff
	s_cselect_b64 s[10:11], -1, 0
	v_cndmask_b32_e64 v102, 0, 1.0, s[10:11]
	v_lshlrev_b32_e32 v103, 16, v8
	v_and_b32_e32 v104, 0xffff0000, v9
	v_and_b32_e32 v0, 0xffff0000, v6
	v_fmac_f32_e32 v103, v102, v104
	v_fma_f32 v103, v103, 0.5, -v0
	v_and_b32_e32 v104, 0xffff0000, v8
	v_lshlrev_b32_e32 v105, 16, v10
	v_fmac_f32_e32 v0, v137, v103
	v_lshlrev_b32_e32 v103, 16, v7
	v_fmac_f32_e32 v104, v102, v105
	v_fma_f32 v104, v104, 0.5, -v103
	v_lshlrev_b32_e32 v105, 16, v9
	v_and_b32_e32 v150, 0xffff0000, v10
	v_fmac_f32_e32 v103, v138, v104
	v_and_b32_e32 v104, 0xffff0000, v7
	v_fmac_f32_e32 v105, v102, v150
	v_fma_f32 v102, v105, 0.5, -v104
	v_mul_f32_e32 v105, v134, v103
	v_fmac_f32_e32 v104, v139, v102
	v_mul_f32_e32 v102, v105, v105
	v_mov_b32_e32 v151, 0
	ds_read_b32 v150, v145 offset:16384
	v_mov_b32_dpp v102, v102 quad_perm:[1,0,3,2] row_mask:0xf bank_mask:0xf bound_ctrl:1
	v_fmac_f32_e32 v102, v105, v105
	s_and_b64 vcc, exec, s[8:9]
	s_nop 0
	v_add_f32_dpp v102, v102, v102 quad_perm:[2,3,0,1] row_mask:0xf bank_mask:0xf bound_ctrl:1
	s_nop 1
	v_add_f32_dpp v102, v102, v102 row_half_mirror row_mask:0xf bank_mask:0xf bound_ctrl:1
	s_nop 1
	v_add_f32_dpp v102, v102, v102 row_mirror row_mask:0xf bank_mask:0xf bound_ctrl:1
	s_nop 1
	v_mov_b32_dpp v151, v102 row_bcast:15 row_mask:0xa bank_mask:0xf
	v_add_f32_e32 v102, v102, v151
	v_mov_b32_e32 v151, 0
	s_nop 1
	v_mov_b32_dpp v151, v102 row_bcast:31 row_mask:0xc bank_mask:0xf
	v_add_f32_e32 v102, v102, v151
	s_nop 0
	v_readlane_b32 s10, v102, 63
	s_nop 1
	v_max_f32_e64 v102, s10, s10
	v_max_f32_e32 v102, 0x179abe15, v102
	v_rsq_f32_e32 v151, v102
	s_waitcnt lgkmcnt(0)
	v_add_f32_e32 v102, -1.0, v150
	v_fma_f32 v102, v135, v102, 1.0
	v_mul_f32_e32 v102, v103, v102
	v_mul_f32_e32 v103, v105, v151
	v_mul_f32_e32 v105, v150, v103
	ds_write2st64_b32 v145, v103, v105 offset0:160 offset1:161
	ds_write2st64_b32 v145, v102, v0 offset0:162 offset1:163
	ds_write_b32 v145, v104 offset:41984
	s_cbranch_vccnz .LBB0_1335
	v_mul_f32_e32 v0, v0, v102
	v_mul_f32_e32 v102, v136, v0
	s_nop 1
	v_mov_b32_dpp v102, v102 quad_perm:[1,0,3,2] row_mask:0xf bank_mask:0xf bound_ctrl:1
	v_fmac_f32_e32 v102, v136, v0
	s_nop 1
	v_add_f32_dpp v0, v102, v102 quad_perm:[2,3,0,1] row_mask:0xf bank_mask:0xf bound_ctrl:1
	v_mov_b32_e32 v102, 0
	s_nop 0
	v_add_f32_dpp v0, v0, v0 row_half_mirror row_mask:0xf bank_mask:0xf bound_ctrl:1
	s_nop 1
	v_add_f32_dpp v0, v0, v0 row_mirror row_mask:0xf bank_mask:0xf bound_ctrl:1
	s_nop 1
	v_mov_b32_dpp v102, v0 row_bcast:15 row_mask:0xa bank_mask:0xf
	v_add_f32_e32 v0, v0, v102
	v_mov_b32_e32 v102, 0
	s_nop 1
	v_mov_b32_dpp v102, v0 row_bcast:31 row_mask:0xc bank_mask:0xf
	v_add_f32_e32 v0, v0, v102
	s_nop 0
	v_readlane_b32 s48, v0, 63
	s_and_saveexec_b64 s[10:11], s[4:5]
	s_cbranch_execz .LBB0_1334
	s_lshl_b32 s45, s45, 7
	s_add_i32 s45, s45, s60
	v_mov_b32_e32 v0, s45
	v_mov_b32_e32 v102, s48
	global_store_dword v0, v102, s[24:25]

.LBB0_1337:
	v_cndmask_b32_e64 v0, 0, 1, s[16:17]
	v_cmp_ne_u32_e64 s[10:11], 1, v0
	s_andn2_b64 vcc, exec, s[16:17]
	s_branch .LBB0_1339
	s_add_i32 s45, s40, 32
	s_sub_i32 s48, s41, 32
	s_and_b64 s[16:17], s[0:1], exec
	s_cselect_b32 s16, s45, s48
	s_mulk_i32 s16, 0xe00
	v_add_lshl_u32 v0, s16, v142, 1
	v_add_u32_e32 v8, 0x1c00, v0
	v_add_u32_e32 v9, 0x800, v0
	v_add_u32_e32 v10, 0xffffdc00, v0
	v_add_u32_e32 v102, 0xffffec00, v0
	v_add_u32_e32 v103, 0x1400, v0
	v_add_u32_e32 v7, 0xffffe400, v0
	global_load_ushort v196, v9, s[72:73]
	global_load_ushort v197, v10, s[72:73]
	global_load_ushort v198, v102, s[72:73]
	global_load_ushort v199, v103, s[72:73]
	global_load_ushort v200, v8, s[72:73]
	v_add_u32_e32 v10, 0x2400, v0
	v_add_u32_e32 v103, 0xfffff800, v0
	global_load_ushort v201, v10, s[72:73]
	global_load_ushort v202, v7, s[72:73]
	global_load_ushort v203, v0, s[72:73]
	global_load_ushort v204, v103, s[72:73]

.LBB0_1341:
	s_waitcnt vmcnt(0)
	s_branch .LBB0_1322
	s_and_b64 vcc, exec, s[6:7]
	s_cbranch_vccnz .LBB0_1322
	s_add_i32 s10, s40, 16
	s_add_i32 s11, s41, -16
	s_and_b64 s[6:7], s[0:1], exec
	s_cselect_b32 s10, s10, s11
	s_cmp_eq_u32 s10, 0
	s_cselect_b64 s[6:7], -1, 0
	s_cmpk_lt_u32 s10, 0x3fff
	v_cndmask_b32_e64 v11, 1.0, 0, s[6:7]
	s_cselect_b64 s[6:7], -1, 0
	v_cndmask_b32_e64 v102, 0, 1.0, s[6:7]
	v_lshlrev_b32_e32 v104, 16, v5
	v_and_b32_e32 v103, 0xffff0000, v3
	v_mul_f32_e32 v104, v102, v104
	v_lshlrev_b32_e32 v0, 16, v2
	v_fmac_f32_e32 v104, v11, v103
	v_and_b32_e32 v105, 0xffff0000, v5
	v_fma_f32 v103, v104, 0.5, -v0
	v_lshlrev_b32_e32 v104, 16, v4
	v_mul_f32_e32 v105, v102, v105
	v_fmac_f32_e32 v0, v137, v103
	v_and_b32_e32 v103, 0xffff0000, v2
	v_fmac_f32_e32 v105, v11, v104
	v_lshlrev_b32_e32 v112, 16, v6
	v_fma_f32 v104, v105, 0.5, -v103
	v_and_b32_e32 v105, 0xffff0000, v4
	v_mul_f32_e32 v102, v102, v112
	v_fmac_f32_e32 v103, v138, v104
	v_lshlrev_b32_e32 v104, 16, v3
	v_fmac_f32_e32 v102, v11, v105
	v_fma_f32 v11, v102, 0.5, -v104
	v_mul_f32_e32 v102, v134, v103
	v_fmac_f32_e32 v104, v139, v11
	v_mul_f32_e32 v11, v102, v102
	v_mov_b32_e32 v112, 0
	ds_read_b32 v105, v145 offset:12288
	v_mov_b32_dpp v11, v11 quad_perm:[1,0,3,2] row_mask:0xf bank_mask:0xf bound_ctrl:1
	v_fmac_f32_e32 v11, v102, v102
	s_and_b64 vcc, exec, s[8:9]
	s_nop 0
	v_add_f32_dpp v11, v11, v11 quad_perm:[2,3,0,1] row_mask:0xf bank_mask:0xf bound_ctrl:1
	s_nop 1
	v_add_f32_dpp v11, v11, v11 row_half_mirror row_mask:0xf bank_mask:0xf bound_ctrl:1
	s_nop 1
	v_add_f32_dpp v11, v11, v11 row_mirror row_mask:0xf bank_mask:0xf bound_ctrl:1
	s_nop 1
	v_mov_b32_dpp v112, v11 row_bcast:15 row_mask:0xa bank_mask:0xf
	v_add_f32_e32 v11, v11, v112
	v_mov_b32_e32 v112, 0
	s_nop 1
	v_mov_b32_dpp v112, v11 row_bcast:31 row_mask:0xc bank_mask:0xf
	v_add_f32_e32 v11, v11, v112
	s_nop 0
	v_readlane_b32 s6, v11, 63
	s_nop 1
	v_max_f32_e64 v11, s6, s6
	v_max_f32_e32 v11, 0x179abe15, v11
	v_rsq_f32_e32 v112, v11
	s_waitcnt lgkmcnt(0)
	v_add_f32_e32 v11, -1.0, v105
	v_fma_f32 v11, v135, v11, 1.0
	v_mul_f32_e32 v11, v103, v11
	v_mul_f32_e32 v102, v102, v112
	v_mul_f32_e32 v103, v105, v102
	ds_write2st64_b32 v145, v102, v103 offset0:80 offset1:81
	ds_write2st64_b32 v145, v11, v0 offset0:82 offset1:83
	ds_write_b32 v145, v104 offset:21504
	s_cbranch_vccnz .LBB0_1322
	v_mul_f32_e32 v0, v0, v11
	v_mul_f32_e32 v11, v136, v0
	s_nop 1
	v_mov_b32_dpp v11, v11 quad_perm:[1,0,3,2] row_mask:0xf bank_mask:0xf bound_ctrl:1
	v_fmac_f32_e32 v11, v136, v0
	s_nop 1
	v_add_f32_dpp v0, v11, v11 quad_perm:[2,3,0,1] row_mask:0xf bank_mask:0xf bound_ctrl:1
	v_mov_b32_e32 v11, 0
	s_nop 0
	v_add_f32_dpp v0, v0, v0 row_half_mirror row_mask:0xf bank_mask:0xf bound_ctrl:1
	s_nop 1
	v_add_f32_dpp v0, v0, v0 row_mirror row_mask:0xf bank_mask:0xf bound_ctrl:1
	s_nop 1
	v_mov_b32_dpp v11, v0 row_bcast:15 row_mask:0xa bank_mask:0xf
	v_add_f32_e32 v0, v0, v11
	v_mov_b32_e32 v11, 0
	s_nop 1
	v_mov_b32_dpp v11, v0 row_bcast:31 row_mask:0xc bank_mask:0xf
	v_add_f32_e32 v0, v0, v11
	s_nop 0
	v_readlane_b32 s8, v0, 63
	s_and_saveexec_b64 s[6:7], s[4:5]
	s_cbranch_execz .LBB0_1321
	s_lshl_b32 s9, s10, 7
	s_add_i32 s9, s9, s60
	v_mov_b32_e32 v0, s9
	v_mov_b32_e32 v11, s8
	global_store_dword v0, v11, s[24:25]
	s_branch .LBB0_1321

; template <int RG>
; __device__ __forceinline__ void scan_waves16(const Params& p, float* lds, const int T, const int dir, const int wave, const int lane,
;                                            const size_t tok0, const int head, const int row_base) {
;   const float* Wd = lds + LDS_WD; const float* F = lds + LDS_F;
;   const int rowl = lane >> 4, part = lane & 15, k0 = part * 4;
;   int rowi[RG]; f32x2_t S[RG][2];
; #pragma unroll
;   for (int g = 0; g < RG; ++g) { rowi[g] = row_base + g * 16 + wave * 4 + rowl; S[g][0] = S[g][1] = (f32x2_t){0.f, 0.f}; }
;   const int orow = row_base + (part & (RG - 1)) * 16 + wave * 4 + rowl;
;   char* const obase = dir == 0 ? (char*)(p.ws + OFF_YB) : (char*)(p.ws + OFF_OB);
;   const unsigned ostride = dir == 0 ? (unsigned)DM * 2u : 2048u;
;   const unsigned ooff0 = dir == 0 ? ((unsigned)tok0 * (unsigned)DM + 1024u + (unsigned)(64 * head + orow)) * 2u
;                                   : ((unsigned)tok0 * 1024u + (unsigned)(64 * head + orow)) * 2u;
;   const int nb = T / 16; int i3 = 0;
.LBB0_1346:
	s_andn2_saveexec_b64 s[4:5], s[46:47]
	s_cbranch_execz .LBB0_1353
	s_brev_b32 s8, 48
	s_and_b64 s[6:7], s[0:1], exec
	s_cselect_b32 s6, s8, 0x1a900400
	s_add_u32 s6, s74, s6
	s_addc_u32 s7, s75, 0
	s_lshl_b32 s13, s59, 7
	s_add_i32 s14, s13, 0x800
	s_movk_i32 s11, 0x1000
	s_and_b64 s[8:9], s[0:1], exec
	s_cselect_b32 s11, s11, 0xfffff800
	s_sub_i32 s12, 12, s58
	s_waitcnt vmcnt(5)
	v_lshrrev_b32_e32 v0, 4, v148
	s_and_b64 s[8:9], s[0:1], exec
	v_lshl_or_b32 v0, s3, 4, v0
	s_cselect_b32 s8, s14, s13
	s_waitcnt vmcnt(4)
	v_and_b32_e32 v1, 15, v140
	s_waitcnt vmcnt(0)
	v_lshl_add_u32 v5, v6, 2, v0
	v_mov_b32_e32 v0, 0
	s_mov_b32 s10, 0
	v_lshlrev_b32_e32 v4, 2, v1
	v_lshl_add_u32 v6, v5, 1, s8
	v_lshl_add_u32 v7, v1, 4, 0
	v_cmp_eq_u32_e32 vcc, 0, v1
	s_mov_b32 s3, -2
	s_movk_i32 s13, 0xffe0
	s_movk_i32 s14, 0x401f
	s_movk_i32 s15, 0x7fff
	v_mov_b32_e32 v1, v0
	v_mov_b32_e32 v2, v0
	v_mov_b32_e32 v3, v0
	v_lshrrev_b32_e32 v8, 2, v4
	v_and_b32_e32 v9, 8, v4
	v_and_b32_e32 v13, 4, v4
	v_mul_lo_u32 v8, v8, s11
	s_branch .LBB0_1350

; template <int RG>
; __device__ __forceinline__ void scan_waves16(const Params& p, float* lds, const int T, const int dir, const int wave, const int lane,
;                                            const size_t tok0, const int head, const int row_base) {
;     ...
;       }
;       i3 = (i3 == 2) ? 0 : i3 + 1;
;     }
;     lds_barrier();
.Lmy_sw_next:
	s_add_i32 s8, s10, 1
	s_cmp_lg_u32 s10, 2
	s_cselect_b32 s10, s8, 0

; __device__ __forceinline__ float row16_sum(float x) { x = red8_sum(x); x += dpp_f<0x140>(x); return x; }
; template <int RG>
; __device__ __forceinline__ void scan_waves16(const Params& p, float* lds, const int T, const int dir, const int wave, const int lane,
;                                            const size_t tok0, const int head, const int row_base) {
;     ...
;       LD16(0, 0);
; #pragma unroll
;       for (int st = 0; st < 16; ++st) {
;         const int B = st & 1;
;         if (st + 1 < 16) LD16(1 - B, st + 1);
;         asm volatile("" ::: "memory");
;         float sa[RG], o[RG];
; #pragma unroll
;         for (int g = 0; g < RG; ++g) {
;           const f32x2_t a0 = __builtin_elementwise_fma(S[g][1], kk[B][1], S[g][0] * kk[B][0]);
;           sa[g] = a0.x + a0.y;
;         }
; #pragma unroll
;         for (int g = 0; g < RG; ++g) sa[g] = -row16_sum(sa[g]);
; #pragma unroll
;         for (int g = 0; g < RG; ++g) {
;           const f32x2_t sav = {sa[g], sa[g]}, vvv = {vv[B][g], vv[B][g]};
;           S[g][0] = __builtin_elementwise_fma(vvv, kd[B][0], __builtin_elementwise_fma(sav, qa[B][0], S[g][0] * w[B][0]));
;           S[g][1] = __builtin_elementwise_fma(vvv, kd[B][1], __builtin_elementwise_fma(sav, qa[B][1], S[g][1] * w[B][1]));
;         }
; #pragma unroll
;         for (int g = 0; g < RG; ++g) {
;           const f32x2_t a0 = __builtin_elementwise_fma(S[g][1], r[B][1], S[g][0] * r[B][0]);
;           o[g] = a0.x + a0.y;
;         }
; #pragma unroll
;         for (int g = 0; g < RG; ++g) o[g] = row16_sum(o[g]);
;         float os = o[0];
; #pragma unroll
;         for (int g = 1; g < RG; ++g) os = (part == g) ? o[g] : os;
;         osv[st] = os;
;       }
.LBB0_1350:
	s_cmp_lt_i32 s3, 0
	s_cbranch_scc1 .LBB0_1349
	s_bitcmp1_b32 s3, 0
	s_cselect_b32 s8, 0x5000, 0
	v_lshl_add_u32 v10, v4, 2, s8
	v_lshl_add_u32 v11, s10, 12, v7
	v_lshl_add_u32 v12, v5, 2, s8
	ds_read_b128 v[20:23], v10 offset:20480
	ds_read_b128 v[16:19], v11
	ds_read_b128 v[28:31], v10 offset:20992
	ds_read_b32 v36, v12 offset:21504
	ds_read_b128 v[24:27], v10 offset:20736
	ds_read_b128 v[32:35], v10 offset:21248
	s_waitcnt lgkmcnt(0)
	ds_read_b128 v[44:47], v10 offset:21760
	ds_read_b128 v[40:43], v11 offset:256
	ds_read_b128 v[52:55], v10 offset:22272
	ds_read_b32 v60, v12 offset:22784
	ds_read_b128 v[48:51], v10 offset:22016
	ds_read_b128 v[56:59], v10 offset:22528
	v_pk_mul_f32 v[80:81], v[0:1], v[20:21]
	v_pk_fma_f32 v[80:81], v[2:3], v[22:23], v[80:81]
	v_add_f32_e32 v82, v80, v81
	v_pk_mul_f32 v[84:85], v[0:1], v[16:17]
	v_pk_mul_f32 v[86:87], v[2:3], v[18:19]
	v_add_f32_dpp v82, v82, v82 quad_perm:[1,0,3,2] row_mask:0xf bank_mask:0xf bound_ctrl:1
	v_pk_fma_f32 v[84:85], v[36:37], v[28:29], v[84:85] op_sel_hi:[0,1,1]
	v_pk_fma_f32 v[86:87], v[36:37], v[30:31], v[86:87] op_sel_hi:[0,1,1]
	v_add_f32_dpp v82, v82, v82 quad_perm:[2,3,0,1] row_mask:0xf bank_mask:0xf bound_ctrl:1
	s_nop 1
	v_add_f32_dpp v82, v82, v82 row_half_mirror row_mask:0xf bank_mask:0xf bound_ctrl:1
	s_nop 1
	v_add_f32_dpp v82, v82, v82 row_mirror row_mask:0xf bank_mask:0xf bound_ctrl:1
	v_pk_fma_f32 v[0:1], v[82:83], v[24:25], v[84:85] op_sel_hi:[0,1,1] neg_lo:[1,0,0] neg_hi:[1,0,0]
	v_pk_fma_f32 v[2:3], v[82:83], v[26:27], v[86:87] op_sel_hi:[0,1,1] neg_lo:[1,0,0] neg_hi:[1,0,0]
	s_waitcnt lgkmcnt(0)
	ds_read_b128 v[20:23], v10 offset:23040
	ds_read_b128 v[16:19], v11 offset:512
	ds_read_b128 v[28:31], v10 offset:23552
	ds_read_b32 v36, v12 offset:24064
	ds_read_b128 v[24:27], v10 offset:23296
	ds_read_b128 v[96:99], v10 offset:23808
	v_pk_mul_f32 v[80:81], v[0:1], v[44:45]
	v_pk_fma_f32 v[80:81], v[2:3], v[46:47], v[80:81]
	v_add_f32_e32 v82, v80, v81
	v_pk_mul_f32 v[84:85], v[0:1], v[40:41]
	v_pk_mul_f32 v[86:87], v[2:3], v[42:43]
	v_add_f32_dpp v82, v82, v82 quad_perm:[1,0,3,2] row_mask:0xf bank_mask:0xf bound_ctrl:1
	v_pk_fma_f32 v[84:85], v[60:61], v[52:53], v[84:85] op_sel_hi:[0,1,1]
	v_pk_fma_f32 v[86:87], v[60:61], v[54:55], v[86:87] op_sel_hi:[0,1,1]
	v_add_f32_dpp v82, v82, v82 quad_perm:[2,3,0,1] row_mask:0xf bank_mask:0xf bound_ctrl:1
	v_pk_mul_f32 v[88:89], v[0:1], v[32:33]
	v_pk_fma_f32 v[88:89], v[2:3], v[34:35], v[88:89]
	v_add_f32_dpp v82, v82, v82 row_half_mirror row_mask:0xf bank_mask:0xf bound_ctrl:1
	v_add_f32_e32 v64, v88, v89
	s_nop 0
	v_add_f32_dpp v82, v82, v82 row_mirror row_mask:0xf bank_mask:0xf bound_ctrl:1
	v_pk_fma_f32 v[0:1], v[82:83], v[48:49], v[84:85] op_sel_hi:[0,1,1] neg_lo:[1,0,0] neg_hi:[1,0,0]
	v_pk_fma_f32 v[2:3], v[82:83], v[50:51], v[86:87] op_sel_hi:[0,1,1] neg_lo:[1,0,0] neg_hi:[1,0,0]
	s_waitcnt lgkmcnt(0)
	ds_read_b128 v[44:47], v10 offset:24320
	ds_read_b128 v[40:43], v11 offset:768
	ds_read_b128 v[52:55], v10 offset:24832
	ds_read_b32 v60, v12 offset:25344
	ds_read_b128 v[48:51], v10 offset:24576
	ds_read_b128 v[32:35], v10 offset:25088
	v_pk_mul_f32 v[80:81], v[0:1], v[20:21]
	v_pk_fma_f32 v[80:81], v[2:3], v[22:23], v[80:81]
	v_add_f32_e32 v82, v80, v81
	v_pk_mul_f32 v[84:85], v[0:1], v[16:17]
	v_pk_mul_f32 v[86:87], v[2:3], v[18:19]
	v_add_f32_dpp v82, v82, v82 quad_perm:[1,0,3,2] row_mask:0xf bank_mask:0xf bound_ctrl:1
	v_pk_fma_f32 v[84:85], v[36:37], v[28:29], v[84:85] op_sel_hi:[0,1,1]
	v_pk_fma_f32 v[86:87], v[36:37], v[30:31], v[86:87] op_sel_hi:[0,1,1]
	v_add_f32_dpp v82, v82, v82 quad_perm:[2,3,0,1] row_mask:0xf bank_mask:0xf bound_ctrl:1
	v_pk_mul_f32 v[88:89], v[0:1], v[56:57]
	v_pk_fma_f32 v[88:89], v[2:3], v[58:59], v[88:89]
	v_add_f32_dpp v82, v82, v82 row_half_mirror row_mask:0xf bank_mask:0xf bound_ctrl:1
	v_add_f32_e32 v65, v88, v89
	s_nop 0
	v_add_f32_dpp v82, v82, v82 row_mirror row_mask:0xf bank_mask:0xf bound_ctrl:1
	v_pk_fma_f32 v[0:1], v[82:83], v[24:25], v[84:85] op_sel_hi:[0,1,1] neg_lo:[1,0,0] neg_hi:[1,0,0]
	v_pk_fma_f32 v[2:3], v[82:83], v[26:27], v[86:87] op_sel_hi:[0,1,1] neg_lo:[1,0,0] neg_hi:[1,0,0]
	s_waitcnt lgkmcnt(0)
	ds_read_b128 v[20:23], v10 offset:25600
	ds_read_b128 v[16:19], v11 offset:1024
	ds_read_b128 v[28:31], v10 offset:26112
	ds_read_b32 v36, v12 offset:26624
	ds_read_b128 v[24:27], v10 offset:25856
	ds_read_b128 v[56:59], v10 offset:26368
	v_pk_mul_f32 v[80:81], v[0:1], v[44:45]
	v_pk_fma_f32 v[80:81], v[2:3], v[46:47], v[80:81]
	v_add_f32_e32 v82, v80, v81
	v_pk_mul_f32 v[84:85], v[0:1], v[40:41]
	v_pk_mul_f32 v[86:87], v[2:3], v[42:43]
	v_add_f32_dpp v82, v82, v82 quad_perm:[1,0,3,2] row_mask:0xf bank_mask:0xf bound_ctrl:1
	v_pk_fma_f32 v[84:85], v[60:61], v[52:53], v[84:85] op_sel_hi:[0,1,1]
	v_pk_fma_f32 v[86:87], v[60:61], v[54:55], v[86:87] op_sel_hi:[0,1,1]
	v_add_f32_dpp v82, v82, v82 quad_perm:[2,3,0,1] row_mask:0xf bank_mask:0xf bound_ctrl:1
	v_pk_mul_f32 v[88:89], v[0:1], v[96:97]
	v_pk_fma_f32 v[88:89], v[2:3], v[98:99], v[88:89]
	v_add_f32_dpp v82, v82, v82 row_half_mirror row_mask:0xf bank_mask:0xf bound_ctrl:1
	v_add_f32_e32 v66, v88, v89
	s_nop 0
	v_add_f32_dpp v82, v82, v82 row_mirror row_mask:0xf bank_mask:0xf bound_ctrl:1
	v_pk_fma_f32 v[0:1], v[82:83], v[48:49], v[84:85] op_sel_hi:[0,1,1] neg_lo:[1,0,0] neg_hi:[1,0,0]
	v_pk_fma_f32 v[2:3], v[82:83], v[50:51], v[86:87] op_sel_hi:[0,1,1] neg_lo:[1,0,0] neg_hi:[1,0,0]
	s_waitcnt lgkmcnt(0)
; __device__ __forceinline__ float row16_sum(float x) { x = red8_sum(x); x += dpp_f<0x140>(x); return x; }
; template <int RG>
; __device__ __forceinline__ void scan_waves16(const Params& p, float* lds, const int T, const int dir, const int wave, const int lane,
;                                            const size_t tok0, const int head, const int row_base) {
;     ...
;       for (int st = 0; st < 16; ++st) {
;         const int B = st & 1;
;         if (st + 1 < 16) LD16(1 - B, st + 1);
;         asm volatile("" ::: "memory");
;         float sa[RG], o[RG];
; #pragma unroll
;         for (int g = 0; g < RG; ++g) {
;           const f32x2_t a0 = __builtin_elementwise_fma(S[g][1], kk[B][1], S[g][0] * kk[B][0]);
;           sa[g] = a0.x + a0.y;
;         }
; #pragma unroll
;         for (int g = 0; g < RG; ++g) sa[g] = -row16_sum(sa[g]);
; #pragma unroll
;         for (int g = 0; g < RG; ++g) {
;           const f32x2_t sav = {sa[g], sa[g]}, vvv = {vv[B][g], vv[B][g]};
;           S[g][0] = __builtin_elementwise_fma(vvv, kd[B][0], __builtin_elementwise_fma(sav, qa[B][0], S[g][0] * w[B][0]));
;           S[g][1] = __builtin_elementwise_fma(vvv, kd[B][1], __builtin_elementwise_fma(sav, qa[B][1], S[g][1] * w[B][1]));
;         }
; #pragma unroll
;         for (int g = 0; g < RG; ++g) {
;           const f32x2_t a0 = __builtin_elementwise_fma(S[g][1], r[B][1], S[g][0] * r[B][0]);
;           o[g] = a0.x + a0.y;
;         }
; #pragma unroll
;         for (int g = 0; g < RG; ++g) o[g] = row16_sum(o[g]);
;         float os = o[0];
; #pragma unroll
;         for (int g = 1; g < RG; ++g) os = (part == g) ? o[g] : os;
;         osv[st] = os;
;       }
	ds_read_b128 v[44:47], v10 offset:26880
	ds_read_b128 v[40:43], v11 offset:1280
	ds_read_b128 v[52:55], v10 offset:27392
	ds_read_b32 v60, v12 offset:27904
	ds_read_b128 v[48:51], v10 offset:27136
	ds_read_b128 v[96:99], v10 offset:27648
	v_pk_mul_f32 v[80:81], v[0:1], v[20:21]
	v_pk_fma_f32 v[80:81], v[2:3], v[22:23], v[80:81]
	v_add_f32_e32 v82, v80, v81
	v_pk_mul_f32 v[84:85], v[0:1], v[16:17]
	v_pk_mul_f32 v[86:87], v[2:3], v[18:19]
	v_add_f32_dpp v82, v82, v82 quad_perm:[1,0,3,2] row_mask:0xf bank_mask:0xf bound_ctrl:1
	v_pk_fma_f32 v[84:85], v[36:37], v[28:29], v[84:85] op_sel_hi:[0,1,1]
	v_pk_fma_f32 v[86:87], v[36:37], v[30:31], v[86:87] op_sel_hi:[0,1,1]
	v_add_f32_dpp v82, v82, v82 quad_perm:[2,3,0,1] row_mask:0xf bank_mask:0xf bound_ctrl:1
	v_pk_mul_f32 v[88:89], v[0:1], v[32:33]
	v_pk_fma_f32 v[88:89], v[2:3], v[34:35], v[88:89]
	v_add_f32_dpp v82, v82, v82 row_half_mirror row_mask:0xf bank_mask:0xf bound_ctrl:1
	v_add_f32_e32 v67, v88, v89
	s_nop 0
	v_add_f32_dpp v82, v82, v82 row_mirror row_mask:0xf bank_mask:0xf bound_ctrl:1
	v_pk_fma_f32 v[0:1], v[82:83], v[24:25], v[84:85] op_sel_hi:[0,1,1] neg_lo:[1,0,0] neg_hi:[1,0,0]
	v_pk_fma_f32 v[2:3], v[82:83], v[26:27], v[86:87] op_sel_hi:[0,1,1] neg_lo:[1,0,0] neg_hi:[1,0,0]
	s_waitcnt lgkmcnt(0)
	ds_read_b128 v[20:23], v10 offset:28160
	ds_read_b128 v[16:19], v11 offset:1536
	ds_read_b128 v[28:31], v10 offset:28672
	ds_read_b32 v36, v12 offset:29184
	ds_read_b128 v[24:27], v10 offset:28416
	ds_read_b128 v[32:35], v10 offset:28928
	v_pk_mul_f32 v[80:81], v[0:1], v[44:45]
	v_pk_fma_f32 v[80:81], v[2:3], v[46:47], v[80:81]
	v_add_f32_e32 v82, v80, v81
	v_pk_mul_f32 v[84:85], v[0:1], v[40:41]
	v_pk_mul_f32 v[86:87], v[2:3], v[42:43]
	v_add_f32_dpp v82, v82, v82 quad_perm:[1,0,3,2] row_mask:0xf bank_mask:0xf bound_ctrl:1
	v_pk_fma_f32 v[84:85], v[60:61], v[52:53], v[84:85] op_sel_hi:[0,1,1]
	v_pk_fma_f32 v[86:87], v[60:61], v[54:55], v[86:87] op_sel_hi:[0,1,1]
	v_add_f32_dpp v82, v82, v82 quad_perm:[2,3,0,1] row_mask:0xf bank_mask:0xf bound_ctrl:1
	v_pk_mul_f32 v[88:89], v[0:1], v[56:57]
	v_pk_fma_f32 v[88:89], v[2:3], v[58:59], v[88:89]
	v_add_f32_dpp v82, v82, v82 row_half_mirror row_mask:0xf bank_mask:0xf bound_ctrl:1
	v_add_f32_e32 v68, v88, v89
	s_nop 0
	v_add_f32_dpp v82, v82, v82 row_mirror row_mask:0xf bank_mask:0xf bound_ctrl:1
	v_pk_fma_f32 v[0:1], v[82:83], v[48:49], v[84:85] op_sel_hi:[0,1,1] neg_lo:[1,0,0] neg_hi:[1,0,0]
	v_pk_fma_f32 v[2:3], v[82:83], v[50:51], v[86:87] op_sel_hi:[0,1,1] neg_lo:[1,0,0] neg_hi:[1,0,0]
	s_waitcnt lgkmcnt(0)
	ds_read_b128 v[44:47], v10 offset:29440
	ds_read_b128 v[40:43], v11 offset:1792
	ds_read_b128 v[52:55], v10 offset:29952
	ds_read_b32 v60, v12 offset:30464
	ds_read_b128 v[48:51], v10 offset:29696
	ds_read_b128 v[56:59], v10 offset:30208
	v_pk_mul_f32 v[80:81], v[0:1], v[20:21]
	v_pk_fma_f32 v[80:81], v[2:3], v[22:23], v[80:81]
	v_add_f32_e32 v82, v80, v81
	v_pk_mul_f32 v[84:85], v[0:1], v[16:17]
	v_pk_mul_f32 v[86:87], v[2:3], v[18:19]
	v_add_f32_dpp v82, v82, v82 quad_perm:[1,0,3,2] row_mask:0xf bank_mask:0xf bound_ctrl:1
	v_pk_fma_f32 v[84:85], v[36:37], v[28:29], v[84:85] op_sel_hi:[0,1,1]
	v_pk_fma_f32 v[86:87], v[36:37], v[30:31], v[86:87] op_sel_hi:[0,1,1]
	v_add_f32_dpp v82, v82, v82 quad_perm:[2,3,0,1] row_mask:0xf bank_mask:0xf bound_ctrl:1
	v_pk_mul_f32 v[88:89], v[0:1], v[96:97]
	v_pk_fma_f32 v[88:89], v[2:3], v[98:99], v[88:89]
	v_add_f32_dpp v82, v82, v82 row_half_mirror row_mask:0xf bank_mask:0xf bound_ctrl:1
	v_add_f32_e32 v69, v88, v89
	s_nop 0
	v_add_f32_dpp v82, v82, v82 row_mirror row_mask:0xf bank_mask:0xf bound_ctrl:1
	v_pk_fma_f32 v[0:1], v[82:83], v[24:25], v[84:85] op_sel_hi:[0,1,1] neg_lo:[1,0,0] neg_hi:[1,0,0]
	v_pk_fma_f32 v[2:3], v[82:83], v[26:27], v[86:87] op_sel_hi:[0,1,1] neg_lo:[1,0,0] neg_hi:[1,0,0]
	s_waitcnt lgkmcnt(0)
	ds_read_b128 v[20:23], v10 offset:30720
	ds_read_b128 v[16:19], v11 offset:2048
	ds_read_b128 v[28:31], v10 offset:31232
	ds_read_b32 v36, v12 offset:31744
	ds_read_b128 v[24:27], v10 offset:30976
	ds_read_b128 v[96:99], v10 offset:31488
	v_pk_mul_f32 v[80:81], v[0:1], v[44:45]
	v_pk_fma_f32 v[80:81], v[2:3], v[46:47], v[80:81]
	v_add_f32_e32 v82, v80, v81
	v_pk_mul_f32 v[84:85], v[0:1], v[40:41]
	v_pk_mul_f32 v[86:87], v[2:3], v[42:43]
	v_add_f32_dpp v82, v82, v82 quad_perm:[1,0,3,2] row_mask:0xf bank_mask:0xf bound_ctrl:1
	v_pk_fma_f32 v[84:85], v[60:61], v[52:53], v[84:85] op_sel_hi:[0,1,1]
	v_pk_fma_f32 v[86:87], v[60:61], v[54:55], v[86:87] op_sel_hi:[0,1,1]
	v_add_f32_dpp v82, v82, v82 quad_perm:[2,3,0,1] row_mask:0xf bank_mask:0xf bound_ctrl:1
	v_pk_mul_f32 v[88:89], v[0:1], v[32:33]
	v_pk_fma_f32 v[88:89], v[2:3], v[34:35], v[88:89]
	v_add_f32_dpp v82, v82, v82 row_half_mirror row_mask:0xf bank_mask:0xf bound_ctrl:1
	v_add_f32_e32 v70, v88, v89
	s_nop 0
	v_add_f32_dpp v82, v82, v82 row_mirror row_mask:0xf bank_mask:0xf bound_ctrl:1
	v_pk_fma_f32 v[0:1], v[82:83], v[48:49], v[84:85] op_sel_hi:[0,1,1] neg_lo:[1,0,0] neg_hi:[1,0,0]
	v_pk_fma_f32 v[2:3], v[82:83], v[50:51], v[86:87] op_sel_hi:[0,1,1] neg_lo:[1,0,0] neg_hi:[1,0,0]
	s_waitcnt lgkmcnt(0)
; __device__ __forceinline__ float row16_sum(float x) { x = red8_sum(x); x += dpp_f<0x140>(x); return x; }
; template <int RG>
; __device__ __forceinline__ void scan_waves16(const Params& p, float* lds, const int T, const int dir, const int wave, const int lane,
;                                            const size_t tok0, const int head, const int row_base) {
;     ...
;       for (int st = 0; st < 16; ++st) {
;         const int B = st & 1;
;         if (st + 1 < 16) LD16(1 - B, st + 1);
;         asm volatile("" ::: "memory");
;         float sa[RG], o[RG];
; #pragma unroll
;         for (int g = 0; g < RG; ++g) {
;           const f32x2_t a0 = __builtin_elementwise_fma(S[g][1], kk[B][1], S[g][0] * kk[B][0]);
;           sa[g] = a0.x + a0.y;
;         }
; #pragma unroll
;         for (int g = 0; g < RG; ++g) sa[g] = -row16_sum(sa[g]);
; #pragma unroll
;         for (int g = 0; g < RG; ++g) {
;           const f32x2_t sav = {sa[g], sa[g]}, vvv = {vv[B][g], vv[B][g]};
;           S[g][0] = __builtin_elementwise_fma(vvv, kd[B][0], __builtin_elementwise_fma(sav, qa[B][0], S[g][0] * w[B][0]));
;           S[g][1] = __builtin_elementwise_fma(vvv, kd[B][1], __builtin_elementwise_fma(sav, qa[B][1], S[g][1] * w[B][1]));
;         }
; #pragma unroll
;         for (int g = 0; g < RG; ++g) {
;           const f32x2_t a0 = __builtin_elementwise_fma(S[g][1], r[B][1], S[g][0] * r[B][0]);
;           o[g] = a0.x + a0.y;
;         }
; #pragma unroll
;         for (int g = 0; g < RG; ++g) o[g] = row16_sum(o[g]);
;         float os = o[0];
; #pragma unroll
;         for (int g = 1; g < RG; ++g) os = (part == g) ? o[g] : os;
;         osv[st] = os;
;       }
	ds_read_b128 v[44:47], v10 offset:32000
	ds_read_b128 v[40:43], v11 offset:2304
	ds_read_b128 v[52:55], v10 offset:32512
	ds_read_b32 v60, v12 offset:33024
	ds_read_b128 v[48:51], v10 offset:32256
	ds_read_b128 v[32:35], v10 offset:32768
	v_pk_mul_f32 v[80:81], v[0:1], v[20:21]
	v_pk_fma_f32 v[80:81], v[2:3], v[22:23], v[80:81]
	v_add_f32_e32 v82, v80, v81
	v_pk_mul_f32 v[84:85], v[0:1], v[16:17]
	v_pk_mul_f32 v[86:87], v[2:3], v[18:19]
	v_add_f32_dpp v82, v82, v82 quad_perm:[1,0,3,2] row_mask:0xf bank_mask:0xf bound_ctrl:1
	v_pk_fma_f32 v[84:85], v[36:37], v[28:29], v[84:85] op_sel_hi:[0,1,1]
	v_pk_fma_f32 v[86:87], v[36:37], v[30:31], v[86:87] op_sel_hi:[0,1,1]
	v_add_f32_dpp v82, v82, v82 quad_perm:[2,3,0,1] row_mask:0xf bank_mask:0xf bound_ctrl:1
	v_pk_mul_f32 v[88:89], v[0:1], v[56:57]
	v_pk_fma_f32 v[88:89], v[2:3], v[58:59], v[88:89]
	v_add_f32_dpp v82, v82, v82 row_half_mirror row_mask:0xf bank_mask:0xf bound_ctrl:1
	v_add_f32_e32 v71, v88, v89
	s_nop 0
	v_add_f32_dpp v82, v82, v82 row_mirror row_mask:0xf bank_mask:0xf bound_ctrl:1
	v_pk_fma_f32 v[0:1], v[82:83], v[24:25], v[84:85] op_sel_hi:[0,1,1] neg_lo:[1,0,0] neg_hi:[1,0,0]
	v_pk_fma_f32 v[2:3], v[82:83], v[26:27], v[86:87] op_sel_hi:[0,1,1] neg_lo:[1,0,0] neg_hi:[1,0,0]
	s_waitcnt lgkmcnt(0)
	ds_read_b128 v[20:23], v10 offset:33280
	ds_read_b128 v[16:19], v11 offset:2560
	ds_read_b128 v[28:31], v10 offset:33792
	ds_read_b32 v36, v12 offset:34304
	ds_read_b128 v[24:27], v10 offset:33536
	ds_read_b128 v[56:59], v10 offset:34048
	v_pk_mul_f32 v[80:81], v[0:1], v[44:45]
	v_pk_fma_f32 v[80:81], v[2:3], v[46:47], v[80:81]
	v_add_f32_e32 v82, v80, v81
	v_pk_mul_f32 v[84:85], v[0:1], v[40:41]
	v_pk_mul_f32 v[86:87], v[2:3], v[42:43]
	v_add_f32_dpp v82, v82, v82 quad_perm:[1,0,3,2] row_mask:0xf bank_mask:0xf bound_ctrl:1
	v_pk_fma_f32 v[84:85], v[60:61], v[52:53], v[84:85] op_sel_hi:[0,1,1]
	v_pk_fma_f32 v[86:87], v[60:61], v[54:55], v[86:87] op_sel_hi:[0,1,1]
	v_add_f32_dpp v82, v82, v82 quad_perm:[2,3,0,1] row_mask:0xf bank_mask:0xf bound_ctrl:1
	v_pk_mul_f32 v[88:89], v[0:1], v[96:97]
	v_pk_fma_f32 v[88:89], v[2:3], v[98:99], v[88:89]
	v_add_f32_dpp v82, v82, v82 row_half_mirror row_mask:0xf bank_mask:0xf bound_ctrl:1
	v_add_f32_e32 v72, v88, v89
	s_nop 0
	v_add_f32_dpp v82, v82, v82 row_mirror row_mask:0xf bank_mask:0xf bound_ctrl:1
	v_pk_fma_f32 v[0:1], v[82:83], v[48:49], v[84:85] op_sel_hi:[0,1,1] neg_lo:[1,0,0] neg_hi:[1,0,0]
	v_pk_fma_f32 v[2:3], v[82:83], v[50:51], v[86:87] op_sel_hi:[0,1,1] neg_lo:[1,0,0] neg_hi:[1,0,0]
	s_waitcnt lgkmcnt(0)
	ds_read_b128 v[44:47], v10 offset:34560
	ds_read_b128 v[40:43], v11 offset:2816
	ds_read_b128 v[52:55], v10 offset:35072
	ds_read_b32 v60, v12 offset:35584
	ds_read_b128 v[48:51], v10 offset:34816
	ds_read_b128 v[96:99], v10 offset:35328
	v_pk_mul_f32 v[80:81], v[0:1], v[20:21]
	v_pk_fma_f32 v[80:81], v[2:3], v[22:23], v[80:81]
	v_add_f32_e32 v82, v80, v81
	v_pk_mul_f32 v[84:85], v[0:1], v[16:17]
	v_pk_mul_f32 v[86:87], v[2:3], v[18:19]
	v_add_f32_dpp v82, v82, v82 quad_perm:[1,0,3,2] row_mask:0xf bank_mask:0xf bound_ctrl:1
	v_pk_fma_f32 v[84:85], v[36:37], v[28:29], v[84:85] op_sel_hi:[0,1,1]
	v_pk_fma_f32 v[86:87], v[36:37], v[30:31], v[86:87] op_sel_hi:[0,1,1]
	v_add_f32_dpp v82, v82, v82 quad_perm:[2,3,0,1] row_mask:0xf bank_mask:0xf bound_ctrl:1
	v_pk_mul_f32 v[88:89], v[0:1], v[32:33]
	v_pk_fma_f32 v[88:89], v[2:3], v[34:35], v[88:89]
	v_add_f32_dpp v82, v82, v82 row_half_mirror row_mask:0xf bank_mask:0xf bound_ctrl:1
	v_add_f32_e32 v73, v88, v89
	s_nop 0
	v_add_f32_dpp v82, v82, v82 row_mirror row_mask:0xf bank_mask:0xf bound_ctrl:1
	v_pk_fma_f32 v[0:1], v[82:83], v[24:25], v[84:85] op_sel_hi:[0,1,1] neg_lo:[1,0,0] neg_hi:[1,0,0]
	v_pk_fma_f32 v[2:3], v[82:83], v[26:27], v[86:87] op_sel_hi:[0,1,1] neg_lo:[1,0,0] neg_hi:[1,0,0]
	s_waitcnt lgkmcnt(0)
	ds_read_b128 v[20:23], v10 offset:35840
	ds_read_b128 v[16:19], v11 offset:3072
	ds_read_b128 v[28:31], v10 offset:36352
	ds_read_b32 v36, v12 offset:36864
	ds_read_b128 v[24:27], v10 offset:36096
	ds_read_b128 v[32:35], v10 offset:36608
	v_pk_mul_f32 v[80:81], v[0:1], v[44:45]
	v_pk_fma_f32 v[80:81], v[2:3], v[46:47], v[80:81]
	v_add_f32_e32 v82, v80, v81
	v_pk_mul_f32 v[84:85], v[0:1], v[40:41]
	v_pk_mul_f32 v[86:87], v[2:3], v[42:43]
	v_add_f32_dpp v82, v82, v82 quad_perm:[1,0,3,2] row_mask:0xf bank_mask:0xf bound_ctrl:1
	v_pk_fma_f32 v[84:85], v[60:61], v[52:53], v[84:85] op_sel_hi:[0,1,1]
	v_pk_fma_f32 v[86:87], v[60:61], v[54:55], v[86:87] op_sel_hi:[0,1,1]
	v_add_f32_dpp v82, v82, v82 quad_perm:[2,3,0,1] row_mask:0xf bank_mask:0xf bound_ctrl:1
	v_pk_mul_f32 v[88:89], v[0:1], v[56:57]
	v_pk_fma_f32 v[88:89], v[2:3], v[58:59], v[88:89]
	v_add_f32_dpp v82, v82, v82 row_half_mirror row_mask:0xf bank_mask:0xf bound_ctrl:1
	v_add_f32_e32 v74, v88, v89
	s_nop 0
	v_add_f32_dpp v82, v82, v82 row_mirror row_mask:0xf bank_mask:0xf bound_ctrl:1
	v_pk_fma_f32 v[0:1], v[82:83], v[48:49], v[84:85] op_sel_hi:[0,1,1] neg_lo:[1,0,0] neg_hi:[1,0,0]
	v_pk_fma_f32 v[2:3], v[82:83], v[50:51], v[86:87] op_sel_hi:[0,1,1] neg_lo:[1,0,0] neg_hi:[1,0,0]
	s_waitcnt lgkmcnt(0)
; __device__ __forceinline__ float row16_sum(float x) { x = red8_sum(x); x += dpp_f<0x140>(x); return x; }
; template <int RG>
; __device__ __forceinline__ void scan_waves16(const Params& p, float* lds, const int T, const int dir, const int wave, const int lane,
;                                            const size_t tok0, const int head, const int row_base) {
;     ...
;       for (int st = 0; st < 16; ++st) {
;         const int B = st & 1;
;         if (st + 1 < 16) LD16(1 - B, st + 1);
;         asm volatile("" ::: "memory");
;         float sa[RG], o[RG];
; #pragma unroll
;         for (int g = 0; g < RG; ++g) {
;           const f32x2_t a0 = __builtin_elementwise_fma(S[g][1], kk[B][1], S[g][0] * kk[B][0]);
;           sa[g] = a0.x + a0.y;
;         }
; #pragma unroll
;         for (int g = 0; g < RG; ++g) sa[g] = -row16_sum(sa[g]);
; #pragma unroll
;         for (int g = 0; g < RG; ++g) {
;           const f32x2_t sav = {sa[g], sa[g]}, vvv = {vv[B][g], vv[B][g]};
;           S[g][0] = __builtin_elementwise_fma(vvv, kd[B][0], __builtin_elementwise_fma(sav, qa[B][0], S[g][0] * w[B][0]));
;           S[g][1] = __builtin_elementwise_fma(vvv, kd[B][1], __builtin_elementwise_fma(sav, qa[B][1], S[g][1] * w[B][1]));
;         }
; #pragma unroll
;         for (int g = 0; g < RG; ++g) {
;           const f32x2_t a0 = __builtin_elementwise_fma(S[g][1], r[B][1], S[g][0] * r[B][0]);
;           o[g] = a0.x + a0.y;
;         }
; #pragma unroll
;         for (int g = 0; g < RG; ++g) o[g] = row16_sum(o[g]);
;         float os = o[0];
; #pragma unroll
;         for (int g = 1; g < RG; ++g) os = (part == g) ? o[g] : os;
;         osv[st] = os;
;       }
	ds_read_b128 v[44:47], v10 offset:37120
	ds_read_b128 v[40:43], v11 offset:3328
	ds_read_b128 v[52:55], v10 offset:37632
	ds_read_b32 v60, v12 offset:38144
	ds_read_b128 v[48:51], v10 offset:37376
	ds_read_b128 v[56:59], v10 offset:37888
	v_pk_mul_f32 v[80:81], v[0:1], v[20:21]
	v_pk_fma_f32 v[80:81], v[2:3], v[22:23], v[80:81]
	v_add_f32_e32 v82, v80, v81
	v_pk_mul_f32 v[84:85], v[0:1], v[16:17]
	v_pk_mul_f32 v[86:87], v[2:3], v[18:19]
	v_add_f32_dpp v82, v82, v82 quad_perm:[1,0,3,2] row_mask:0xf bank_mask:0xf bound_ctrl:1
	v_pk_fma_f32 v[84:85], v[36:37], v[28:29], v[84:85] op_sel_hi:[0,1,1]
	v_pk_fma_f32 v[86:87], v[36:37], v[30:31], v[86:87] op_sel_hi:[0,1,1]
	v_add_f32_dpp v82, v82, v82 quad_perm:[2,3,0,1] row_mask:0xf bank_mask:0xf bound_ctrl:1
	v_pk_mul_f32 v[88:89], v[0:1], v[96:97]
	v_pk_fma_f32 v[88:89], v[2:3], v[98:99], v[88:89]
	v_add_f32_dpp v82, v82, v82 row_half_mirror row_mask:0xf bank_mask:0xf bound_ctrl:1
	v_add_f32_e32 v75, v88, v89
	s_nop 0
	v_add_f32_dpp v82, v82, v82 row_mirror row_mask:0xf bank_mask:0xf bound_ctrl:1
	v_pk_fma_f32 v[0:1], v[82:83], v[24:25], v[84:85] op_sel_hi:[0,1,1] neg_lo:[1,0,0] neg_hi:[1,0,0]
	v_pk_fma_f32 v[2:3], v[82:83], v[26:27], v[86:87] op_sel_hi:[0,1,1] neg_lo:[1,0,0] neg_hi:[1,0,0]
	s_waitcnt lgkmcnt(0)
	ds_read_b128 v[20:23], v10 offset:38400
	ds_read_b128 v[16:19], v11 offset:3584
	ds_read_b128 v[28:31], v10 offset:38912
	ds_read_b32 v36, v12 offset:39424
	ds_read_b128 v[24:27], v10 offset:38656
	ds_read_b128 v[96:99], v10 offset:39168
	v_pk_mul_f32 v[80:81], v[0:1], v[44:45]
	v_pk_fma_f32 v[80:81], v[2:3], v[46:47], v[80:81]
	v_add_f32_e32 v82, v80, v81
	v_pk_mul_f32 v[84:85], v[0:1], v[40:41]
	v_pk_mul_f32 v[86:87], v[2:3], v[42:43]
	v_add_f32_dpp v82, v82, v82 quad_perm:[1,0,3,2] row_mask:0xf bank_mask:0xf bound_ctrl:1
	v_pk_fma_f32 v[84:85], v[60:61], v[52:53], v[84:85] op_sel_hi:[0,1,1]
	v_pk_fma_f32 v[86:87], v[60:61], v[54:55], v[86:87] op_sel_hi:[0,1,1]
	v_add_f32_dpp v82, v82, v82 quad_perm:[2,3,0,1] row_mask:0xf bank_mask:0xf bound_ctrl:1
	v_pk_mul_f32 v[88:89], v[0:1], v[32:33]
	v_pk_fma_f32 v[88:89], v[2:3], v[34:35], v[88:89]
	v_add_f32_dpp v82, v82, v82 row_half_mirror row_mask:0xf bank_mask:0xf bound_ctrl:1
	v_add_f32_e32 v76, v88, v89
	s_nop 0
	v_add_f32_dpp v82, v82, v82 row_mirror row_mask:0xf bank_mask:0xf bound_ctrl:1
	v_pk_fma_f32 v[0:1], v[82:83], v[48:49], v[84:85] op_sel_hi:[0,1,1] neg_lo:[1,0,0] neg_hi:[1,0,0]
	v_pk_fma_f32 v[2:3], v[82:83], v[50:51], v[86:87] op_sel_hi:[0,1,1] neg_lo:[1,0,0] neg_hi:[1,0,0]
	s_waitcnt lgkmcnt(0)
	ds_read_b128 v[44:47], v10 offset:39680
	ds_read_b128 v[40:43], v11 offset:3840
	ds_read_b128 v[52:55], v10 offset:40192
	ds_read_b32 v60, v12 offset:40704
	ds_read_b128 v[48:51], v10 offset:39936
	ds_read_b128 v[32:35], v10 offset:40448
	v_pk_mul_f32 v[80:81], v[0:1], v[20:21]
	v_pk_fma_f32 v[80:81], v[2:3], v[22:23], v[80:81]
	v_add_f32_e32 v82, v80, v81
	v_pk_mul_f32 v[84:85], v[0:1], v[16:17]
	v_pk_mul_f32 v[86:87], v[2:3], v[18:19]
	v_add_f32_dpp v82, v82, v82 quad_perm:[1,0,3,2] row_mask:0xf bank_mask:0xf bound_ctrl:1
	v_pk_fma_f32 v[84:85], v[36:37], v[28:29], v[84:85] op_sel_hi:[0,1,1]
	v_pk_fma_f32 v[86:87], v[36:37], v[30:31], v[86:87] op_sel_hi:[0,1,1]
	v_add_f32_dpp v82, v82, v82 quad_perm:[2,3,0,1] row_mask:0xf bank_mask:0xf bound_ctrl:1
	v_pk_mul_f32 v[88:89], v[0:1], v[56:57]
	v_pk_fma_f32 v[88:89], v[2:3], v[58:59], v[88:89]
	v_add_f32_dpp v82, v82, v82 row_half_mirror row_mask:0xf bank_mask:0xf bound_ctrl:1
	v_add_f32_e32 v77, v88, v89
	s_nop 0
	v_add_f32_dpp v82, v82, v82 row_mirror row_mask:0xf bank_mask:0xf bound_ctrl:1
	v_pk_fma_f32 v[0:1], v[82:83], v[24:25], v[84:85] op_sel_hi:[0,1,1] neg_lo:[1,0,0] neg_hi:[1,0,0]
	v_pk_fma_f32 v[2:3], v[82:83], v[26:27], v[86:87] op_sel_hi:[0,1,1] neg_lo:[1,0,0] neg_hi:[1,0,0]
	s_waitcnt lgkmcnt(0)
; __device__ __forceinline__ u16 f2bf(float f) { unsigned u = __float_as_uint(f); u += 0x7fffu + ((u >> 16) & 1u); return (u16)(u >> 16); }
; __device__ __forceinline__ float row16_sum(float x) { x = red8_sum(x); x += dpp_f<0x140>(x); return x; }
; template <int RG>
; __device__ __forceinline__ void scan_waves16(const Params& p, float* lds, const int T, const int dir, const int wave, const int lane,
;                                            const size_t tok0, const int head, const int row_base) {
;     ...
; #pragma unroll
;         for (int g = 0; g < RG; ++g) {
;           const f32x2_t a0 = __builtin_elementwise_fma(S[g][1], r[B][1], S[g][0] * r[B][0]);
;           o[g] = a0.x + a0.y;
;         }
; #pragma unroll
;         for (int g = 0; g < RG; ++g) o[g] = row16_sum(o[g]);
;         float os = o[0];
; #pragma unroll
;         for (int g = 1; g < RG; ++g) os = (part == g) ? o[g] : os;
;         osv[st] = os;
;       }
;     ...
;       if (part < RG) {
;         const int s0 = i * 16; const unsigned t0 = dir ? (unsigned)(T - 1 - s0) : (unsigned)s0;
;         unsigned off = ooff0 + t0 * ostride; const unsigned dt = dir ? 0u - ostride : ostride;
; #pragma unroll
;         for (int st = 0; st < 16; ++st) { *(u16*)(obase + (size_t)off) = f2bf(osv[st]); off += dt; }
;       }
	v_pk_mul_f32 v[80:81], v[0:1], v[44:45]
	v_pk_fma_f32 v[80:81], v[2:3], v[46:47], v[80:81]
	v_add_f32_e32 v82, v80, v81
	v_pk_mul_f32 v[84:85], v[0:1], v[40:41]
	v_pk_mul_f32 v[86:87], v[2:3], v[42:43]
	v_add_f32_dpp v82, v82, v82 quad_perm:[1,0,3,2] row_mask:0xf bank_mask:0xf bound_ctrl:1
	v_pk_fma_f32 v[84:85], v[60:61], v[52:53], v[84:85] op_sel_hi:[0,1,1]
	v_pk_fma_f32 v[86:87], v[60:61], v[54:55], v[86:87] op_sel_hi:[0,1,1]
	v_add_f32_dpp v82, v82, v82 quad_perm:[2,3,0,1] row_mask:0xf bank_mask:0xf bound_ctrl:1
	v_pk_mul_f32 v[88:89], v[0:1], v[96:97]
	v_pk_fma_f32 v[88:89], v[2:3], v[98:99], v[88:89]
	v_add_f32_dpp v82, v82, v82 row_half_mirror row_mask:0xf bank_mask:0xf bound_ctrl:1
	v_add_f32_e32 v78, v88, v89
	s_nop 0
	v_add_f32_dpp v82, v82, v82 row_mirror row_mask:0xf bank_mask:0xf bound_ctrl:1
	v_pk_fma_f32 v[0:1], v[82:83], v[48:49], v[84:85] op_sel_hi:[0,1,1] neg_lo:[1,0,0] neg_hi:[1,0,0]
	v_pk_fma_f32 v[2:3], v[82:83], v[50:51], v[86:87] op_sel_hi:[0,1,1] neg_lo:[1,0,0] neg_hi:[1,0,0]
	v_pk_mul_f32 v[88:89], v[0:1], v[32:33]
	v_pk_fma_f32 v[88:89], v[2:3], v[34:35], v[88:89]
	v_add_f32_e32 v79, v88, v89
	v_cmp_ne_u32_e32 vcc, 0, v9
	v_add_f32_dpp v64, v64, v64 row_mirror row_mask:0xf bank_mask:0x3 bound_ctrl:1
	v_add_f32_dpp v64, v72, v72 row_mirror row_mask:0xf bank_mask:0xc bound_ctrl:1
	v_add_f32_dpp v65, v65, v65 row_mirror row_mask:0xf bank_mask:0x3 bound_ctrl:1
	v_add_f32_dpp v65, v73, v73 row_mirror row_mask:0xf bank_mask:0xc bound_ctrl:1
	v_add_f32_dpp v66, v66, v66 row_mirror row_mask:0xf bank_mask:0x3 bound_ctrl:1
	v_add_f32_dpp v66, v74, v74 row_mirror row_mask:0xf bank_mask:0xc bound_ctrl:1
	v_add_f32_dpp v67, v67, v67 row_mirror row_mask:0xf bank_mask:0x3 bound_ctrl:1
	v_add_f32_dpp v67, v75, v75 row_mirror row_mask:0xf bank_mask:0xc bound_ctrl:1
	v_add_f32_dpp v68, v68, v68 row_mirror row_mask:0xf bank_mask:0x3 bound_ctrl:1
	v_add_f32_dpp v68, v76, v76 row_mirror row_mask:0xf bank_mask:0xc bound_ctrl:1
	v_add_f32_dpp v69, v69, v69 row_mirror row_mask:0xf bank_mask:0x3 bound_ctrl:1
	v_add_f32_dpp v69, v77, v77 row_mirror row_mask:0xf bank_mask:0xc bound_ctrl:1
	v_add_f32_dpp v70, v70, v70 row_mirror row_mask:0xf bank_mask:0x3 bound_ctrl:1
	v_add_f32_dpp v70, v78, v78 row_mirror row_mask:0xf bank_mask:0xc bound_ctrl:1
	v_add_f32_dpp v71, v71, v71 row_mirror row_mask:0xf bank_mask:0x3 bound_ctrl:1
	v_add_f32_dpp v71, v79, v79 row_mirror row_mask:0xf bank_mask:0xc bound_ctrl:1
	v_add_f32_dpp v64, v64, v64 row_half_mirror row_mask:0xf bank_mask:0x5 bound_ctrl:1
	v_add_f32_dpp v64, v68, v68 row_half_mirror row_mask:0xf bank_mask:0xa bound_ctrl:1
	v_add_f32_dpp v65, v65, v65 row_half_mirror row_mask:0xf bank_mask:0x5 bound_ctrl:1
	v_add_f32_dpp v65, v69, v69 row_half_mirror row_mask:0xf bank_mask:0xa bound_ctrl:1
	v_add_f32_dpp v66, v66, v66 row_half_mirror row_mask:0xf bank_mask:0x5 bound_ctrl:1
	v_add_f32_dpp v66, v70, v70 row_half_mirror row_mask:0xf bank_mask:0xa bound_ctrl:1
	v_add_f32_dpp v67, v67, v67 row_half_mirror row_mask:0xf bank_mask:0x5 bound_ctrl:1
	v_add_f32_dpp v67, v71, v71 row_half_mirror row_mask:0xf bank_mask:0xa bound_ctrl:1
	s_nop 0
	v_cndmask_b32_e32 v90, v66, v64, vcc
	v_cndmask_b32_e32 v91, v67, v65, vcc
	v_cndmask_b32_e32 v92, v64, v66, vcc
	v_cndmask_b32_e32 v93, v65, v67, vcc
	v_cmp_ne_u32_e32 vcc, 0, v13
	v_add_f32_dpp v94, v90, v92 quad_perm:[2,3,0,1] row_mask:0xf bank_mask:0xf bound_ctrl:1
	v_add_f32_dpp v95, v91, v93 quad_perm:[2,3,0,1] row_mask:0xf bank_mask:0xf bound_ctrl:1
	s_and_b64 s[16:17], s[0:1], exec
	v_cndmask_b32_e32 v90, v95, v94, vcc
	v_cndmask_b32_e32 v92, v94, v95, vcc
	s_cselect_b32 s16, s13, s14
	s_lshl_b32 s16, s16, s12
	v_add_f32_dpp v94, v90, v92 quad_perm:[1,0,3,2] row_mask:0xf bank_mask:0xf bound_ctrl:1
	v_add3_u32 v91, v6, v8, s16
	v_cvt_pk_bf16_f32 v94, v94, v94
	global_store_short v91, v94, s[6:7]
	s_branch .Lmy_sw_next
